# no priority toggling in GEMM loops plus back-to-back duplicate s_waitcnt lgkmcnt(0) collapsed (92 removed)
# speedup vs baseline: 1.0081x; 1.0018x over previous
.LBB0_190:
	ds_read_b128 v[180:183], v172
	ds_read_b128 v[184:187], v172 offset:1024
	ds_read_b128 v[188:191], v172 offset:2048
	ds_read_b128 v[192:195], v172 offset:3072
	v_add_u32_e32 v178, 0xc000, v152
	v_lshl_add_u64 v[244:245], s[20:21], 0, v[146:147]
	v_readfirstlane_b32 s1, v178
	v_add_u32_e32 v179, 0xe000, v152
	v_lshl_add_u64 v[224:225], v[244:245], 0, s[48:49]
	s_mov_b32 m0, s1
	v_lshl_add_u64 v[246:247], s[20:21], 0, v[148:149]
	v_readfirstlane_b32 s1, v179
	ds_read_b128 v[174:177], v161
	ds_read_b128 v[196:199], v161 offset:1024
	ds_read_b128 v[200:203], v160
	ds_read_b128 v[204:207], v160 offset:1024
	ds_read_b128 v[208:211], v159
	ds_read_b128 v[212:215], v159 offset:1024
	ds_read_b128 v[216:219], v158
	ds_read_b128 v[220:223], v158 offset:1024
	global_load_lds_dwordx4 v[224:225], off
	v_lshl_add_u64 v[224:225], v[246:247], 0, s[48:49]
	s_mov_b32 m0, s1
	s_nop 0
	global_load_lds_dwordx4 v[224:225], off
	s_waitcnt lgkmcnt(8)
	s_barrier
	s_waitcnt lgkmcnt(0)
	v_mfma_f32_16x16x32_bf16 v[124:127], v[180:183], v[174:177], v[124:127]
	v_mfma_f32_16x16x32_bf16 v[120:123], v[188:191], v[174:177], v[120:123]
	v_mfma_f32_16x16x32_bf16 v[116:119], v[180:183], v[200:203], v[116:119]
	v_mfma_f32_16x16x32_bf16 v[112:115], v[188:191], v[200:203], v[112:115]
	v_mfma_f32_16x16x32_bf16 v[108:111], v[180:183], v[208:211], v[108:111]
	v_mfma_f32_16x16x32_bf16 v[104:107], v[188:191], v[208:211], v[104:107]
	v_mfma_f32_16x16x32_bf16 v[100:103], v[180:183], v[216:219], v[100:103]
	v_mfma_f32_16x16x32_bf16 v[96:99], v[188:191], v[216:219], v[96:99]
	v_mfma_f32_16x16x32_bf16 v[124:127], v[184:187], v[196:199], v[124:127]
	v_mfma_f32_16x16x32_bf16 v[120:123], v[192:195], v[196:199], v[120:123]
	v_mfma_f32_16x16x32_bf16 v[116:119], v[184:187], v[204:207], v[116:119]
	v_mfma_f32_16x16x32_bf16 v[112:115], v[192:195], v[204:207], v[112:115]
	v_mfma_f32_16x16x32_bf16 v[108:111], v[184:187], v[212:215], v[108:111]
	v_mfma_f32_16x16x32_bf16 v[104:107], v[192:195], v[212:215], v[104:107]
	v_mfma_f32_16x16x32_bf16 v[100:103], v[184:187], v[220:223], v[100:103]
	v_mfma_f32_16x16x32_bf16 v[96:99], v[192:195], v[220:223], v[96:99]
	s_barrier
	v_lshl_add_u64 v[248:249], s[20:21], 0, v[142:143]
	v_readfirstlane_b32 s1, v153
	v_add_u32_e32 v173, 0x2000, v153
	v_lshl_add_u64 v[240:241], v[248:249], 0, s[50:51]
	s_mov_b32 m0, s1
	v_lshl_add_u64 v[250:251], s[20:21], 0, v[144:145]
	v_readfirstlane_b32 s1, v173
	ds_read_b128 v[224:227], v169
	ds_read_b128 v[228:231], v169 offset:1024
	ds_read_b128 v[232:235], v169 offset:2048
	ds_read_b128 v[236:239], v169 offset:3072
	global_load_lds_dwordx4 v[240:241], off
	v_lshl_add_u64 v[240:241], v[250:251], 0, s[50:51]
	s_mov_b32 m0, s1
	s_nop 0
	global_load_lds_dwordx4 v[240:241], off
	s_barrier
	s_waitcnt lgkmcnt(0)
	v_mfma_f32_16x16x32_bf16 v[92:95], v[224:227], v[174:177], v[92:95]
	v_mfma_f32_16x16x32_bf16 v[88:91], v[232:235], v[174:177], v[88:91]
	v_mfma_f32_16x16x32_bf16 v[84:87], v[224:227], v[200:203], v[84:87]
	v_mfma_f32_16x16x32_bf16 v[80:83], v[232:235], v[200:203], v[80:83]
	v_mfma_f32_16x16x32_bf16 v[76:79], v[224:227], v[208:211], v[76:79]
	v_mfma_f32_16x16x32_bf16 v[72:75], v[232:235], v[208:211], v[72:75]
	v_mfma_f32_16x16x32_bf16 v[68:71], v[224:227], v[216:219], v[68:71]
	v_mfma_f32_16x16x32_bf16 v[64:67], v[232:235], v[216:219], v[64:67]
	v_mfma_f32_16x16x32_bf16 v[92:95], v[228:231], v[196:199], v[92:95]
	v_mfma_f32_16x16x32_bf16 v[88:91], v[236:239], v[196:199], v[88:91]
	v_mfma_f32_16x16x32_bf16 v[84:87], v[228:231], v[204:207], v[84:87]
	v_mfma_f32_16x16x32_bf16 v[80:83], v[236:239], v[204:207], v[80:83]
	v_mfma_f32_16x16x32_bf16 v[76:79], v[228:231], v[212:215], v[76:79]
	v_mfma_f32_16x16x32_bf16 v[72:75], v[236:239], v[212:215], v[72:75]
	v_mfma_f32_16x16x32_bf16 v[68:71], v[228:231], v[220:223], v[68:71]
	v_mfma_f32_16x16x32_bf16 v[64:67], v[236:239], v[220:223], v[64:67]
	v_readfirstlane_b32 s1, v152
	v_lshl_add_u64 v[174:175], v[244:245], 0, s[52:53]
	s_mov_b32 m0, s1
	s_barrier
	ds_read_b128 v[196:199], v161 offset:16384
	ds_read_b128 v[200:203], v161 offset:17408
	ds_read_b128 v[204:207], v160 offset:16384
	ds_read_b128 v[208:211], v160 offset:17408
	ds_read_b128 v[212:215], v159 offset:16384
	ds_read_b128 v[216:219], v159 offset:17408
	ds_read_b128 v[220:223], v158 offset:16384
	ds_read_b128 v[240:243], v158 offset:17408
	global_load_lds_dwordx4 v[174:175], off
	v_add_u32_e32 v174, 0x2000, v152
	v_lshl_add_u64 v[176:177], v[246:247], 0, s[52:53]
	v_readfirstlane_b32 s1, v174
	s_mov_b32 m0, s1
	s_nop 0
	global_load_lds_dwordx4 v[176:177], off
	s_barrier
	s_waitcnt lgkmcnt(0)
	v_mfma_f32_16x16x32_bf16 v[60:63], v[180:183], v[196:199], v[60:63]
	v_mfma_f32_16x16x32_bf16 v[56:59], v[188:191], v[196:199], v[56:59]
	v_mfma_f32_16x16x32_bf16 v[52:55], v[180:183], v[204:207], v[52:55]
	v_mfma_f32_16x16x32_bf16 v[48:51], v[188:191], v[204:207], v[48:51]
	v_mfma_f32_16x16x32_bf16 v[44:47], v[180:183], v[212:215], v[44:47]
	v_mfma_f32_16x16x32_bf16 v[40:43], v[188:191], v[212:215], v[40:43]
	v_mfma_f32_16x16x32_bf16 v[36:39], v[180:183], v[220:223], v[36:39]
	v_mfma_f32_16x16x32_bf16 v[32:35], v[188:191], v[220:223], v[32:35]
	v_mfma_f32_16x16x32_bf16 v[60:63], v[184:187], v[200:203], v[60:63]
	v_mfma_f32_16x16x32_bf16 v[56:59], v[192:195], v[200:203], v[56:59]
	v_mfma_f32_16x16x32_bf16 v[52:55], v[184:187], v[208:211], v[52:55]
	v_mfma_f32_16x16x32_bf16 v[48:51], v[192:195], v[208:211], v[48:51]
	v_mfma_f32_16x16x32_bf16 v[44:47], v[184:187], v[216:219], v[44:47]
	v_mfma_f32_16x16x32_bf16 v[40:43], v[192:195], v[216:219], v[40:43]
	v_mfma_f32_16x16x32_bf16 v[36:39], v[184:187], v[240:243], v[36:39]
	v_mfma_f32_16x16x32_bf16 v[32:35], v[192:195], v[240:243], v[32:35]
	s_barrier
	v_readfirstlane_b32 s1, v151
	v_add_u32_e32 v175, 0x2000, v151
	v_lshl_add_u64 v[176:177], v[248:249], 0, s[54:55]
	s_mov_b32 m0, s1
	v_readfirstlane_b32 s1, v175
	global_load_lds_dwordx4 v[176:177], off
	v_lshl_add_u64 v[176:177], v[250:251], 0, s[54:55]
	s_mov_b32 m0, s1
	s_nop 0
	global_load_lds_dwordx4 v[176:177], off
	s_waitcnt vmcnt(6)
	s_barrier
	v_mfma_f32_16x16x32_bf16 v[28:31], v[224:227], v[196:199], v[28:31]
	v_mfma_f32_16x16x32_bf16 v[24:27], v[232:235], v[196:199], v[24:27]
	v_mfma_f32_16x16x32_bf16 v[20:23], v[224:227], v[204:207], v[20:23]
	v_mfma_f32_16x16x32_bf16 v[16:19], v[232:235], v[204:207], v[16:19]
	v_mfma_f32_16x16x32_bf16 v[12:15], v[224:227], v[212:215], v[12:15]
	v_mfma_f32_16x16x32_bf16 v[8:11], v[232:235], v[212:215], v[8:11]
	v_mfma_f32_16x16x32_bf16 v[4:7], v[224:227], v[220:223], v[4:7]
	v_mfma_f32_16x16x32_bf16 v[0:3], v[232:235], v[220:223], v[0:3]
	v_mfma_f32_16x16x32_bf16 v[28:31], v[228:231], v[200:203], v[28:31]
	v_mfma_f32_16x16x32_bf16 v[24:27], v[236:239], v[200:203], v[24:27]
	v_mfma_f32_16x16x32_bf16 v[20:23], v[228:231], v[208:211], v[20:23]
	v_mfma_f32_16x16x32_bf16 v[16:19], v[236:239], v[208:211], v[16:19]
	v_mfma_f32_16x16x32_bf16 v[12:15], v[228:231], v[216:219], v[12:15]
	v_mfma_f32_16x16x32_bf16 v[8:11], v[236:239], v[216:219], v[8:11]
	v_mfma_f32_16x16x32_bf16 v[4:7], v[228:231], v[240:243], v[4:7]
	v_mfma_f32_16x16x32_bf16 v[0:3], v[236:239], v[240:243], v[0:3]
	s_barrier
	ds_read_b128 v[180:183], v163
	ds_read_b128 v[184:187], v163 offset:1024
	ds_read_b128 v[188:191], v163 offset:2048
	ds_read_b128 v[192:195], v163 offset:3072
	v_add_u32_e32 v176, 0x4000, v152
	v_add_u32_e32 v177, 0x6000, v152
	v_readfirstlane_b32 s1, v176
	v_lshl_add_u64 v[228:229], v[244:245], 0, s[56:57]
	s_mov_b32 m0, s1
	v_readfirstlane_b32 s1, v177
	ds_read_b128 v[196:199], v161 offset:32768
	ds_read_b128 v[200:203], v161 offset:33792
	ds_read_b128 v[204:207], v160 offset:32768
	ds_read_b128 v[208:211], v160 offset:33792
	ds_read_b128 v[212:215], v159 offset:32768
	ds_read_b128 v[216:219], v159 offset:33792
	ds_read_b128 v[220:223], v158 offset:32768
	ds_read_b128 v[224:227], v158 offset:33792
	global_load_lds_dwordx4 v[228:229], off
	v_lshl_add_u64 v[228:229], v[246:247], 0, s[56:57]
	s_mov_b32 m0, s1
	s_nop 0
	global_load_lds_dwordx4 v[228:229], off
	s_waitcnt lgkmcnt(8)
	s_barrier
	s_waitcnt lgkmcnt(0)
	v_mfma_f32_16x16x32_bf16 v[124:127], v[180:183], v[196:199], v[124:127]
	v_mfma_f32_16x16x32_bf16 v[120:123], v[188:191], v[196:199], v[120:123]
	v_mfma_f32_16x16x32_bf16 v[116:119], v[180:183], v[204:207], v[116:119]
	v_mfma_f32_16x16x32_bf16 v[112:115], v[188:191], v[204:207], v[112:115]
	v_mfma_f32_16x16x32_bf16 v[108:111], v[180:183], v[212:215], v[108:111]
	v_mfma_f32_16x16x32_bf16 v[104:107], v[188:191], v[212:215], v[104:107]
	v_mfma_f32_16x16x32_bf16 v[100:103], v[180:183], v[220:223], v[100:103]
	v_mfma_f32_16x16x32_bf16 v[96:99], v[188:191], v[220:223], v[96:99]
	v_mfma_f32_16x16x32_bf16 v[124:127], v[184:187], v[200:203], v[124:127]
	v_mfma_f32_16x16x32_bf16 v[120:123], v[192:195], v[200:203], v[120:123]
	v_mfma_f32_16x16x32_bf16 v[116:119], v[184:187], v[208:211], v[116:119]
	v_mfma_f32_16x16x32_bf16 v[112:115], v[192:195], v[208:211], v[112:115]
	v_mfma_f32_16x16x32_bf16 v[108:111], v[184:187], v[216:219], v[108:111]
	v_mfma_f32_16x16x32_bf16 v[104:107], v[192:195], v[216:219], v[104:107]
	v_mfma_f32_16x16x32_bf16 v[100:103], v[184:187], v[224:227], v[100:103]
	v_mfma_f32_16x16x32_bf16 v[96:99], v[192:195], v[224:227], v[96:99]
	s_barrier
	v_readfirstlane_b32 s1, v167
	v_add_u32_e32 v254, 0x2000, v167
	v_lshl_add_u64 v[252:253], v[248:249], 0, s[58:59]
	s_mov_b32 m0, s1
	v_readfirstlane_b32 s1, v254
	ds_read_b128 v[228:231], v162
	ds_read_b128 v[232:235], v162 offset:1024
	ds_read_b128 v[236:239], v162 offset:2048
	ds_read_b128 v[240:243], v162 offset:3072
	global_load_lds_dwordx4 v[252:253], off
	v_lshl_add_u64 v[252:253], v[250:251], 0, s[58:59]
	s_mov_b32 m0, s1
	s_nop 0
	global_load_lds_dwordx4 v[252:253], off
	s_barrier
	s_waitcnt lgkmcnt(0)
	v_mfma_f32_16x16x32_bf16 v[92:95], v[228:231], v[196:199], v[92:95]
	v_mfma_f32_16x16x32_bf16 v[88:91], v[236:239], v[196:199], v[88:91]
	v_mfma_f32_16x16x32_bf16 v[84:87], v[228:231], v[204:207], v[84:87]
	v_mfma_f32_16x16x32_bf16 v[80:83], v[236:239], v[204:207], v[80:83]
	v_mfma_f32_16x16x32_bf16 v[76:79], v[228:231], v[212:215], v[76:79]
	v_mfma_f32_16x16x32_bf16 v[72:75], v[236:239], v[212:215], v[72:75]
	v_mfma_f32_16x16x32_bf16 v[68:71], v[228:231], v[220:223], v[68:71]
	v_mfma_f32_16x16x32_bf16 v[64:67], v[236:239], v[220:223], v[64:67]
	v_mfma_f32_16x16x32_bf16 v[92:95], v[232:235], v[200:203], v[92:95]
	v_mfma_f32_16x16x32_bf16 v[88:91], v[240:243], v[200:203], v[88:91]
	v_mfma_f32_16x16x32_bf16 v[84:87], v[232:235], v[208:211], v[84:87]
	v_mfma_f32_16x16x32_bf16 v[80:83], v[240:243], v[208:211], v[80:83]
	v_mfma_f32_16x16x32_bf16 v[76:79], v[232:235], v[216:219], v[76:79]
	v_mfma_f32_16x16x32_bf16 v[72:75], v[240:243], v[216:219], v[72:75]
	v_mfma_f32_16x16x32_bf16 v[68:71], v[232:235], v[224:227], v[68:71]
	v_mfma_f32_16x16x32_bf16 v[64:67], v[240:243], v[224:227], v[64:67]
	v_readfirstlane_b32 s1, v168
	v_lshl_add_u64 v[244:245], v[244:245], 0, s[60:61]
	s_mov_b32 m0, s1
	v_readfirstlane_b32 s1, v170
	s_barrier
	ds_read_b128 v[196:199], v161 offset:49152
	ds_read_b128 v[200:203], v161 offset:50176
	ds_read_b128 v[204:207], v160 offset:49152
	ds_read_b128 v[208:211], v160 offset:50176
	ds_read_b128 v[212:215], v159 offset:49152
	ds_read_b128 v[216:219], v159 offset:50176
	ds_read_b128 v[220:223], v158 offset:49152
	ds_read_b128 v[224:227], v158 offset:50176
	global_load_lds_dwordx4 v[244:245], off
	v_lshl_add_u64 v[244:245], v[246:247], 0, s[60:61]
	s_mov_b32 m0, s1
	s_nop 0
	global_load_lds_dwordx4 v[244:245], off
	s_barrier
	s_waitcnt lgkmcnt(0)
	v_mfma_f32_16x16x32_bf16 v[60:63], v[180:183], v[196:199], v[60:63]
	v_mfma_f32_16x16x32_bf16 v[56:59], v[188:191], v[196:199], v[56:59]
	v_mfma_f32_16x16x32_bf16 v[52:55], v[180:183], v[204:207], v[52:55]
	v_mfma_f32_16x16x32_bf16 v[48:51], v[188:191], v[204:207], v[48:51]
	v_mfma_f32_16x16x32_bf16 v[44:47], v[180:183], v[212:215], v[44:47]
	v_mfma_f32_16x16x32_bf16 v[40:43], v[188:191], v[212:215], v[40:43]
	v_mfma_f32_16x16x32_bf16 v[36:39], v[180:183], v[220:223], v[36:39]
	v_mfma_f32_16x16x32_bf16 v[32:35], v[188:191], v[220:223], v[32:35]
	v_mfma_f32_16x16x32_bf16 v[60:63], v[184:187], v[200:203], v[60:63]
	v_mfma_f32_16x16x32_bf16 v[56:59], v[192:195], v[200:203], v[56:59]
	v_mfma_f32_16x16x32_bf16 v[52:55], v[184:187], v[208:211], v[52:55]
	v_mfma_f32_16x16x32_bf16 v[48:51], v[192:195], v[208:211], v[48:51]
	v_mfma_f32_16x16x32_bf16 v[44:47], v[184:187], v[216:219], v[44:47]
	v_mfma_f32_16x16x32_bf16 v[40:43], v[192:195], v[216:219], v[40:43]
	v_mfma_f32_16x16x32_bf16 v[36:39], v[184:187], v[224:227], v[36:39]
	v_mfma_f32_16x16x32_bf16 v[32:35], v[192:195], v[224:227], v[32:35]
	s_barrier
	v_readfirstlane_b32 s1, v171
	v_add_u32_e32 v182, 0x2000, v171
	v_lshl_add_u64 v[180:181], v[248:249], 0, s[62:63]
	s_mov_b32 m0, s1
	v_readfirstlane_b32 s1, v182
	global_load_lds_dwordx4 v[180:181], off
	v_lshl_add_u64 v[180:181], v[250:251], 0, s[62:63]
	s_mov_b32 m0, s1
	s_nop 0
	global_load_lds_dwordx4 v[180:181], off
	s_waitcnt vmcnt(6)
	s_barrier
	v_mfma_f32_16x16x32_bf16 v[28:31], v[228:231], v[196:199], v[28:31]
	v_mfma_f32_16x16x32_bf16 v[24:27], v[236:239], v[196:199], v[24:27]
	v_mfma_f32_16x16x32_bf16 v[20:23], v[228:231], v[204:207], v[20:23]
	v_mfma_f32_16x16x32_bf16 v[16:19], v[236:239], v[204:207], v[16:19]
	v_mfma_f32_16x16x32_bf16 v[12:15], v[228:231], v[212:215], v[12:15]
	v_mfma_f32_16x16x32_bf16 v[8:11], v[236:239], v[212:215], v[8:11]
	v_mfma_f32_16x16x32_bf16 v[4:7], v[228:231], v[220:223], v[4:7]
	v_mfma_f32_16x16x32_bf16 v[0:3], v[236:239], v[220:223], v[0:3]
	v_mfma_f32_16x16x32_bf16 v[28:31], v[232:235], v[200:203], v[28:31]
	v_mfma_f32_16x16x32_bf16 v[24:27], v[240:243], v[200:203], v[24:27]
	v_mfma_f32_16x16x32_bf16 v[20:23], v[232:235], v[208:211], v[20:23]
	v_mfma_f32_16x16x32_bf16 v[16:19], v[240:243], v[208:211], v[16:19]
	v_mfma_f32_16x16x32_bf16 v[12:15], v[232:235], v[216:219], v[12:15]
	v_mfma_f32_16x16x32_bf16 v[8:11], v[240:243], v[216:219], v[8:11]
	v_mfma_f32_16x16x32_bf16 v[4:7], v[232:235], v[224:227], v[4:7]
	v_mfma_f32_16x16x32_bf16 v[0:3], v[240:243], v[224:227], v[0:3]
	s_add_i32 s0, s0, 2
	v_lshl_add_u64 v[142:143], v[142:143], 0, s[50:51]
	v_lshl_add_u64 v[144:145], v[144:145], 0, s[50:51]
	v_lshl_add_u64 v[146:147], v[146:147], 0, s[50:51]
	s_cmp_lt_u32 s0, 12
	v_lshl_add_u64 v[148:149], v[148:149], 0, s[50:51]
	s_barrier
	s_cbranch_scc1 .LBB0_190
	s_or_b32 s0, s6, 0x80
	s_ashr_i32 s1, s0, 31
	s_lshl_b64 s[0:1], s[0:1], 11
	s_add_u32 s0, s45, s0
	s_addc_u32 s1, s46, s1
	v_lshl_add_u64 v[170:171], s[0:1], 0, v[130:131]
	v_lshl_add_u64 v[138:139], v[138:139], 1, v[170:171]
	v_readfirstlane_b32 s2, v178
	v_lshl_add_u64 v[138:139], v[138:139], 0, s[64:65]
	s_mov_b32 m0, s2
	ds_read_b128 v[142:145], v172
	ds_read_b128 v[146:149], v172 offset:1024
	ds_read_b128 v[180:183], v172 offset:2048
	ds_read_b128 v[184:187], v172 offset:3072
	ds_read_b128 v[188:191], v161
	ds_read_b128 v[192:195], v161 offset:1024
	ds_read_b128 v[196:199], v160
	ds_read_b128 v[200:203], v160 offset:1024
	ds_read_b128 v[204:207], v159
	ds_read_b128 v[208:211], v159 offset:1024
	ds_read_b128 v[212:215], v158
	ds_read_b128 v[216:219], v158 offset:1024
	global_load_lds_dwordx4 v[138:139], off
	v_lshl_add_u64 v[138:139], s[0:1], 0, v[134:135]
	v_lshl_add_u64 v[138:139], v[140:141], 1, v[138:139]
	v_readfirstlane_b32 s0, v179
	v_lshl_add_u64 v[138:139], v[138:139], 0, s[64:65]
	s_mov_b32 m0, s0
	v_readlane_b32 s0, v255, 11
	global_load_lds_dwordx4 v[138:139], off
	s_add_i32 s82, s82, s0
	s_barrier
	s_waitcnt lgkmcnt(0)
	s_cmpk_gt_i32 s82, 0x54
	s_cselect_b64 s[66:67], -1, 0
	s_waitcnt lgkmcnt(0)
	v_mfma_f32_16x16x32_bf16 v[124:127], v[142:145], v[188:191], v[124:127]
	v_mfma_f32_16x16x32_bf16 v[116:119], v[142:145], v[196:199], v[116:119]
	v_mfma_f32_16x16x32_bf16 v[108:111], v[142:145], v[204:207], v[108:111]
	v_mfma_f32_16x16x32_bf16 v[100:103], v[142:145], v[212:215], v[100:103]
	v_mfma_f32_16x16x32_bf16 v[124:127], v[146:149], v[192:195], v[124:127]
	v_mfma_f32_16x16x32_bf16 v[120:123], v[180:183], v[188:191], v[120:123]
	v_mfma_f32_16x16x32_bf16 v[116:119], v[146:149], v[200:203], v[116:119]
	v_mfma_f32_16x16x32_bf16 v[112:115], v[180:183], v[196:199], v[112:115]
	v_mfma_f32_16x16x32_bf16 v[108:111], v[146:149], v[208:211], v[108:111]
	v_mfma_f32_16x16x32_bf16 v[104:107], v[180:183], v[204:207], v[104:107]
	v_mfma_f32_16x16x32_bf16 v[100:103], v[146:149], v[216:219], v[100:103]
	v_mfma_f32_16x16x32_bf16 v[96:99], v[180:183], v[212:215], v[96:99]
	v_mfma_f32_16x16x32_bf16 v[138:141], v[184:187], v[192:195], v[120:123]
	v_mfma_f32_16x16x32_bf16 v[220:223], v[184:187], v[200:203], v[112:115]
	v_mfma_f32_16x16x32_bf16 v[224:227], v[184:187], v[208:211], v[104:107]
	v_mfma_f32_16x16x32_bf16 v[228:231], v[184:187], v[216:219], v[96:99]
	s_barrier
	s_nop 1
	ds_read_b128 v[96:99], v169
	ds_read_b128 v[104:107], v169 offset:1024
	ds_read_b128 v[112:115], v169 offset:2048
	ds_read_b128 v[120:123], v169 offset:3072
	s_barrier
	s_waitcnt lgkmcnt(0)
	v_mfma_f32_16x16x32_bf16 v[92:95], v[96:99], v[188:191], v[92:95]
	v_mfma_f32_16x16x32_bf16 v[88:91], v[112:115], v[188:191], v[88:91]
	v_mfma_f32_16x16x32_bf16 v[84:87], v[96:99], v[196:199], v[84:87]
	v_mfma_f32_16x16x32_bf16 v[80:83], v[112:115], v[196:199], v[80:83]
	v_mfma_f32_16x16x32_bf16 v[76:79], v[96:99], v[204:207], v[76:79]
	v_mfma_f32_16x16x32_bf16 v[72:75], v[112:115], v[204:207], v[72:75]
	v_mfma_f32_16x16x32_bf16 v[68:71], v[96:99], v[212:215], v[68:71]
	v_mfma_f32_16x16x32_bf16 v[64:67], v[112:115], v[212:215], v[64:67]
	v_mfma_f32_16x16x32_bf16 v[92:95], v[104:107], v[192:195], v[92:95]
	v_mfma_f32_16x16x32_bf16 v[88:91], v[120:123], v[192:195], v[88:91]
	v_mfma_f32_16x16x32_bf16 v[84:87], v[104:107], v[200:203], v[84:87]
	v_mfma_f32_16x16x32_bf16 v[80:83], v[120:123], v[200:203], v[80:83]
	v_mfma_f32_16x16x32_bf16 v[76:79], v[104:107], v[208:211], v[76:79]
	v_mfma_f32_16x16x32_bf16 v[72:75], v[120:123], v[208:211], v[72:75]
	v_mfma_f32_16x16x32_bf16 v[68:71], v[104:107], v[216:219], v[68:71]
	v_mfma_f32_16x16x32_bf16 v[64:67], v[120:123], v[216:219], v[64:67]
	s_barrier
	ds_read_b128 v[168:171], v161 offset:16384
	ds_read_b128 v[188:191], v161 offset:17408
	ds_read_b128 v[192:195], v160 offset:16384
	ds_read_b128 v[196:199], v160 offset:17408
	ds_read_b128 v[200:203], v159 offset:16384
	ds_read_b128 v[204:207], v159 offset:17408
	ds_read_b128 v[208:211], v158 offset:16384
	ds_read_b128 v[212:215], v158 offset:17408
	s_waitcnt vmcnt(4)
	s_barrier
	s_waitcnt lgkmcnt(0)
	v_mfma_f32_16x16x32_bf16 v[60:63], v[142:145], v[168:171], v[60:63]
	v_mfma_f32_16x16x32_bf16 v[52:55], v[142:145], v[192:195], v[52:55]
	v_mfma_f32_16x16x32_bf16 v[44:47], v[142:145], v[200:203], v[44:47]
	v_mfma_f32_16x16x32_bf16 v[36:39], v[142:145], v[208:211], v[36:39]
	v_mfma_f32_16x16x32_bf16 v[60:63], v[146:149], v[188:191], v[60:63]
	v_mfma_f32_16x16x32_bf16 v[56:59], v[180:183], v[168:171], v[56:59]
	v_mfma_f32_16x16x32_bf16 v[52:55], v[146:149], v[196:199], v[52:55]
	v_mfma_f32_16x16x32_bf16 v[48:51], v[180:183], v[192:195], v[48:51]
	v_mfma_f32_16x16x32_bf16 v[44:47], v[146:149], v[204:207], v[44:47]
	v_mfma_f32_16x16x32_bf16 v[40:43], v[180:183], v[200:203], v[40:43]
	v_mfma_f32_16x16x32_bf16 v[36:39], v[146:149], v[212:215], v[36:39]
	v_mfma_f32_16x16x32_bf16 v[32:35], v[180:183], v[208:211], v[32:35]
	v_mfma_f32_16x16x32_bf16 v[216:219], v[184:187], v[188:191], v[56:59]
	v_mfma_f32_16x16x32_bf16 v[232:235], v[184:187], v[196:199], v[48:51]
	v_mfma_f32_16x16x32_bf16 v[236:239], v[184:187], v[204:207], v[40:43]
	v_mfma_f32_16x16x32_bf16 v[142:145], v[184:187], v[212:215], v[32:35]
	v_mfma_f32_16x16x32_bf16 v[28:31], v[96:99], v[168:171], v[28:31]
	v_mfma_f32_16x16x32_bf16 v[24:27], v[112:115], v[168:171], v[24:27]
	v_mfma_f32_16x16x32_bf16 v[20:23], v[96:99], v[192:195], v[20:23]
	v_mfma_f32_16x16x32_bf16 v[16:19], v[112:115], v[192:195], v[16:19]
	v_mfma_f32_16x16x32_bf16 v[12:15], v[96:99], v[200:203], v[12:15]
	v_mfma_f32_16x16x32_bf16 v[8:11], v[112:115], v[200:203], v[8:11]
	v_mfma_f32_16x16x32_bf16 v[4:7], v[96:99], v[208:211], v[4:7]
	v_mfma_f32_16x16x32_bf16 v[0:3], v[112:115], v[208:211], v[0:3]
	v_mfma_f32_16x16x32_bf16 v[28:31], v[104:107], v[188:191], v[28:31]
	v_mfma_f32_16x16x32_bf16 v[24:27], v[120:123], v[188:191], v[24:27]
	v_mfma_f32_16x16x32_bf16 v[20:23], v[104:107], v[196:199], v[20:23]
	v_mfma_f32_16x16x32_bf16 v[16:19], v[120:123], v[196:199], v[16:19]
	v_mfma_f32_16x16x32_bf16 v[12:15], v[104:107], v[204:207], v[12:15]
	v_mfma_f32_16x16x32_bf16 v[8:11], v[120:123], v[204:207], v[8:11]
	v_mfma_f32_16x16x32_bf16 v[4:7], v[104:107], v[212:215], v[4:7]
	v_mfma_f32_16x16x32_bf16 v[0:3], v[120:123], v[212:215], v[0:3]
	s_barrier
	ds_read_b128 v[32:35], v163
	ds_read_b128 v[146:149], v163 offset:1024
	ds_read_b128 v[168:171], v163 offset:2048
	ds_read_b128 v[178:181], v163 offset:3072
	ds_read_b128 v[40:43], v161 offset:32768
	ds_read_b128 v[48:51], v161 offset:33792
	ds_read_b128 v[56:59], v160 offset:32768
	ds_read_b128 v[182:185], v160 offset:33792
	ds_read_b128 v[186:189], v159 offset:32768
	ds_read_b128 v[190:193], v159 offset:33792
	ds_read_b128 v[194:197], v158 offset:32768
	ds_read_b128 v[198:201], v158 offset:33792
	s_waitcnt vmcnt(2)
	s_barrier
	s_waitcnt lgkmcnt(0)
	v_mfma_f32_16x16x32_bf16 v[96:99], v[32:35], v[40:43], v[124:127]
	v_mfma_f32_16x16x32_bf16 v[120:123], v[146:149], v[48:51], v[96:99]
	v_mfma_f32_16x16x32_bf16 v[96:99], v[168:171], v[40:43], v[138:141]
	v_mfma_f32_16x16x32_bf16 v[124:127], v[178:181], v[48:51], v[96:99]
	v_mfma_f32_16x16x32_bf16 v[96:99], v[32:35], v[56:59], v[116:119]
	v_mfma_f32_16x16x32_bf16 v[112:115], v[146:149], v[182:185], v[96:99]
	v_mfma_f32_16x16x32_bf16 v[96:99], v[168:171], v[56:59], v[220:223]
	v_mfma_f32_16x16x32_bf16 v[116:119], v[178:181], v[182:185], v[96:99]
	v_mfma_f32_16x16x32_bf16 v[96:99], v[32:35], v[186:189], v[108:111]
	v_mfma_f32_16x16x32_bf16 v[104:107], v[146:149], v[190:193], v[96:99]
	v_mfma_f32_16x16x32_bf16 v[96:99], v[168:171], v[186:189], v[224:227]
	v_mfma_f32_16x16x32_bf16 v[108:111], v[178:181], v[190:193], v[96:99]
	v_mfma_f32_16x16x32_bf16 v[96:99], v[32:35], v[194:197], v[100:103]
	v_mfma_f32_16x16x32_bf16 v[100:103], v[168:171], v[194:197], v[228:231]
	v_mfma_f32_16x16x32_bf16 v[96:99], v[146:149], v[198:201], v[96:99]
	v_mfma_f32_16x16x32_bf16 v[100:103], v[178:181], v[198:201], v[100:103]
	s_barrier
	ds_read_b128 v[138:141], v162
	ds_read_b128 v[202:205], v162 offset:1024
	ds_read_b128 v[206:209], v162 offset:2048
	ds_read_b128 v[210:213], v162 offset:3072
	s_waitcnt vmcnt(0)
	s_barrier
	s_waitcnt lgkmcnt(0)
	v_mfma_f32_16x16x32_bf16 v[92:95], v[138:141], v[40:43], v[92:95]
	v_mfma_f32_16x16x32_bf16 v[40:43], v[206:209], v[40:43], v[88:91]
	v_mfma_f32_16x16x32_bf16 v[88:91], v[210:213], v[48:51], v[40:43]
	v_mfma_f32_16x16x32_bf16 v[40:43], v[138:141], v[56:59], v[84:87]
	v_mfma_f32_16x16x32_bf16 v[84:87], v[202:205], v[182:185], v[40:43]
	v_mfma_f32_16x16x32_bf16 v[40:43], v[206:209], v[56:59], v[80:83]
	v_mfma_f32_16x16x32_bf16 v[80:83], v[210:213], v[182:185], v[40:43]
	v_mfma_f32_16x16x32_bf16 v[40:43], v[138:141], v[186:189], v[76:79]
	v_mfma_f32_16x16x32_bf16 v[76:79], v[202:205], v[190:193], v[40:43]
	v_mfma_f32_16x16x32_bf16 v[40:43], v[206:209], v[186:189], v[72:75]
	v_mfma_f32_16x16x32_bf16 v[72:75], v[210:213], v[190:193], v[40:43]
	v_mfma_f32_16x16x32_bf16 v[40:43], v[138:141], v[194:197], v[68:71]
	v_mfma_f32_16x16x32_bf16 v[68:71], v[202:205], v[198:201], v[40:43]
	v_mfma_f32_16x16x32_bf16 v[40:43], v[206:209], v[194:197], v[64:67]
	v_mfma_f32_16x16x32_bf16 v[92:95], v[202:205], v[48:51], v[92:95]
	v_mfma_f32_16x16x32_bf16 v[64:67], v[210:213], v[198:201], v[40:43]
	s_barrier
	ds_read_b128 v[182:185], v161 offset:49152
	ds_read_b128 v[186:189], v161 offset:50176
	ds_read_b128 v[190:193], v160 offset:49152
	ds_read_b128 v[160:163], v160 offset:50176
	ds_read_b128 v[194:197], v159 offset:49152
	ds_read_b128 v[198:201], v159 offset:50176
	ds_read_b128 v[220:223], v158 offset:49152
	ds_read_b128 v[224:227], v158 offset:50176
	s_barrier
	s_waitcnt lgkmcnt(0)
	v_mfma_f32_16x16x32_bf16 v[40:43], v[32:35], v[182:185], v[60:63]
	v_mfma_f32_16x16x32_bf16 v[56:59], v[146:149], v[186:189], v[40:43]
	v_mfma_f32_16x16x32_bf16 v[40:43], v[168:171], v[182:185], v[216:219]
	v_mfma_f32_16x16x32_bf16 v[60:63], v[178:181], v[186:189], v[40:43]
	v_mfma_f32_16x16x32_bf16 v[40:43], v[32:35], v[190:193], v[52:55]
	v_mfma_f32_16x16x32_bf16 v[48:51], v[146:149], v[160:163], v[40:43]
	v_mfma_f32_16x16x32_bf16 v[40:43], v[168:171], v[190:193], v[232:235]
	v_mfma_f32_16x16x32_bf16 v[52:55], v[178:181], v[160:163], v[40:43]
	v_mfma_f32_16x16x32_bf16 v[40:43], v[32:35], v[194:197], v[44:47]
	v_mfma_f32_16x16x32_bf16 v[44:47], v[168:171], v[194:197], v[236:239]
	v_mfma_f32_16x16x32_bf16 v[32:35], v[32:35], v[220:223], v[36:39]
	v_mfma_f32_16x16x32_bf16 v[36:39], v[168:171], v[220:223], v[142:145]
	v_mfma_f32_16x16x32_bf16 v[40:43], v[146:149], v[198:201], v[40:43]
	v_mfma_f32_16x16x32_bf16 v[44:47], v[178:181], v[198:201], v[44:47]
	v_mfma_f32_16x16x32_bf16 v[32:35], v[146:149], v[224:227], v[32:35]
	v_mfma_f32_16x16x32_bf16 v[36:39], v[178:181], v[224:227], v[36:39]
	v_mfma_f32_16x16x32_bf16 v[28:31], v[138:141], v[182:185], v[28:31]
	v_mfma_f32_16x16x32_bf16 v[24:27], v[206:209], v[182:185], v[24:27]
	v_mfma_f32_16x16x32_bf16 v[20:23], v[138:141], v[190:193], v[20:23]
	v_mfma_f32_16x16x32_bf16 v[16:19], v[206:209], v[190:193], v[16:19]
	v_mfma_f32_16x16x32_bf16 v[12:15], v[138:141], v[194:197], v[12:15]
	v_mfma_f32_16x16x32_bf16 v[8:11], v[206:209], v[194:197], v[8:11]
	v_mfma_f32_16x16x32_bf16 v[4:7], v[138:141], v[220:223], v[4:7]
	v_mfma_f32_16x16x32_bf16 v[0:3], v[206:209], v[220:223], v[0:3]
	v_mfma_f32_16x16x32_bf16 v[28:31], v[202:205], v[186:189], v[28:31]
	v_mfma_f32_16x16x32_bf16 v[24:27], v[210:213], v[186:189], v[24:27]
	v_mfma_f32_16x16x32_bf16 v[20:23], v[202:205], v[160:163], v[20:23]
	v_mfma_f32_16x16x32_bf16 v[16:19], v[210:213], v[160:163], v[16:19]
	v_mfma_f32_16x16x32_bf16 v[12:15], v[202:205], v[198:201], v[12:15]
	v_mfma_f32_16x16x32_bf16 v[8:11], v[210:213], v[198:201], v[8:11]
	v_mfma_f32_16x16x32_bf16 v[4:7], v[202:205], v[224:227], v[4:7]
	v_mfma_f32_16x16x32_bf16 v[0:3], v[210:213], v[224:227], v[0:3]
	s_and_b64 vcc, exec, s[66:67]
	s_barrier
	s_cbranch_vccnz .LBB0_193
	s_mul_hi_i32 s0, s82, 0x66666667
	s_lshr_b32 s1, s0, 31
	s_ashr_i32 s0, s0, 1
	s_add_i32 s0, s0, s1
	v_readlane_b32 s1, v255, 15
	s_add_i32 s1, s0, s1
	s_mul_i32 s0, s0, 5
	s_sub_i32 s0, s82, s0
	v_readlane_b32 s2, v255, 14
	s_add_i32 s2, s0, s2
	s_lshl_b32 s8, s2, 8
	s_ashr_i32 s9, s8, 31
	s_lshl_b32 s0, s1, 8
	s_lshl_b64 s[40:41], s[8:9], 11
	s_add_u32 s40, s20, s40
	s_addc_u32 s41, s21, s41
	v_lshl_add_u64 v[138:139], s[40:41], 0, v[130:131]
	v_readfirstlane_b32 s1, v153
	v_lshl_add_u64 v[138:139], v[138:139], 0, v[132:133]
	s_mov_b32 m0, s1
	v_readfirstlane_b32 s1, v173
	global_load_lds_dwordx4 v[138:139], off
	s_mov_b32 m0, s1
	s_ashr_i32 s1, s0, 31
	v_lshl_add_u64 v[138:139], s[40:41], 0, v[134:135]
	s_lshl_b64 s[40:41], s[0:1], 11
	s_add_u32 s40, s45, s40
	v_lshl_add_u64 v[138:139], v[138:139], 0, v[136:137]
	s_addc_u32 s41, s46, s41
	s_bitset1_b32 s8, 7
	global_load_lds_dwordx4 v[138:139], off
	v_lshl_add_u64 v[138:139], s[40:41], 0, v[130:131]
	v_readfirstlane_b32 s1, v152
	s_ashr_i32 s9, s8, 31
	v_lshl_add_u64 v[138:139], v[138:139], 0, v[132:133]
	s_mov_b32 m0, s1
	s_lshl_b64 s[8:9], s[8:9], 11
	global_load_lds_dwordx4 v[138:139], off
	v_lshl_add_u64 v[138:139], s[40:41], 0, v[134:135]
	v_readfirstlane_b32 s1, v174
	s_add_u32 s8, s20, s8
	v_lshl_add_u64 v[138:139], v[138:139], 0, v[136:137]
	s_mov_b32 m0, s1
	s_addc_u32 s9, s21, s9
	global_load_lds_dwordx4 v[138:139], off
	v_lshl_add_u64 v[138:139], s[8:9], 0, v[130:131]
	v_readfirstlane_b32 s1, v151
	v_lshl_add_u64 v[138:139], v[138:139], 0, v[132:133]
	s_mov_b32 m0, s1
	v_readfirstlane_b32 s1, v175
	s_bitset1_b32 s0, 7
	global_load_lds_dwordx4 v[138:139], off
	s_mov_b32 m0, s1
	s_ashr_i32 s1, s0, 31
	s_lshl_b64 s[0:1], s[0:1], 11
	s_add_u32 s0, s45, s0
	v_lshl_add_u64 v[138:139], s[8:9], 0, v[134:135]
	s_addc_u32 s1, s46, s1
	v_lshl_add_u64 v[138:139], v[138:139], 0, v[136:137]
	v_lshl_add_u64 v[130:131], s[0:1], 0, v[130:131]
	v_readfirstlane_b32 s2, v176
	global_load_lds_dwordx4 v[138:139], off
	v_lshl_add_u64 v[130:131], v[130:131], 0, v[132:133]
	s_mov_b32 m0, s2
	s_nop 0
	global_load_lds_dwordx4 v[130:131], off
	v_lshl_add_u64 v[130:131], s[0:1], 0, v[134:135]
	v_readfirstlane_b32 s0, v177
	v_lshl_add_u64 v[130:131], v[130:131], 0, v[136:137]
	s_mov_b32 m0, s0
	s_nop 0
	global_load_lds_dwordx4 v[130:131], off

.LBB0_1529:
	ds_read_b128 v[182:185], v180
	ds_read_b128 v[186:189], v180 offset:1024
	ds_read_b128 v[190:193], v180 offset:2048
	ds_read_b128 v[194:197], v180 offset:3072
	v_add_u32_e32 v0, 0xc000, v162
	v_lshl_add_u64 v[246:247], v[142:143], 0, s[60:61]
	v_readfirstlane_b32 s1, v0
	v_lshl_add_u64 v[2:3], v[246:247], 0, s[18:19]
	s_mov_b32 m0, s1
	ds_read_b128 v[198:201], v161
	ds_read_b128 v[202:205], v161 offset:1024
	ds_read_b128 v[206:209], v160
	ds_read_b128 v[210:213], v160 offset:1024
	ds_read_b128 v[214:217], v159
	ds_read_b128 v[218:221], v159 offset:1024
	ds_read_b128 v[222:225], v158
	ds_read_b128 v[226:229], v158 offset:1024
	global_load_lds_dwordx4 v[2:3], off
	v_add_u32_e32 v2, 0xe000, v162
	v_lshl_add_u64 v[248:249], v[144:145], 0, s[60:61]
	v_readfirstlane_b32 s1, v2
	v_lshl_add_u64 v[230:231], v[248:249], 0, s[18:19]
	s_mov_b32 m0, s1
	s_nop 0
	global_load_lds_dwordx4 v[230:231], off
	s_waitcnt lgkmcnt(8)
	s_barrier
	s_waitcnt lgkmcnt(0)
	v_mfma_f32_16x16x32_bf16 v[128:131], v[182:185], v[198:201], v[128:131]
	v_mfma_f32_16x16x32_bf16 v[124:127], v[190:193], v[198:201], v[124:127]
	v_mfma_f32_16x16x32_bf16 v[120:123], v[182:185], v[206:209], v[120:123]
	v_mfma_f32_16x16x32_bf16 v[116:119], v[190:193], v[206:209], v[116:119]
	v_mfma_f32_16x16x32_bf16 v[112:115], v[182:185], v[214:217], v[112:115]
	v_mfma_f32_16x16x32_bf16 v[108:111], v[190:193], v[214:217], v[108:111]
	v_mfma_f32_16x16x32_bf16 v[104:107], v[182:185], v[222:225], v[104:107]
	v_mfma_f32_16x16x32_bf16 v[100:103], v[190:193], v[222:225], v[100:103]
	v_mfma_f32_16x16x32_bf16 v[128:131], v[186:189], v[202:205], v[128:131]
	v_mfma_f32_16x16x32_bf16 v[124:127], v[194:197], v[202:205], v[124:127]
	v_mfma_f32_16x16x32_bf16 v[120:123], v[186:189], v[210:213], v[120:123]
	v_mfma_f32_16x16x32_bf16 v[116:119], v[194:197], v[210:213], v[116:119]
	v_mfma_f32_16x16x32_bf16 v[112:115], v[186:189], v[218:221], v[112:115]
	v_mfma_f32_16x16x32_bf16 v[108:111], v[194:197], v[218:221], v[108:111]
	v_mfma_f32_16x16x32_bf16 v[104:107], v[186:189], v[226:229], v[104:107]
	v_mfma_f32_16x16x32_bf16 v[100:103], v[194:197], v[226:229], v[100:103]
	s_barrier
	v_lshl_add_u64 v[250:251], v[138:139], 0, s[60:61]
	v_readfirstlane_b32 s1, v147
	v_lshl_add_u64 v[252:253], v[250:251], 0, s[20:21]
	s_mov_b32 m0, s1
	v_add_u32_e32 v3, 0x2000, v147
	ds_read_b128 v[230:233], v178
	ds_read_b128 v[234:237], v178 offset:1024
	ds_read_b128 v[238:241], v178 offset:2048
	ds_read_b128 v[242:245], v178 offset:3072
	global_load_lds_dwordx4 v[252:253], off
	v_lshl_add_u64 v[252:253], v[140:141], 0, s[60:61]
	v_readfirstlane_b32 s1, v3
	v_lshl_add_u64 v[132:133], v[252:253], 0, s[20:21]
	s_mov_b32 m0, s1
	s_add_i32 s1, s0, 2
	global_load_lds_dwordx4 v[132:133], off
	s_barrier
	s_waitcnt lgkmcnt(0)
	v_mfma_f32_16x16x32_bf16 v[96:99], v[230:233], v[198:201], v[96:99]
	v_mfma_f32_16x16x32_bf16 v[92:95], v[238:241], v[198:201], v[92:95]
	v_mfma_f32_16x16x32_bf16 v[88:91], v[230:233], v[206:209], v[88:91]
	v_mfma_f32_16x16x32_bf16 v[84:87], v[238:241], v[206:209], v[84:87]
	v_mfma_f32_16x16x32_bf16 v[80:83], v[230:233], v[214:217], v[80:83]
	v_mfma_f32_16x16x32_bf16 v[76:79], v[238:241], v[214:217], v[76:79]
	v_mfma_f32_16x16x32_bf16 v[72:75], v[230:233], v[222:225], v[72:75]
	v_mfma_f32_16x16x32_bf16 v[68:71], v[238:241], v[222:225], v[68:71]
	v_mfma_f32_16x16x32_bf16 v[96:99], v[234:237], v[202:205], v[96:99]
	v_mfma_f32_16x16x32_bf16 v[92:95], v[242:245], v[202:205], v[92:95]
	v_mfma_f32_16x16x32_bf16 v[88:91], v[234:237], v[210:213], v[88:91]
	v_mfma_f32_16x16x32_bf16 v[84:87], v[242:245], v[210:213], v[84:87]
	v_mfma_f32_16x16x32_bf16 v[80:83], v[234:237], v[218:221], v[80:83]
	v_mfma_f32_16x16x32_bf16 v[76:79], v[242:245], v[218:221], v[76:79]
	v_mfma_f32_16x16x32_bf16 v[72:75], v[234:237], v[226:229], v[72:75]
	v_mfma_f32_16x16x32_bf16 v[68:71], v[242:245], v[226:229], v[68:71]
	v_readfirstlane_b32 s2, v162
	v_lshl_add_u64 v[132:133], v[246:247], 0, s[24:25]
	s_mov_b32 m0, s2
	v_readfirstlane_b32 s2, v163
	s_barrier
	ds_read_b128 v[198:201], v161 offset:16384
	ds_read_b128 v[202:205], v161 offset:17408
	ds_read_b128 v[206:209], v160 offset:16384
	ds_read_b128 v[210:213], v160 offset:17408
	ds_read_b128 v[214:217], v159 offset:16384
	ds_read_b128 v[218:221], v159 offset:17408
	ds_read_b128 v[222:225], v158 offset:16384
	ds_read_b128 v[226:229], v158 offset:17408
	global_load_lds_dwordx4 v[132:133], off
	v_lshl_add_u64 v[132:133], v[248:249], 0, s[24:25]
	s_mov_b32 m0, s2
	s_nop 0
	global_load_lds_dwordx4 v[132:133], off
	s_barrier
	s_waitcnt lgkmcnt(0)
	v_mfma_f32_16x16x32_bf16 v[64:67], v[182:185], v[198:201], v[64:67]
	v_mfma_f32_16x16x32_bf16 v[60:63], v[190:193], v[198:201], v[60:63]
	v_mfma_f32_16x16x32_bf16 v[56:59], v[182:185], v[206:209], v[56:59]
	v_mfma_f32_16x16x32_bf16 v[52:55], v[190:193], v[206:209], v[52:55]
	v_mfma_f32_16x16x32_bf16 v[48:51], v[182:185], v[214:217], v[48:51]
	v_mfma_f32_16x16x32_bf16 v[44:47], v[190:193], v[214:217], v[44:47]
	v_mfma_f32_16x16x32_bf16 v[40:43], v[182:185], v[222:225], v[40:43]
	v_mfma_f32_16x16x32_bf16 v[36:39], v[190:193], v[222:225], v[36:39]
	v_mfma_f32_16x16x32_bf16 v[64:67], v[186:189], v[202:205], v[64:67]
	v_mfma_f32_16x16x32_bf16 v[60:63], v[194:197], v[202:205], v[60:63]
	v_mfma_f32_16x16x32_bf16 v[56:59], v[186:189], v[210:213], v[56:59]
	v_mfma_f32_16x16x32_bf16 v[52:55], v[194:197], v[210:213], v[52:55]
	v_mfma_f32_16x16x32_bf16 v[48:51], v[186:189], v[218:221], v[48:51]
	v_mfma_f32_16x16x32_bf16 v[44:47], v[194:197], v[218:221], v[44:47]
	v_mfma_f32_16x16x32_bf16 v[40:43], v[186:189], v[226:229], v[40:43]
	v_mfma_f32_16x16x32_bf16 v[36:39], v[194:197], v[226:229], v[36:39]
	s_barrier
	v_readfirstlane_b32 s2, v168
	v_add_u32_e32 v3, 0x2000, v168
	v_lshl_add_u64 v[132:133], v[250:251], 0, s[26:27]
	s_mov_b32 m0, s2
	v_readfirstlane_b32 s2, v3
	global_load_lds_dwordx4 v[132:133], off
	v_lshl_add_u64 v[132:133], v[252:253], 0, s[26:27]
	s_mov_b32 m0, s2
	s_nop 0
	global_load_lds_dwordx4 v[132:133], off
	s_waitcnt vmcnt(6)
	s_barrier
	v_mfma_f32_16x16x32_bf16 v[32:35], v[230:233], v[198:201], v[32:35]
	v_mfma_f32_16x16x32_bf16 v[28:31], v[238:241], v[198:201], v[28:31]
	v_mfma_f32_16x16x32_bf16 v[24:27], v[230:233], v[206:209], v[24:27]
	v_mfma_f32_16x16x32_bf16 v[20:23], v[238:241], v[206:209], v[20:23]
	v_mfma_f32_16x16x32_bf16 v[16:19], v[230:233], v[214:217], v[16:19]
	v_mfma_f32_16x16x32_bf16 v[12:15], v[238:241], v[214:217], v[12:15]
	v_mfma_f32_16x16x32_bf16 v[8:11], v[230:233], v[222:225], v[8:11]
	v_mfma_f32_16x16x32_bf16 v[4:7], v[238:241], v[222:225], v[4:7]
	v_mfma_f32_16x16x32_bf16 v[32:35], v[234:237], v[202:205], v[32:35]
	v_mfma_f32_16x16x32_bf16 v[28:31], v[242:245], v[202:205], v[28:31]
	v_mfma_f32_16x16x32_bf16 v[24:27], v[234:237], v[210:213], v[24:27]
	v_mfma_f32_16x16x32_bf16 v[20:23], v[242:245], v[210:213], v[20:23]
	v_mfma_f32_16x16x32_bf16 v[16:19], v[234:237], v[218:221], v[16:19]
	v_mfma_f32_16x16x32_bf16 v[12:15], v[242:245], v[218:221], v[12:15]
	v_mfma_f32_16x16x32_bf16 v[8:11], v[234:237], v[226:229], v[8:11]
	v_mfma_f32_16x16x32_bf16 v[4:7], v[242:245], v[226:229], v[4:7]
	s_barrier
	ds_read_b128 v[182:185], v170
	ds_read_b128 v[186:189], v170 offset:1024
	ds_read_b128 v[190:193], v170 offset:2048
	ds_read_b128 v[194:197], v170 offset:3072
	v_readfirstlane_b32 s2, v169
	v_lshl_add_u64 v[132:133], v[246:247], 0, s[28:29]
	s_mov_b32 m0, s2
	v_readfirstlane_b32 s2, v171
	ds_read_b128 v[198:201], v161 offset:32768
	ds_read_b128 v[202:205], v161 offset:33792
	ds_read_b128 v[206:209], v160 offset:32768
	ds_read_b128 v[210:213], v160 offset:33792
	ds_read_b128 v[214:217], v159 offset:32768
	ds_read_b128 v[218:221], v159 offset:33792
	ds_read_b128 v[222:225], v158 offset:32768
	ds_read_b128 v[226:229], v158 offset:33792
	global_load_lds_dwordx4 v[132:133], off
	v_lshl_add_u64 v[132:133], v[248:249], 0, s[28:29]
	s_mov_b32 m0, s2
	s_nop 0
	global_load_lds_dwordx4 v[132:133], off
	s_waitcnt lgkmcnt(8)
	s_barrier
	s_waitcnt lgkmcnt(0)
	v_mfma_f32_16x16x32_bf16 v[128:131], v[182:185], v[198:201], v[128:131]
	v_mfma_f32_16x16x32_bf16 v[124:127], v[190:193], v[198:201], v[124:127]
	v_mfma_f32_16x16x32_bf16 v[120:123], v[182:185], v[206:209], v[120:123]
	v_mfma_f32_16x16x32_bf16 v[116:119], v[190:193], v[206:209], v[116:119]
	v_mfma_f32_16x16x32_bf16 v[112:115], v[182:185], v[214:217], v[112:115]
	v_mfma_f32_16x16x32_bf16 v[108:111], v[190:193], v[214:217], v[108:111]
	v_mfma_f32_16x16x32_bf16 v[104:107], v[182:185], v[222:225], v[104:107]
	v_mfma_f32_16x16x32_bf16 v[100:103], v[190:193], v[222:225], v[100:103]
	v_mfma_f32_16x16x32_bf16 v[128:131], v[186:189], v[202:205], v[128:131]
	v_mfma_f32_16x16x32_bf16 v[124:127], v[194:197], v[202:205], v[124:127]
	v_mfma_f32_16x16x32_bf16 v[120:123], v[186:189], v[210:213], v[120:123]
	v_mfma_f32_16x16x32_bf16 v[116:119], v[194:197], v[210:213], v[116:119]
	v_mfma_f32_16x16x32_bf16 v[112:115], v[186:189], v[218:221], v[112:115]
	v_mfma_f32_16x16x32_bf16 v[108:111], v[194:197], v[218:221], v[108:111]
	v_mfma_f32_16x16x32_bf16 v[104:107], v[186:189], v[226:229], v[104:107]
	v_mfma_f32_16x16x32_bf16 v[100:103], v[194:197], v[226:229], v[100:103]
	s_barrier
	v_readfirstlane_b32 s2, v172
	v_lshl_add_u64 v[132:133], v[250:251], 0, s[30:31]
	s_mov_b32 m0, s2
	v_readfirstlane_b32 s2, v173
	ds_read_b128 v[230:233], v167
	ds_read_b128 v[234:237], v167 offset:1024
	ds_read_b128 v[238:241], v167 offset:2048
	ds_read_b128 v[242:245], v167 offset:3072
	global_load_lds_dwordx4 v[132:133], off
	v_lshl_add_u64 v[132:133], v[252:253], 0, s[30:31]
	s_mov_b32 m0, s2
	s_nop 0
	global_load_lds_dwordx4 v[132:133], off
	s_barrier
	s_waitcnt lgkmcnt(0)
	v_mfma_f32_16x16x32_bf16 v[96:99], v[230:233], v[198:201], v[96:99]
	v_mfma_f32_16x16x32_bf16 v[92:95], v[238:241], v[198:201], v[92:95]
	v_mfma_f32_16x16x32_bf16 v[88:91], v[230:233], v[206:209], v[88:91]
	v_mfma_f32_16x16x32_bf16 v[84:87], v[238:241], v[206:209], v[84:87]
	v_mfma_f32_16x16x32_bf16 v[80:83], v[230:233], v[214:217], v[80:83]
	v_mfma_f32_16x16x32_bf16 v[76:79], v[238:241], v[214:217], v[76:79]
	v_mfma_f32_16x16x32_bf16 v[72:75], v[230:233], v[222:225], v[72:75]
	v_mfma_f32_16x16x32_bf16 v[68:71], v[238:241], v[222:225], v[68:71]
	v_mfma_f32_16x16x32_bf16 v[96:99], v[234:237], v[202:205], v[96:99]
	v_mfma_f32_16x16x32_bf16 v[92:95], v[242:245], v[202:205], v[92:95]
	v_mfma_f32_16x16x32_bf16 v[88:91], v[234:237], v[210:213], v[88:91]
	v_mfma_f32_16x16x32_bf16 v[84:87], v[242:245], v[210:213], v[84:87]
	v_mfma_f32_16x16x32_bf16 v[80:83], v[234:237], v[218:221], v[80:83]
	v_mfma_f32_16x16x32_bf16 v[76:79], v[242:245], v[218:221], v[76:79]
	v_mfma_f32_16x16x32_bf16 v[72:75], v[234:237], v[226:229], v[72:75]
	v_mfma_f32_16x16x32_bf16 v[68:71], v[242:245], v[226:229], v[68:71]
	v_readfirstlane_b32 s2, v174
	v_lshl_add_u64 v[132:133], v[246:247], 0, s[34:35]
	s_mov_b32 m0, s2
	v_readfirstlane_b32 s2, v175
	s_barrier
	ds_read_b128 v[198:201], v161 offset:49152
	ds_read_b128 v[202:205], v161 offset:50176
	ds_read_b128 v[206:209], v160 offset:49152
	ds_read_b128 v[210:213], v160 offset:50176
	ds_read_b128 v[214:217], v159 offset:49152
	ds_read_b128 v[218:221], v159 offset:50176
	ds_read_b128 v[222:225], v158 offset:49152
	ds_read_b128 v[226:229], v158 offset:50176
	global_load_lds_dwordx4 v[132:133], off
	v_lshl_add_u64 v[132:133], v[248:249], 0, s[34:35]
	s_mov_b32 m0, s2
	s_nop 0
	global_load_lds_dwordx4 v[132:133], off
	s_barrier
	s_waitcnt lgkmcnt(0)
	v_mfma_f32_16x16x32_bf16 v[64:67], v[182:185], v[198:201], v[64:67]
	v_mfma_f32_16x16x32_bf16 v[60:63], v[190:193], v[198:201], v[60:63]
	v_mfma_f32_16x16x32_bf16 v[56:59], v[182:185], v[206:209], v[56:59]
	v_mfma_f32_16x16x32_bf16 v[52:55], v[190:193], v[206:209], v[52:55]
	v_mfma_f32_16x16x32_bf16 v[48:51], v[182:185], v[214:217], v[48:51]
	v_mfma_f32_16x16x32_bf16 v[44:47], v[190:193], v[214:217], v[44:47]
	v_mfma_f32_16x16x32_bf16 v[40:43], v[182:185], v[222:225], v[40:43]
	v_mfma_f32_16x16x32_bf16 v[36:39], v[190:193], v[222:225], v[36:39]
	v_mfma_f32_16x16x32_bf16 v[64:67], v[186:189], v[202:205], v[64:67]
	v_mfma_f32_16x16x32_bf16 v[60:63], v[194:197], v[202:205], v[60:63]
	v_mfma_f32_16x16x32_bf16 v[56:59], v[186:189], v[210:213], v[56:59]
	v_mfma_f32_16x16x32_bf16 v[52:55], v[194:197], v[210:213], v[52:55]
	v_mfma_f32_16x16x32_bf16 v[48:51], v[186:189], v[218:221], v[48:51]
	v_mfma_f32_16x16x32_bf16 v[44:47], v[194:197], v[218:221], v[44:47]
	v_mfma_f32_16x16x32_bf16 v[40:43], v[186:189], v[226:229], v[40:43]
	v_mfma_f32_16x16x32_bf16 v[36:39], v[194:197], v[226:229], v[36:39]
	s_barrier
	v_readfirstlane_b32 s2, v176
	v_lshl_add_u64 v[132:133], v[250:251], 0, s[36:37]
	s_mov_b32 m0, s2
	v_readfirstlane_b32 s2, v177
	global_load_lds_dwordx4 v[132:133], off
	v_lshl_add_u64 v[132:133], v[252:253], 0, s[36:37]
	s_mov_b32 m0, s2
	s_nop 0
	global_load_lds_dwordx4 v[132:133], off
	s_waitcnt vmcnt(6)
	s_barrier
	v_mfma_f32_16x16x32_bf16 v[32:35], v[230:233], v[198:201], v[32:35]
	v_mfma_f32_16x16x32_bf16 v[28:31], v[238:241], v[198:201], v[28:31]
	v_mfma_f32_16x16x32_bf16 v[24:27], v[230:233], v[206:209], v[24:27]
	v_mfma_f32_16x16x32_bf16 v[20:23], v[238:241], v[206:209], v[20:23]
	v_mfma_f32_16x16x32_bf16 v[16:19], v[230:233], v[214:217], v[16:19]
	v_mfma_f32_16x16x32_bf16 v[12:15], v[238:241], v[214:217], v[12:15]
	v_mfma_f32_16x16x32_bf16 v[8:11], v[230:233], v[222:225], v[8:11]
	v_mfma_f32_16x16x32_bf16 v[4:7], v[238:241], v[222:225], v[4:7]
	v_mfma_f32_16x16x32_bf16 v[32:35], v[234:237], v[202:205], v[32:35]
	v_mfma_f32_16x16x32_bf16 v[28:31], v[242:245], v[202:205], v[28:31]
	v_mfma_f32_16x16x32_bf16 v[24:27], v[234:237], v[210:213], v[24:27]
	v_mfma_f32_16x16x32_bf16 v[20:23], v[242:245], v[210:213], v[20:23]
	v_mfma_f32_16x16x32_bf16 v[16:19], v[234:237], v[218:221], v[16:19]
	v_mfma_f32_16x16x32_bf16 v[12:15], v[242:245], v[218:221], v[12:15]
	v_mfma_f32_16x16x32_bf16 v[8:11], v[234:237], v[226:229], v[8:11]
	v_mfma_f32_16x16x32_bf16 v[4:7], v[242:245], v[226:229], v[4:7]
	s_add_u32 s60, s60, 0x100
	s_addc_u32 s61, s61, 0
	s_cmp_gt_u32 s0, 11
	s_barrier
	s_cbranch_scc1 .LBB0_1532
	s_mov_b32 s0, s1
	s_cmp_lt_i32 s0, 12
	s_cbranch_scc1 .LBB0_1493

.LBB0_1532:
	v_readfirstlane_b32 s0, v0
	v_lshl_add_u64 v[134:135], v[134:135], 0, s[56:57]
	s_mov_b32 m0, s0
	v_readfirstlane_b32 s0, v2
	ds_read_b128 v[138:141], v180
	ds_read_b128 v[142:145], v180 offset:1024
	ds_read_b128 v[172:175], v180 offset:2048
	ds_read_b128 v[180:183], v180 offset:3072
	ds_read_b128 v[184:187], v161
	ds_read_b128 v[188:191], v161 offset:1024
	ds_read_b128 v[192:195], v160
	ds_read_b128 v[196:199], v160 offset:1024
	ds_read_b128 v[200:203], v159
	ds_read_b128 v[204:207], v159 offset:1024
	ds_read_b128 v[208:211], v158
	ds_read_b128 v[212:215], v158 offset:1024
	global_load_lds_dwordx4 v[134:135], off
	v_lshl_add_u64 v[134:135], v[136:137], 0, s[56:57]
	s_mov_b32 m0, s0
	s_nop 0
	global_load_lds_dwordx4 v[134:135], off
	s_barrier
	s_waitcnt lgkmcnt(0)
	v_mfma_f32_16x16x32_bf16 v[128:131], v[138:141], v[184:187], v[128:131]
	v_mfma_f32_16x16x32_bf16 v[124:127], v[172:175], v[184:187], v[124:127]
	v_mfma_f32_16x16x32_bf16 v[120:123], v[138:141], v[192:195], v[120:123]
	v_mfma_f32_16x16x32_bf16 v[116:119], v[172:175], v[192:195], v[116:119]
	v_mfma_f32_16x16x32_bf16 v[112:115], v[138:141], v[200:203], v[112:115]
	v_mfma_f32_16x16x32_bf16 v[108:111], v[172:175], v[200:203], v[108:111]
	v_mfma_f32_16x16x32_bf16 v[104:107], v[138:141], v[208:211], v[104:107]
	v_mfma_f32_16x16x32_bf16 v[100:103], v[172:175], v[208:211], v[100:103]
	v_mfma_f32_16x16x32_bf16 v[128:131], v[142:145], v[188:191], v[128:131]
	v_mfma_f32_16x16x32_bf16 v[124:127], v[180:183], v[188:191], v[124:127]
	v_mfma_f32_16x16x32_bf16 v[120:123], v[142:145], v[196:199], v[120:123]
	v_mfma_f32_16x16x32_bf16 v[116:119], v[180:183], v[196:199], v[116:119]
	v_mfma_f32_16x16x32_bf16 v[112:115], v[142:145], v[204:207], v[112:115]
	v_mfma_f32_16x16x32_bf16 v[108:111], v[180:183], v[204:207], v[108:111]
	v_mfma_f32_16x16x32_bf16 v[104:107], v[142:145], v[212:215], v[104:107]
	v_mfma_f32_16x16x32_bf16 v[100:103], v[180:183], v[212:215], v[100:103]
	s_barrier
	ds_read_b128 v[134:137], v178
	ds_read_b128 v[216:219], v178 offset:1024
	ds_read_b128 v[220:223], v178 offset:2048
	ds_read_b128 v[176:179], v178 offset:3072
	s_barrier
	s_waitcnt lgkmcnt(0)
	v_mfma_f32_16x16x32_bf16 v[96:99], v[134:137], v[184:187], v[96:99]
	v_mfma_f32_16x16x32_bf16 v[92:95], v[220:223], v[184:187], v[92:95]
	v_mfma_f32_16x16x32_bf16 v[88:91], v[134:137], v[192:195], v[88:91]
	v_mfma_f32_16x16x32_bf16 v[84:87], v[220:223], v[192:195], v[84:87]
	v_mfma_f32_16x16x32_bf16 v[80:83], v[134:137], v[200:203], v[80:83]
	v_mfma_f32_16x16x32_bf16 v[76:79], v[220:223], v[200:203], v[76:79]
	v_mfma_f32_16x16x32_bf16 v[72:75], v[134:137], v[208:211], v[72:75]
	v_mfma_f32_16x16x32_bf16 v[68:71], v[220:223], v[208:211], v[68:71]
	v_mfma_f32_16x16x32_bf16 v[96:99], v[216:219], v[188:191], v[96:99]
	v_mfma_f32_16x16x32_bf16 v[92:95], v[176:179], v[188:191], v[92:95]
	v_mfma_f32_16x16x32_bf16 v[88:91], v[216:219], v[196:199], v[88:91]
	v_mfma_f32_16x16x32_bf16 v[84:87], v[176:179], v[196:199], v[84:87]
	v_mfma_f32_16x16x32_bf16 v[80:83], v[216:219], v[204:207], v[80:83]
	v_mfma_f32_16x16x32_bf16 v[76:79], v[176:179], v[204:207], v[76:79]
	v_mfma_f32_16x16x32_bf16 v[72:75], v[216:219], v[212:215], v[72:75]
	v_mfma_f32_16x16x32_bf16 v[68:71], v[176:179], v[212:215], v[68:71]
	s_barrier
	ds_read_b128 v[184:187], v161 offset:16384
	ds_read_b128 v[188:191], v161 offset:17408
	ds_read_b128 v[192:195], v160 offset:16384
	ds_read_b128 v[196:199], v160 offset:17408
	ds_read_b128 v[200:203], v159 offset:16384
	ds_read_b128 v[204:207], v159 offset:17408
	ds_read_b128 v[208:211], v158 offset:16384
	ds_read_b128 v[212:215], v158 offset:17408
	s_waitcnt vmcnt(4)
	s_barrier
	s_waitcnt lgkmcnt(0)
	v_mfma_f32_16x16x32_bf16 v[64:67], v[138:141], v[184:187], v[64:67]
	v_mfma_f32_16x16x32_bf16 v[56:59], v[138:141], v[192:195], v[56:59]
	v_mfma_f32_16x16x32_bf16 v[48:51], v[138:141], v[200:203], v[48:51]
	v_mfma_f32_16x16x32_bf16 v[40:43], v[138:141], v[208:211], v[40:43]
	v_mfma_f32_16x16x32_bf16 v[36:39], v[172:175], v[208:211], v[36:39]
	v_mfma_f32_16x16x32_bf16 v[224:227], v[142:145], v[188:191], v[64:67]
	v_mfma_f32_16x16x32_bf16 v[60:63], v[172:175], v[184:187], v[60:63]
	v_mfma_f32_16x16x32_bf16 v[232:235], v[142:145], v[196:199], v[56:59]
	v_mfma_f32_16x16x32_bf16 v[52:55], v[172:175], v[192:195], v[52:55]
	v_mfma_f32_16x16x32_bf16 v[240:243], v[142:145], v[204:207], v[48:51]
	v_mfma_f32_16x16x32_bf16 v[44:47], v[172:175], v[200:203], v[44:47]
	v_mfma_f32_16x16x32_bf16 v[138:141], v[142:145], v[212:215], v[40:43]
	v_mfma_f32_16x16x32_bf16 v[142:145], v[180:183], v[212:215], v[36:39]
	v_mfma_f32_16x16x32_bf16 v[228:231], v[180:183], v[188:191], v[60:63]
	v_mfma_f32_16x16x32_bf16 v[236:239], v[180:183], v[196:199], v[52:55]
	v_mfma_f32_16x16x32_bf16 v[244:247], v[180:183], v[204:207], v[44:47]
	v_mfma_f32_16x16x32_bf16 v[8:11], v[134:137], v[208:211], v[8:11]
	v_mfma_f32_16x16x32_bf16 v[32:35], v[134:137], v[184:187], v[32:35]
	v_mfma_f32_16x16x32_bf16 v[28:31], v[220:223], v[184:187], v[28:31]
	v_mfma_f32_16x16x32_bf16 v[24:27], v[134:137], v[192:195], v[24:27]
	v_mfma_f32_16x16x32_bf16 v[20:23], v[220:223], v[192:195], v[20:23]
	v_mfma_f32_16x16x32_bf16 v[16:19], v[134:137], v[200:203], v[16:19]
	v_mfma_f32_16x16x32_bf16 v[12:15], v[220:223], v[200:203], v[12:15]
	v_mfma_f32_16x16x32_bf16 v[134:137], v[216:219], v[212:215], v[8:11]
	v_mfma_f32_16x16x32_bf16 v[2:5], v[220:223], v[208:211], v[4:7]
	v_mfma_f32_16x16x32_bf16 v[172:175], v[216:219], v[188:191], v[32:35]
	v_mfma_f32_16x16x32_bf16 v[180:183], v[176:179], v[188:191], v[28:31]
	v_mfma_f32_16x16x32_bf16 v[184:187], v[216:219], v[196:199], v[24:27]
	v_mfma_f32_16x16x32_bf16 v[188:191], v[176:179], v[196:199], v[20:23]
	v_mfma_f32_16x16x32_bf16 v[192:195], v[216:219], v[204:207], v[16:19]
	v_mfma_f32_16x16x32_bf16 v[196:199], v[176:179], v[204:207], v[12:15]
	v_mfma_f32_16x16x32_bf16 v[176:179], v[176:179], v[212:215], v[2:5]
	s_barrier
	ds_read_b128 v[200:203], v170
	ds_read_b128 v[204:207], v170 offset:1024
	ds_read_b128 v[208:211], v170 offset:2048
	ds_read_b128 v[168:171], v170 offset:3072
	ds_read_b128 v[22:25], v161 offset:32768
	ds_read_b128 v[34:37], v161 offset:33792
	ds_read_b128 v[38:41], v160 offset:32768
	ds_read_b128 v[50:53], v160 offset:33792
	ds_read_b128 v[54:57], v159 offset:32768
	ds_read_b128 v[58:61], v159 offset:33792
	ds_read_b128 v[62:65], v158 offset:32768
	ds_read_b128 v[212:215], v158 offset:33792
	s_waitcnt vmcnt(2)
	s_barrier
	s_waitcnt lgkmcnt(0)
	v_mfma_f32_16x16x32_bf16 v[18:21], v[200:203], v[54:57], v[112:115]
	v_mfma_f32_16x16x32_bf16 v[26:29], v[204:207], v[58:61], v[18:21]
	v_mfma_f32_16x16x32_bf16 v[18:21], v[208:211], v[54:57], v[108:111]
	v_mfma_f32_16x16x32_bf16 v[30:33], v[168:171], v[58:61], v[18:21]
	v_mfma_f32_16x16x32_bf16 v[18:21], v[200:203], v[62:65], v[104:107]
	v_mfma_f32_16x16x32_bf16 v[2:5], v[200:203], v[22:25], v[128:131]
	v_mfma_f32_16x16x32_bf16 v[6:9], v[208:211], v[22:25], v[124:127]
	v_mfma_f32_16x16x32_bf16 v[10:13], v[200:203], v[38:41], v[120:123]
	v_mfma_f32_16x16x32_bf16 v[14:17], v[208:211], v[38:41], v[116:119]
	v_mfma_f32_16x16x32_bf16 v[42:45], v[204:207], v[212:215], v[18:21]
	v_mfma_f32_16x16x32_bf16 v[18:21], v[208:211], v[62:65], v[100:103]
	v_mfma_f32_16x16x32_bf16 v[2:5], v[204:207], v[34:37], v[2:5]
	v_mfma_f32_16x16x32_bf16 v[6:9], v[168:171], v[34:37], v[6:9]
	v_mfma_f32_16x16x32_bf16 v[10:13], v[204:207], v[50:53], v[10:13]
	v_mfma_f32_16x16x32_bf16 v[14:17], v[168:171], v[50:53], v[14:17]
	v_mfma_f32_16x16x32_bf16 v[46:49], v[168:171], v[212:215], v[18:21]
	s_barrier
	ds_read_b128 v[122:125], v167
	ds_read_b128 v[126:129], v167 offset:1024
	ds_read_b128 v[216:219], v167 offset:2048
	ds_read_b128 v[220:223], v167 offset:3072
	s_waitcnt vmcnt(0)
	s_barrier
	s_waitcnt lgkmcnt(0)
	v_mfma_f32_16x16x32_bf16 v[18:21], v[122:125], v[22:25], v[96:99]
	v_mfma_f32_16x16x32_bf16 v[22:25], v[216:219], v[22:25], v[92:95]
	v_mfma_f32_16x16x32_bf16 v[18:21], v[126:129], v[34:37], v[18:21]
	v_mfma_f32_16x16x32_bf16 v[22:25], v[220:223], v[34:37], v[22:25]
	v_mfma_f32_16x16x32_bf16 v[34:37], v[122:125], v[38:41], v[88:91]
	v_mfma_f32_16x16x32_bf16 v[38:41], v[216:219], v[38:41], v[84:87]
	v_mfma_f32_16x16x32_bf16 v[34:37], v[126:129], v[50:53], v[34:37]
	v_mfma_f32_16x16x32_bf16 v[38:41], v[220:223], v[50:53], v[38:41]
	v_mfma_f32_16x16x32_bf16 v[50:53], v[122:125], v[54:57], v[80:83]
	v_mfma_f32_16x16x32_bf16 v[54:57], v[216:219], v[54:57], v[76:79]
	v_mfma_f32_16x16x32_bf16 v[50:53], v[126:129], v[58:61], v[50:53]
	v_mfma_f32_16x16x32_bf16 v[54:57], v[220:223], v[58:61], v[54:57]
	v_mfma_f32_16x16x32_bf16 v[58:61], v[122:125], v[62:65], v[72:75]
	v_mfma_f32_16x16x32_bf16 v[62:65], v[216:219], v[62:65], v[68:71]
	v_mfma_f32_16x16x32_bf16 v[58:61], v[126:129], v[212:215], v[58:61]
	v_mfma_f32_16x16x32_bf16 v[62:65], v[220:223], v[212:215], v[62:65]
	s_barrier
	ds_read_b128 v[86:89], v161 offset:49152
	ds_read_b128 v[94:97], v161 offset:50176
	ds_read_b128 v[102:105], v160 offset:49152
	ds_read_b128 v[110:113], v160 offset:50176
	ds_read_b128 v[118:121], v159 offset:49152
	ds_read_b128 v[160:163], v159 offset:50176
	ds_read_b128 v[212:215], v158 offset:49152
	ds_read_b128 v[248:251], v158 offset:50176
	s_barrier
	s_waitcnt lgkmcnt(0)
	v_mfma_f32_16x16x32_bf16 v[78:81], v[208:211], v[102:105], v[236:239]
	v_mfma_f32_16x16x32_bf16 v[82:85], v[168:171], v[110:113], v[78:81]
	v_mfma_f32_16x16x32_bf16 v[78:81], v[200:203], v[118:121], v[240:243]
	v_mfma_f32_16x16x32_bf16 v[90:93], v[204:207], v[160:163], v[78:81]
	v_mfma_f32_16x16x32_bf16 v[78:81], v[208:211], v[118:121], v[244:247]
	v_mfma_f32_16x16x32_bf16 v[98:101], v[168:171], v[160:163], v[78:81]
	v_mfma_f32_16x16x32_bf16 v[78:81], v[200:203], v[212:215], v[138:141]
	v_mfma_f32_16x16x32_bf16 v[66:69], v[200:203], v[86:89], v[224:227]
	v_mfma_f32_16x16x32_bf16 v[70:73], v[208:211], v[86:89], v[228:231]
	v_mfma_f32_16x16x32_bf16 v[74:77], v[200:203], v[102:105], v[232:235]
	v_mfma_f32_16x16x32_bf16 v[106:109], v[204:207], v[248:251], v[78:81]
	v_mfma_f32_16x16x32_bf16 v[78:81], v[208:211], v[212:215], v[142:145]
	v_mfma_f32_16x16x32_bf16 v[66:69], v[204:207], v[94:97], v[66:69]
	v_mfma_f32_16x16x32_bf16 v[70:73], v[168:171], v[94:97], v[70:73]
	v_mfma_f32_16x16x32_bf16 v[74:77], v[204:207], v[110:113], v[74:77]
	v_mfma_f32_16x16x32_bf16 v[114:117], v[168:171], v[248:251], v[78:81]
	v_mfma_f32_16x16x32_bf16 v[78:81], v[122:125], v[86:89], v[172:175]
	v_mfma_f32_16x16x32_bf16 v[86:89], v[216:219], v[86:89], v[180:183]
	v_mfma_f32_16x16x32_bf16 v[78:81], v[126:129], v[94:97], v[78:81]
	v_mfma_f32_16x16x32_bf16 v[86:89], v[220:223], v[94:97], v[86:89]
	v_mfma_f32_16x16x32_bf16 v[94:97], v[122:125], v[102:105], v[184:187]
	v_mfma_f32_16x16x32_bf16 v[102:105], v[216:219], v[102:105], v[188:191]
	v_mfma_f32_16x16x32_bf16 v[94:97], v[126:129], v[110:113], v[94:97]
	v_mfma_f32_16x16x32_bf16 v[102:105], v[220:223], v[110:113], v[102:105]
	v_mfma_f32_16x16x32_bf16 v[110:113], v[122:125], v[118:121], v[192:195]
	v_mfma_f32_16x16x32_bf16 v[122:125], v[122:125], v[212:215], v[134:137]
	v_mfma_f32_16x16x32_bf16 v[110:113], v[126:129], v[160:163], v[110:113]
	v_mfma_f32_16x16x32_bf16 v[118:121], v[216:219], v[118:121], v[196:199]
	v_mfma_f32_16x16x32_bf16 v[122:125], v[126:129], v[248:251], v[122:125]
	v_mfma_f32_16x16x32_bf16 v[126:129], v[216:219], v[212:215], v[176:179]
	v_mfma_f32_16x16x32_bf16 v[118:121], v[220:223], v[160:163], v[118:121]
	v_mfma_f32_16x16x32_bf16 v[126:129], v[220:223], v[248:251], v[126:129]
	v_and_b32_e32 v0, 0xffffff00, v149
	v_lshlrev_b32_e32 v130, 2, v155
	v_add3_u32 v131, s70, v0, v130
	v_add3_u32 v0, s71, v0, v130
	s_barrier
	ds_read2_b32 v[136:137], v131 offset1:16
	ds_read2_b32 v[138:139], v131 offset0:32 offset1:48
	ds_read2_b32 v[142:143], v0 offset1:16
	ds_read2_b32 v[146:147], v0 offset0:32 offset1:48
	v_cmp_gt_u32_e32 vcc, s55, v149
	s_waitcnt lgkmcnt(0)
	v_mov_b32_e32 v0, v137
	v_mov_b32_e32 v140, v139
	v_mov_b32_e32 v144, v143
	v_mov_b32_e32 v134, v147
	s_and_saveexec_b64 s[4:5], vcc
	s_cbranch_execz .LBB0_1487
	s_barrier
	s_branch .LBB0_1487

.LBB0_1661:
	ds_read_b128 v[180:183], v172
	ds_read_b128 v[184:187], v172 offset:1024
	ds_read_b128 v[188:191], v172 offset:2048
	ds_read_b128 v[192:195], v172 offset:3072
	v_add_u32_e32 v178, 0xc000, v152
	v_lshl_add_u64 v[244:245], s[8:9], 0, v[146:147]
	v_readfirstlane_b32 s1, v178
	v_add_u32_e32 v179, 0xe000, v152
	v_lshl_add_u64 v[224:225], v[244:245], 0, s[12:13]
	s_mov_b32 m0, s1
	v_lshl_add_u64 v[246:247], s[8:9], 0, v[148:149]
	v_readfirstlane_b32 s1, v179
	ds_read_b128 v[174:177], v161
	ds_read_b128 v[196:199], v161 offset:1024
	ds_read_b128 v[200:203], v160
	ds_read_b128 v[204:207], v160 offset:1024
	ds_read_b128 v[208:211], v159
	ds_read_b128 v[212:215], v159 offset:1024
	ds_read_b128 v[216:219], v158
	ds_read_b128 v[220:223], v158 offset:1024
	global_load_lds_dwordx4 v[224:225], off
	v_lshl_add_u64 v[224:225], v[246:247], 0, s[12:13]
	s_mov_b32 m0, s1
	s_nop 0
	global_load_lds_dwordx4 v[224:225], off
	s_waitcnt lgkmcnt(8)
	s_barrier
	s_waitcnt lgkmcnt(0)
	v_mfma_f32_16x16x32_bf16 v[124:127], v[180:183], v[174:177], v[124:127]
	v_mfma_f32_16x16x32_bf16 v[120:123], v[188:191], v[174:177], v[120:123]
	v_mfma_f32_16x16x32_bf16 v[116:119], v[180:183], v[200:203], v[116:119]
	v_mfma_f32_16x16x32_bf16 v[112:115], v[188:191], v[200:203], v[112:115]
	v_mfma_f32_16x16x32_bf16 v[108:111], v[180:183], v[208:211], v[108:111]
	v_mfma_f32_16x16x32_bf16 v[104:107], v[188:191], v[208:211], v[104:107]
	v_mfma_f32_16x16x32_bf16 v[100:103], v[180:183], v[216:219], v[100:103]
	v_mfma_f32_16x16x32_bf16 v[96:99], v[188:191], v[216:219], v[96:99]
	v_mfma_f32_16x16x32_bf16 v[124:127], v[184:187], v[196:199], v[124:127]
	v_mfma_f32_16x16x32_bf16 v[120:123], v[192:195], v[196:199], v[120:123]
	v_mfma_f32_16x16x32_bf16 v[116:119], v[184:187], v[204:207], v[116:119]
	v_mfma_f32_16x16x32_bf16 v[112:115], v[192:195], v[204:207], v[112:115]
	v_mfma_f32_16x16x32_bf16 v[108:111], v[184:187], v[212:215], v[108:111]
	v_mfma_f32_16x16x32_bf16 v[104:107], v[192:195], v[212:215], v[104:107]
	v_mfma_f32_16x16x32_bf16 v[100:103], v[184:187], v[220:223], v[100:103]
	v_mfma_f32_16x16x32_bf16 v[96:99], v[192:195], v[220:223], v[96:99]
	s_barrier
	v_lshl_add_u64 v[248:249], s[8:9], 0, v[142:143]
	v_readfirstlane_b32 s1, v153
	v_add_u32_e32 v173, 0x2000, v153
	v_lshl_add_u64 v[240:241], v[248:249], 0, s[14:15]
	s_mov_b32 m0, s1
	v_lshl_add_u64 v[250:251], s[8:9], 0, v[144:145]
	v_readfirstlane_b32 s1, v173
	ds_read_b128 v[224:227], v168
	ds_read_b128 v[228:231], v168 offset:1024
	ds_read_b128 v[232:235], v168 offset:2048
	ds_read_b128 v[236:239], v168 offset:3072
	global_load_lds_dwordx4 v[240:241], off
	v_lshl_add_u64 v[240:241], v[250:251], 0, s[14:15]
	s_mov_b32 m0, s1
	s_nop 0
	global_load_lds_dwordx4 v[240:241], off
	s_barrier
	s_waitcnt lgkmcnt(0)
	v_mfma_f32_16x16x32_bf16 v[92:95], v[224:227], v[174:177], v[92:95]
	v_mfma_f32_16x16x32_bf16 v[88:91], v[232:235], v[174:177], v[88:91]
	v_mfma_f32_16x16x32_bf16 v[84:87], v[224:227], v[200:203], v[84:87]
	v_mfma_f32_16x16x32_bf16 v[80:83], v[232:235], v[200:203], v[80:83]
	v_mfma_f32_16x16x32_bf16 v[76:79], v[224:227], v[208:211], v[76:79]
	v_mfma_f32_16x16x32_bf16 v[72:75], v[232:235], v[208:211], v[72:75]
	v_mfma_f32_16x16x32_bf16 v[68:71], v[224:227], v[216:219], v[68:71]
	v_mfma_f32_16x16x32_bf16 v[64:67], v[232:235], v[216:219], v[64:67]
	v_mfma_f32_16x16x32_bf16 v[92:95], v[228:231], v[196:199], v[92:95]
	v_mfma_f32_16x16x32_bf16 v[88:91], v[236:239], v[196:199], v[88:91]
	v_mfma_f32_16x16x32_bf16 v[84:87], v[228:231], v[204:207], v[84:87]
	v_mfma_f32_16x16x32_bf16 v[80:83], v[236:239], v[204:207], v[80:83]
	v_mfma_f32_16x16x32_bf16 v[76:79], v[228:231], v[212:215], v[76:79]
	v_mfma_f32_16x16x32_bf16 v[72:75], v[236:239], v[212:215], v[72:75]
	v_mfma_f32_16x16x32_bf16 v[68:71], v[228:231], v[220:223], v[68:71]
	v_mfma_f32_16x16x32_bf16 v[64:67], v[236:239], v[220:223], v[64:67]
	v_readfirstlane_b32 s1, v152
	v_lshl_add_u64 v[174:175], v[244:245], 0, s[16:17]
	s_mov_b32 m0, s1
	s_barrier
	ds_read_b128 v[196:199], v161 offset:16384
	ds_read_b128 v[200:203], v161 offset:17408
	ds_read_b128 v[204:207], v160 offset:16384
	ds_read_b128 v[208:211], v160 offset:17408
	ds_read_b128 v[212:215], v159 offset:16384
	ds_read_b128 v[216:219], v159 offset:17408
	ds_read_b128 v[220:223], v158 offset:16384
	ds_read_b128 v[240:243], v158 offset:17408
	global_load_lds_dwordx4 v[174:175], off
	v_add_u32_e32 v174, 0x2000, v152
	v_lshl_add_u64 v[176:177], v[246:247], 0, s[16:17]
	v_readfirstlane_b32 s1, v174
	s_mov_b32 m0, s1
	s_nop 0
	global_load_lds_dwordx4 v[176:177], off
	s_barrier
	s_waitcnt lgkmcnt(0)
	v_mfma_f32_16x16x32_bf16 v[60:63], v[180:183], v[196:199], v[60:63]
	v_mfma_f32_16x16x32_bf16 v[56:59], v[188:191], v[196:199], v[56:59]
	v_mfma_f32_16x16x32_bf16 v[52:55], v[180:183], v[204:207], v[52:55]
	v_mfma_f32_16x16x32_bf16 v[48:51], v[188:191], v[204:207], v[48:51]
	v_mfma_f32_16x16x32_bf16 v[44:47], v[180:183], v[212:215], v[44:47]
	v_mfma_f32_16x16x32_bf16 v[40:43], v[188:191], v[212:215], v[40:43]
	v_mfma_f32_16x16x32_bf16 v[36:39], v[180:183], v[220:223], v[36:39]
	v_mfma_f32_16x16x32_bf16 v[32:35], v[188:191], v[220:223], v[32:35]
	v_mfma_f32_16x16x32_bf16 v[60:63], v[184:187], v[200:203], v[60:63]
	v_mfma_f32_16x16x32_bf16 v[56:59], v[192:195], v[200:203], v[56:59]
	v_mfma_f32_16x16x32_bf16 v[52:55], v[184:187], v[208:211], v[52:55]
	v_mfma_f32_16x16x32_bf16 v[48:51], v[192:195], v[208:211], v[48:51]
	v_mfma_f32_16x16x32_bf16 v[44:47], v[184:187], v[216:219], v[44:47]
	v_mfma_f32_16x16x32_bf16 v[40:43], v[192:195], v[216:219], v[40:43]
	v_mfma_f32_16x16x32_bf16 v[36:39], v[184:187], v[240:243], v[36:39]
	v_mfma_f32_16x16x32_bf16 v[32:35], v[192:195], v[240:243], v[32:35]
	s_barrier
	v_readfirstlane_b32 s1, v151
	v_add_u32_e32 v175, 0x2000, v151
	v_lshl_add_u64 v[176:177], v[248:249], 0, s[18:19]
	s_mov_b32 m0, s1
	v_readfirstlane_b32 s1, v175
	global_load_lds_dwordx4 v[176:177], off
	v_lshl_add_u64 v[176:177], v[250:251], 0, s[18:19]
	s_mov_b32 m0, s1
	s_nop 0
	global_load_lds_dwordx4 v[176:177], off
	s_waitcnt vmcnt(6)
	s_barrier
	v_mfma_f32_16x16x32_bf16 v[28:31], v[224:227], v[196:199], v[28:31]
	v_mfma_f32_16x16x32_bf16 v[24:27], v[232:235], v[196:199], v[24:27]
	v_mfma_f32_16x16x32_bf16 v[20:23], v[224:227], v[204:207], v[20:23]
	v_mfma_f32_16x16x32_bf16 v[16:19], v[232:235], v[204:207], v[16:19]
	v_mfma_f32_16x16x32_bf16 v[12:15], v[224:227], v[212:215], v[12:15]
	v_mfma_f32_16x16x32_bf16 v[8:11], v[232:235], v[212:215], v[8:11]
	v_mfma_f32_16x16x32_bf16 v[4:7], v[224:227], v[220:223], v[4:7]
	v_mfma_f32_16x16x32_bf16 v[0:3], v[232:235], v[220:223], v[0:3]
	v_mfma_f32_16x16x32_bf16 v[28:31], v[228:231], v[200:203], v[28:31]
	v_mfma_f32_16x16x32_bf16 v[24:27], v[236:239], v[200:203], v[24:27]
	v_mfma_f32_16x16x32_bf16 v[20:23], v[228:231], v[208:211], v[20:23]
	v_mfma_f32_16x16x32_bf16 v[16:19], v[236:239], v[208:211], v[16:19]
	v_mfma_f32_16x16x32_bf16 v[12:15], v[228:231], v[216:219], v[12:15]
	v_mfma_f32_16x16x32_bf16 v[8:11], v[236:239], v[216:219], v[8:11]
	v_mfma_f32_16x16x32_bf16 v[4:7], v[228:231], v[240:243], v[4:7]
	v_mfma_f32_16x16x32_bf16 v[0:3], v[236:239], v[240:243], v[0:3]
	s_barrier
	ds_read_b128 v[180:183], v163
	ds_read_b128 v[184:187], v163 offset:1024
	ds_read_b128 v[188:191], v163 offset:2048
	ds_read_b128 v[192:195], v163 offset:3072
	v_add_u32_e32 v176, 0x4000, v152
	v_add_u32_e32 v177, 0x6000, v152
	v_readfirstlane_b32 s1, v176
	v_lshl_add_u64 v[228:229], v[244:245], 0, s[20:21]
	s_mov_b32 m0, s1
	v_readfirstlane_b32 s1, v177
	ds_read_b128 v[196:199], v161 offset:32768
	ds_read_b128 v[200:203], v161 offset:33792
	ds_read_b128 v[204:207], v160 offset:32768
	ds_read_b128 v[208:211], v160 offset:33792
	ds_read_b128 v[212:215], v159 offset:32768
	ds_read_b128 v[216:219], v159 offset:33792
	ds_read_b128 v[220:223], v158 offset:32768
	ds_read_b128 v[224:227], v158 offset:33792
	global_load_lds_dwordx4 v[228:229], off
	v_lshl_add_u64 v[228:229], v[246:247], 0, s[20:21]
	s_mov_b32 m0, s1
	s_nop 0
	global_load_lds_dwordx4 v[228:229], off
	s_waitcnt lgkmcnt(8)
	s_barrier
	s_waitcnt lgkmcnt(0)
	v_mfma_f32_16x16x32_bf16 v[124:127], v[180:183], v[196:199], v[124:127]
	v_mfma_f32_16x16x32_bf16 v[120:123], v[188:191], v[196:199], v[120:123]
	v_mfma_f32_16x16x32_bf16 v[116:119], v[180:183], v[204:207], v[116:119]
	v_mfma_f32_16x16x32_bf16 v[112:115], v[188:191], v[204:207], v[112:115]
	v_mfma_f32_16x16x32_bf16 v[108:111], v[180:183], v[212:215], v[108:111]
	v_mfma_f32_16x16x32_bf16 v[104:107], v[188:191], v[212:215], v[104:107]
	v_mfma_f32_16x16x32_bf16 v[100:103], v[180:183], v[220:223], v[100:103]
	v_mfma_f32_16x16x32_bf16 v[96:99], v[188:191], v[220:223], v[96:99]
	v_mfma_f32_16x16x32_bf16 v[124:127], v[184:187], v[200:203], v[124:127]
	v_mfma_f32_16x16x32_bf16 v[120:123], v[192:195], v[200:203], v[120:123]
	v_mfma_f32_16x16x32_bf16 v[116:119], v[184:187], v[208:211], v[116:119]
	v_mfma_f32_16x16x32_bf16 v[112:115], v[192:195], v[208:211], v[112:115]
	v_mfma_f32_16x16x32_bf16 v[108:111], v[184:187], v[216:219], v[108:111]
	v_mfma_f32_16x16x32_bf16 v[104:107], v[192:195], v[216:219], v[104:107]
	v_mfma_f32_16x16x32_bf16 v[100:103], v[184:187], v[224:227], v[100:103]
	v_mfma_f32_16x16x32_bf16 v[96:99], v[192:195], v[224:227], v[96:99]
	s_barrier
	v_readfirstlane_b32 s1, v167
	v_add_u32_e32 v254, 0x2000, v167
	v_lshl_add_u64 v[252:253], v[248:249], 0, s[24:25]
	s_mov_b32 m0, s1
	v_readfirstlane_b32 s1, v254
	ds_read_b128 v[228:231], v162
	ds_read_b128 v[232:235], v162 offset:1024
	ds_read_b128 v[236:239], v162 offset:2048
	ds_read_b128 v[240:243], v162 offset:3072
	global_load_lds_dwordx4 v[252:253], off
	v_lshl_add_u64 v[252:253], v[250:251], 0, s[24:25]
	s_mov_b32 m0, s1
	s_nop 0
	global_load_lds_dwordx4 v[252:253], off
	s_barrier
	s_waitcnt lgkmcnt(0)
	v_mfma_f32_16x16x32_bf16 v[92:95], v[228:231], v[196:199], v[92:95]
	v_mfma_f32_16x16x32_bf16 v[88:91], v[236:239], v[196:199], v[88:91]
	v_mfma_f32_16x16x32_bf16 v[84:87], v[228:231], v[204:207], v[84:87]
	v_mfma_f32_16x16x32_bf16 v[80:83], v[236:239], v[204:207], v[80:83]
	v_mfma_f32_16x16x32_bf16 v[76:79], v[228:231], v[212:215], v[76:79]
	v_mfma_f32_16x16x32_bf16 v[72:75], v[236:239], v[212:215], v[72:75]
	v_mfma_f32_16x16x32_bf16 v[68:71], v[228:231], v[220:223], v[68:71]
	v_mfma_f32_16x16x32_bf16 v[64:67], v[236:239], v[220:223], v[64:67]
	v_mfma_f32_16x16x32_bf16 v[92:95], v[232:235], v[200:203], v[92:95]
	v_mfma_f32_16x16x32_bf16 v[88:91], v[240:243], v[200:203], v[88:91]
	v_mfma_f32_16x16x32_bf16 v[84:87], v[232:235], v[208:211], v[84:87]
	v_mfma_f32_16x16x32_bf16 v[80:83], v[240:243], v[208:211], v[80:83]
	v_mfma_f32_16x16x32_bf16 v[76:79], v[232:235], v[216:219], v[76:79]
	v_mfma_f32_16x16x32_bf16 v[72:75], v[240:243], v[216:219], v[72:75]
	v_mfma_f32_16x16x32_bf16 v[68:71], v[232:235], v[224:227], v[68:71]
	v_mfma_f32_16x16x32_bf16 v[64:67], v[240:243], v[224:227], v[64:67]
	v_readfirstlane_b32 s1, v169
	v_lshl_add_u64 v[244:245], v[244:245], 0, s[26:27]
	s_mov_b32 m0, s1
	v_readfirstlane_b32 s1, v170
	s_barrier
	ds_read_b128 v[196:199], v161 offset:49152
	ds_read_b128 v[200:203], v161 offset:50176
	ds_read_b128 v[204:207], v160 offset:49152
	ds_read_b128 v[208:211], v160 offset:50176
	ds_read_b128 v[212:215], v159 offset:49152
	ds_read_b128 v[216:219], v159 offset:50176
	ds_read_b128 v[220:223], v158 offset:49152
	ds_read_b128 v[224:227], v158 offset:50176
	global_load_lds_dwordx4 v[244:245], off
	v_lshl_add_u64 v[244:245], v[246:247], 0, s[26:27]
	s_mov_b32 m0, s1
	s_nop 0
	global_load_lds_dwordx4 v[244:245], off
	s_barrier
	s_waitcnt lgkmcnt(0)
	v_mfma_f32_16x16x32_bf16 v[60:63], v[180:183], v[196:199], v[60:63]
	v_mfma_f32_16x16x32_bf16 v[56:59], v[188:191], v[196:199], v[56:59]
	v_mfma_f32_16x16x32_bf16 v[52:55], v[180:183], v[204:207], v[52:55]
	v_mfma_f32_16x16x32_bf16 v[48:51], v[188:191], v[204:207], v[48:51]
	v_mfma_f32_16x16x32_bf16 v[44:47], v[180:183], v[212:215], v[44:47]
	v_mfma_f32_16x16x32_bf16 v[40:43], v[188:191], v[212:215], v[40:43]
	v_mfma_f32_16x16x32_bf16 v[36:39], v[180:183], v[220:223], v[36:39]
	v_mfma_f32_16x16x32_bf16 v[32:35], v[188:191], v[220:223], v[32:35]
	v_mfma_f32_16x16x32_bf16 v[60:63], v[184:187], v[200:203], v[60:63]
	v_mfma_f32_16x16x32_bf16 v[56:59], v[192:195], v[200:203], v[56:59]
	v_mfma_f32_16x16x32_bf16 v[52:55], v[184:187], v[208:211], v[52:55]
	v_mfma_f32_16x16x32_bf16 v[48:51], v[192:195], v[208:211], v[48:51]
	v_mfma_f32_16x16x32_bf16 v[44:47], v[184:187], v[216:219], v[44:47]
	v_mfma_f32_16x16x32_bf16 v[40:43], v[192:195], v[216:219], v[40:43]
	v_mfma_f32_16x16x32_bf16 v[36:39], v[184:187], v[224:227], v[36:39]
	v_mfma_f32_16x16x32_bf16 v[32:35], v[192:195], v[224:227], v[32:35]
	s_barrier
	v_readfirstlane_b32 s1, v171
	v_add_u32_e32 v182, 0x2000, v171
	v_lshl_add_u64 v[180:181], v[248:249], 0, s[28:29]
	s_mov_b32 m0, s1
	v_readfirstlane_b32 s1, v182
	global_load_lds_dwordx4 v[180:181], off
	v_lshl_add_u64 v[180:181], v[250:251], 0, s[28:29]
	s_mov_b32 m0, s1
	s_nop 0
	global_load_lds_dwordx4 v[180:181], off
	s_waitcnt vmcnt(6)
	s_barrier
	v_mfma_f32_16x16x32_bf16 v[28:31], v[228:231], v[196:199], v[28:31]
	v_mfma_f32_16x16x32_bf16 v[24:27], v[236:239], v[196:199], v[24:27]
	v_mfma_f32_16x16x32_bf16 v[20:23], v[228:231], v[204:207], v[20:23]
	v_mfma_f32_16x16x32_bf16 v[16:19], v[236:239], v[204:207], v[16:19]
	v_mfma_f32_16x16x32_bf16 v[12:15], v[228:231], v[212:215], v[12:15]
	v_mfma_f32_16x16x32_bf16 v[8:11], v[236:239], v[212:215], v[8:11]
	v_mfma_f32_16x16x32_bf16 v[4:7], v[228:231], v[220:223], v[4:7]
	v_mfma_f32_16x16x32_bf16 v[0:3], v[236:239], v[220:223], v[0:3]
	v_mfma_f32_16x16x32_bf16 v[28:31], v[232:235], v[200:203], v[28:31]
	v_mfma_f32_16x16x32_bf16 v[24:27], v[240:243], v[200:203], v[24:27]
	v_mfma_f32_16x16x32_bf16 v[20:23], v[232:235], v[208:211], v[20:23]
	v_mfma_f32_16x16x32_bf16 v[16:19], v[240:243], v[208:211], v[16:19]
	v_mfma_f32_16x16x32_bf16 v[12:15], v[232:235], v[216:219], v[12:15]
	v_mfma_f32_16x16x32_bf16 v[8:11], v[240:243], v[216:219], v[8:11]
	v_mfma_f32_16x16x32_bf16 v[4:7], v[232:235], v[224:227], v[4:7]
	v_mfma_f32_16x16x32_bf16 v[0:3], v[240:243], v[224:227], v[0:3]
	s_add_i32 s0, s0, 2
	v_lshl_add_u64 v[142:143], v[142:143], 0, s[30:31]
	v_lshl_add_u64 v[144:145], v[144:145], 0, s[30:31]
	v_lshl_add_u64 v[146:147], v[146:147], 0, s[30:31]
	s_cmp_lt_u32 s0, 12
	v_lshl_add_u64 v[148:149], v[148:149], 0, s[30:31]
	s_barrier
	s_cbranch_scc1 .LBB0_1661
	s_or_b32 s0, s36, 0x80
	s_ashr_i32 s1, s0, 31
	s_lshl_b64 s[0:1], s[0:1], 11
	s_add_u32 s0, s39, s0
	s_addc_u32 s1, s46, s1
	v_lshl_add_u64 v[170:171], s[0:1], 0, v[130:131]
	v_lshl_add_u64 v[138:139], v[138:139], 1, v[170:171]
	v_readfirstlane_b32 s2, v178
	v_lshl_add_u64 v[138:139], v[138:139], 0, s[34:35]
	s_mov_b32 m0, s2
	ds_read_b128 v[142:145], v172
	ds_read_b128 v[146:149], v172 offset:1024
	ds_read_b128 v[180:183], v172 offset:2048
	ds_read_b128 v[184:187], v172 offset:3072
	ds_read_b128 v[188:191], v161
	ds_read_b128 v[192:195], v161 offset:1024
	ds_read_b128 v[196:199], v160
	ds_read_b128 v[200:203], v160 offset:1024
	ds_read_b128 v[204:207], v159
	ds_read_b128 v[208:211], v159 offset:1024
	ds_read_b128 v[212:215], v158
	ds_read_b128 v[216:219], v158 offset:1024
	global_load_lds_dwordx4 v[138:139], off
	v_lshl_add_u64 v[138:139], s[0:1], 0, v[134:135]
	v_lshl_add_u64 v[138:139], v[140:141], 1, v[138:139]
	v_readfirstlane_b32 s0, v179
	v_lshl_add_u64 v[138:139], v[138:139], 0, s[34:35]
	s_mov_b32 m0, s0
	v_readlane_b32 s0, v255, 11
	global_load_lds_dwordx4 v[138:139], off
	s_add_i32 s70, s70, s0
	s_barrier
	s_waitcnt lgkmcnt(0)
	s_cmpk_gt_i32 s70, 0x7f
	s_cselect_b64 s[58:59], -1, 0
	s_waitcnt lgkmcnt(0)
	v_mfma_f32_16x16x32_bf16 v[124:127], v[142:145], v[188:191], v[124:127]
	v_mfma_f32_16x16x32_bf16 v[120:123], v[180:183], v[188:191], v[120:123]
	v_mfma_f32_16x16x32_bf16 v[116:119], v[142:145], v[196:199], v[116:119]
	v_mfma_f32_16x16x32_bf16 v[112:115], v[180:183], v[196:199], v[112:115]
	v_mfma_f32_16x16x32_bf16 v[108:111], v[142:145], v[204:207], v[108:111]
	v_mfma_f32_16x16x32_bf16 v[104:107], v[180:183], v[204:207], v[104:107]
	v_mfma_f32_16x16x32_bf16 v[100:103], v[142:145], v[212:215], v[100:103]
	v_mfma_f32_16x16x32_bf16 v[96:99], v[180:183], v[212:215], v[96:99]
	v_mfma_f32_16x16x32_bf16 v[124:127], v[146:149], v[192:195], v[124:127]
	v_mfma_f32_16x16x32_bf16 v[120:123], v[184:187], v[192:195], v[120:123]
	v_mfma_f32_16x16x32_bf16 v[116:119], v[146:149], v[200:203], v[116:119]
	v_mfma_f32_16x16x32_bf16 v[112:115], v[184:187], v[200:203], v[112:115]
	v_mfma_f32_16x16x32_bf16 v[108:111], v[146:149], v[208:211], v[108:111]
	v_mfma_f32_16x16x32_bf16 v[104:107], v[184:187], v[208:211], v[104:107]
	v_mfma_f32_16x16x32_bf16 v[100:103], v[146:149], v[216:219], v[100:103]
	v_mfma_f32_16x16x32_bf16 v[96:99], v[184:187], v[216:219], v[96:99]
	s_barrier
	ds_read_b128 v[138:141], v168
	ds_read_b128 v[220:223], v168 offset:1024
	ds_read_b128 v[224:227], v168 offset:2048
	ds_read_b128 v[168:171], v168 offset:3072
	s_barrier
	s_waitcnt lgkmcnt(0)
	v_mfma_f32_16x16x32_bf16 v[92:95], v[138:141], v[188:191], v[92:95]
	v_mfma_f32_16x16x32_bf16 v[88:91], v[224:227], v[188:191], v[88:91]
	v_mfma_f32_16x16x32_bf16 v[84:87], v[138:141], v[196:199], v[84:87]
	v_mfma_f32_16x16x32_bf16 v[80:83], v[224:227], v[196:199], v[80:83]
	v_mfma_f32_16x16x32_bf16 v[76:79], v[138:141], v[204:207], v[76:79]
	v_mfma_f32_16x16x32_bf16 v[72:75], v[224:227], v[204:207], v[72:75]
	v_mfma_f32_16x16x32_bf16 v[68:71], v[138:141], v[212:215], v[68:71]
	v_mfma_f32_16x16x32_bf16 v[64:67], v[224:227], v[212:215], v[64:67]
	v_mfma_f32_16x16x32_bf16 v[92:95], v[220:223], v[192:195], v[92:95]
	v_mfma_f32_16x16x32_bf16 v[88:91], v[168:171], v[192:195], v[88:91]
	v_mfma_f32_16x16x32_bf16 v[84:87], v[220:223], v[200:203], v[84:87]
	v_mfma_f32_16x16x32_bf16 v[80:83], v[168:171], v[200:203], v[80:83]
	v_mfma_f32_16x16x32_bf16 v[76:79], v[220:223], v[208:211], v[76:79]
	v_mfma_f32_16x16x32_bf16 v[72:75], v[168:171], v[208:211], v[72:75]
	v_mfma_f32_16x16x32_bf16 v[68:71], v[220:223], v[216:219], v[68:71]
	v_mfma_f32_16x16x32_bf16 v[64:67], v[168:171], v[216:219], v[64:67]
	s_barrier
	ds_read_b128 v[188:191], v161 offset:16384
	ds_read_b128 v[192:195], v161 offset:17408
	ds_read_b128 v[196:199], v160 offset:16384
	ds_read_b128 v[200:203], v160 offset:17408
	ds_read_b128 v[204:207], v159 offset:16384
	ds_read_b128 v[208:211], v159 offset:17408
	ds_read_b128 v[212:215], v158 offset:16384
	ds_read_b128 v[216:219], v158 offset:17408
	s_waitcnt vmcnt(4)
	s_barrier
	s_waitcnt lgkmcnt(0)
	v_mfma_f32_16x16x32_bf16 v[60:63], v[142:145], v[188:191], v[60:63]
	v_mfma_f32_16x16x32_bf16 v[56:59], v[180:183], v[188:191], v[56:59]
	v_mfma_f32_16x16x32_bf16 v[52:55], v[142:145], v[196:199], v[52:55]
	v_mfma_f32_16x16x32_bf16 v[48:51], v[180:183], v[196:199], v[48:51]
	v_mfma_f32_16x16x32_bf16 v[44:47], v[142:145], v[204:207], v[44:47]
	v_mfma_f32_16x16x32_bf16 v[40:43], v[180:183], v[204:207], v[40:43]
	v_mfma_f32_16x16x32_bf16 v[36:39], v[142:145], v[212:215], v[36:39]
	v_mfma_f32_16x16x32_bf16 v[32:35], v[180:183], v[212:215], v[32:35]
	v_mfma_f32_16x16x32_bf16 v[60:63], v[146:149], v[192:195], v[60:63]
	v_mfma_f32_16x16x32_bf16 v[56:59], v[184:187], v[192:195], v[56:59]
	v_mfma_f32_16x16x32_bf16 v[52:55], v[146:149], v[200:203], v[52:55]
	v_mfma_f32_16x16x32_bf16 v[48:51], v[184:187], v[200:203], v[48:51]
	v_mfma_f32_16x16x32_bf16 v[44:47], v[146:149], v[208:211], v[44:47]
	v_mfma_f32_16x16x32_bf16 v[40:43], v[184:187], v[208:211], v[40:43]
	v_mfma_f32_16x16x32_bf16 v[36:39], v[146:149], v[216:219], v[36:39]
	v_mfma_f32_16x16x32_bf16 v[32:35], v[184:187], v[216:219], v[32:35]
	v_mfma_f32_16x16x32_bf16 v[28:31], v[138:141], v[188:191], v[28:31]
	v_mfma_f32_16x16x32_bf16 v[24:27], v[224:227], v[188:191], v[24:27]
	v_mfma_f32_16x16x32_bf16 v[20:23], v[138:141], v[196:199], v[20:23]
	v_mfma_f32_16x16x32_bf16 v[16:19], v[224:227], v[196:199], v[16:19]
	v_mfma_f32_16x16x32_bf16 v[12:15], v[138:141], v[204:207], v[12:15]
	v_mfma_f32_16x16x32_bf16 v[8:11], v[224:227], v[204:207], v[8:11]
	v_mfma_f32_16x16x32_bf16 v[4:7], v[138:141], v[212:215], v[4:7]
	v_mfma_f32_16x16x32_bf16 v[0:3], v[224:227], v[212:215], v[0:3]
	v_mfma_f32_16x16x32_bf16 v[28:31], v[220:223], v[192:195], v[28:31]
	v_mfma_f32_16x16x32_bf16 v[24:27], v[168:171], v[192:195], v[24:27]
	v_mfma_f32_16x16x32_bf16 v[20:23], v[220:223], v[200:203], v[20:23]
	v_mfma_f32_16x16x32_bf16 v[16:19], v[168:171], v[200:203], v[16:19]
	v_mfma_f32_16x16x32_bf16 v[12:15], v[220:223], v[208:211], v[12:15]
	v_mfma_f32_16x16x32_bf16 v[8:11], v[168:171], v[208:211], v[8:11]
	v_mfma_f32_16x16x32_bf16 v[4:7], v[220:223], v[216:219], v[4:7]
	v_mfma_f32_16x16x32_bf16 v[0:3], v[168:171], v[216:219], v[0:3]
	s_barrier
	ds_read_b128 v[138:141], v163
	ds_read_b128 v[142:145], v163 offset:1024
	ds_read_b128 v[146:149], v163 offset:2048
	ds_read_b128 v[168:171], v163 offset:3072
	ds_read_b128 v[178:181], v161 offset:32768
	ds_read_b128 v[182:185], v161 offset:33792
	ds_read_b128 v[186:189], v160 offset:32768
	ds_read_b128 v[190:193], v160 offset:33792
	ds_read_b128 v[194:197], v159 offset:32768
	ds_read_b128 v[198:201], v159 offset:33792
	ds_read_b128 v[202:205], v158 offset:32768
	ds_read_b128 v[206:209], v158 offset:33792
	s_waitcnt vmcnt(2)
	s_barrier
	s_waitcnt lgkmcnt(0)
	v_mfma_f32_16x16x32_bf16 v[124:127], v[138:141], v[178:181], v[124:127]
	v_mfma_f32_16x16x32_bf16 v[120:123], v[146:149], v[178:181], v[120:123]
	v_mfma_f32_16x16x32_bf16 v[116:119], v[138:141], v[186:189], v[116:119]
	v_mfma_f32_16x16x32_bf16 v[112:115], v[146:149], v[186:189], v[112:115]
	v_mfma_f32_16x16x32_bf16 v[108:111], v[138:141], v[194:197], v[108:111]
	v_mfma_f32_16x16x32_bf16 v[104:107], v[146:149], v[194:197], v[104:107]
	v_mfma_f32_16x16x32_bf16 v[100:103], v[138:141], v[202:205], v[100:103]
	v_mfma_f32_16x16x32_bf16 v[96:99], v[146:149], v[202:205], v[96:99]
	v_mfma_f32_16x16x32_bf16 v[124:127], v[142:145], v[182:185], v[124:127]
	v_mfma_f32_16x16x32_bf16 v[120:123], v[168:171], v[182:185], v[120:123]
	v_mfma_f32_16x16x32_bf16 v[116:119], v[142:145], v[190:193], v[116:119]
	v_mfma_f32_16x16x32_bf16 v[112:115], v[168:171], v[190:193], v[112:115]
	v_mfma_f32_16x16x32_bf16 v[108:111], v[142:145], v[198:201], v[108:111]
	v_mfma_f32_16x16x32_bf16 v[104:107], v[168:171], v[198:201], v[104:107]
	v_mfma_f32_16x16x32_bf16 v[100:103], v[142:145], v[206:209], v[100:103]
	v_mfma_f32_16x16x32_bf16 v[96:99], v[168:171], v[206:209], v[96:99]
	s_barrier
	ds_read_b128 v[210:213], v162
	ds_read_b128 v[214:217], v162 offset:1024
	ds_read_b128 v[218:221], v162 offset:2048
	ds_read_b128 v[222:225], v162 offset:3072
	s_waitcnt vmcnt(0)
	s_barrier
	s_waitcnt lgkmcnt(0)
	v_mfma_f32_16x16x32_bf16 v[92:95], v[210:213], v[178:181], v[92:95]
	v_mfma_f32_16x16x32_bf16 v[88:91], v[218:221], v[178:181], v[88:91]
	v_mfma_f32_16x16x32_bf16 v[84:87], v[210:213], v[186:189], v[84:87]
	v_mfma_f32_16x16x32_bf16 v[80:83], v[218:221], v[186:189], v[80:83]
	v_mfma_f32_16x16x32_bf16 v[76:79], v[210:213], v[194:197], v[76:79]
	v_mfma_f32_16x16x32_bf16 v[72:75], v[218:221], v[194:197], v[72:75]
	v_mfma_f32_16x16x32_bf16 v[68:71], v[210:213], v[202:205], v[68:71]
	v_mfma_f32_16x16x32_bf16 v[64:67], v[218:221], v[202:205], v[64:67]
	v_mfma_f32_16x16x32_bf16 v[92:95], v[214:217], v[182:185], v[92:95]
	v_mfma_f32_16x16x32_bf16 v[88:91], v[222:225], v[182:185], v[88:91]
	v_mfma_f32_16x16x32_bf16 v[84:87], v[214:217], v[190:193], v[84:87]
	v_mfma_f32_16x16x32_bf16 v[80:83], v[222:225], v[190:193], v[80:83]
	v_mfma_f32_16x16x32_bf16 v[76:79], v[214:217], v[198:201], v[76:79]
	v_mfma_f32_16x16x32_bf16 v[72:75], v[222:225], v[198:201], v[72:75]
	v_mfma_f32_16x16x32_bf16 v[68:71], v[214:217], v[206:209], v[68:71]
	v_mfma_f32_16x16x32_bf16 v[64:67], v[222:225], v[206:209], v[64:67]
	s_barrier
	ds_read_b128 v[178:181], v161 offset:49152
	ds_read_b128 v[182:185], v161 offset:50176
	ds_read_b128 v[186:189], v160 offset:49152
	ds_read_b128 v[160:163], v160 offset:50176
	ds_read_b128 v[190:193], v159 offset:49152
	ds_read_b128 v[194:197], v159 offset:50176
	ds_read_b128 v[198:201], v158 offset:49152
	ds_read_b128 v[202:205], v158 offset:50176
	s_barrier
	s_waitcnt lgkmcnt(0)
	v_mfma_f32_16x16x32_bf16 v[60:63], v[138:141], v[178:181], v[60:63]
	v_mfma_f32_16x16x32_bf16 v[56:59], v[146:149], v[178:181], v[56:59]
	v_mfma_f32_16x16x32_bf16 v[52:55], v[138:141], v[186:189], v[52:55]
	v_mfma_f32_16x16x32_bf16 v[48:51], v[146:149], v[186:189], v[48:51]
	v_mfma_f32_16x16x32_bf16 v[44:47], v[138:141], v[190:193], v[44:47]
	v_mfma_f32_16x16x32_bf16 v[40:43], v[146:149], v[190:193], v[40:43]
	v_mfma_f32_16x16x32_bf16 v[36:39], v[138:141], v[198:201], v[36:39]
	v_mfma_f32_16x16x32_bf16 v[32:35], v[146:149], v[198:201], v[32:35]
	v_mfma_f32_16x16x32_bf16 v[60:63], v[142:145], v[182:185], v[60:63]
	v_mfma_f32_16x16x32_bf16 v[56:59], v[168:171], v[182:185], v[56:59]
	v_mfma_f32_16x16x32_bf16 v[52:55], v[142:145], v[160:163], v[52:55]
	v_mfma_f32_16x16x32_bf16 v[48:51], v[168:171], v[160:163], v[48:51]
	v_mfma_f32_16x16x32_bf16 v[44:47], v[142:145], v[194:197], v[44:47]
	v_mfma_f32_16x16x32_bf16 v[40:43], v[168:171], v[194:197], v[40:43]
	v_mfma_f32_16x16x32_bf16 v[36:39], v[142:145], v[202:205], v[36:39]
	v_mfma_f32_16x16x32_bf16 v[32:35], v[168:171], v[202:205], v[32:35]
	v_mfma_f32_16x16x32_bf16 v[28:31], v[210:213], v[178:181], v[28:31]
	v_mfma_f32_16x16x32_bf16 v[24:27], v[218:221], v[178:181], v[24:27]
	v_mfma_f32_16x16x32_bf16 v[20:23], v[210:213], v[186:189], v[20:23]
	v_mfma_f32_16x16x32_bf16 v[16:19], v[218:221], v[186:189], v[16:19]
	v_mfma_f32_16x16x32_bf16 v[12:15], v[210:213], v[190:193], v[12:15]
	v_mfma_f32_16x16x32_bf16 v[8:11], v[218:221], v[190:193], v[8:11]
	v_mfma_f32_16x16x32_bf16 v[4:7], v[210:213], v[198:201], v[4:7]
	v_mfma_f32_16x16x32_bf16 v[0:3], v[218:221], v[198:201], v[0:3]
	v_mfma_f32_16x16x32_bf16 v[28:31], v[214:217], v[182:185], v[28:31]
	v_mfma_f32_16x16x32_bf16 v[24:27], v[222:225], v[182:185], v[24:27]
	v_mfma_f32_16x16x32_bf16 v[20:23], v[214:217], v[160:163], v[20:23]
	v_mfma_f32_16x16x32_bf16 v[16:19], v[222:225], v[160:163], v[16:19]
	v_mfma_f32_16x16x32_bf16 v[12:15], v[214:217], v[194:197], v[12:15]
	v_mfma_f32_16x16x32_bf16 v[8:11], v[222:225], v[194:197], v[8:11]
	v_mfma_f32_16x16x32_bf16 v[4:7], v[214:217], v[202:205], v[4:7]
	v_mfma_f32_16x16x32_bf16 v[0:3], v[222:225], v[202:205], v[0:3]
	s_and_b64 vcc, exec, s[58:59]
	s_barrier
	s_cbranch_vccnz .LBB0_1664
	s_lshr_b32 s0, s70, 2
	s_and_b32 s1, s70, 3
	s_add_i32 s0, s0, s56
	s_or_b32 s1, s1, s53
	s_lshl_b32 s0, s0, 8
	s_lshl_b32 s1, s1, 19
	s_add_u32 s40, s57, s1
	s_addc_u32 s41, s62, 0
	v_lshl_add_u64 v[138:139], s[40:41], 0, v[130:131]
	v_readfirstlane_b32 s1, v153
	v_lshl_add_u64 v[138:139], v[138:139], 0, v[132:133]
	s_mov_b32 m0, s1
	v_readfirstlane_b32 s1, v173
	global_load_lds_dwordx4 v[138:139], off
	s_mov_b32 m0, s1
	s_ashr_i32 s1, s0, 31
	s_lshl_b64 s[42:43], s[0:1], 11
	v_lshl_add_u64 v[138:139], s[40:41], 0, v[134:135]
	s_add_u32 s42, s39, s42
	v_lshl_add_u64 v[138:139], v[138:139], 0, v[136:137]
	s_addc_u32 s43, s46, s43
	global_load_lds_dwordx4 v[138:139], off
	v_lshl_add_u64 v[138:139], s[42:43], 0, v[130:131]
	v_readfirstlane_b32 s1, v152
	v_lshl_add_u64 v[138:139], v[138:139], 0, v[132:133]
	s_mov_b32 m0, s1
	v_readfirstlane_b32 s1, v174
	global_load_lds_dwordx4 v[138:139], off
	v_lshl_add_u64 v[138:139], s[42:43], 0, v[134:135]
	s_add_u32 s40, s40, 0x40000
	v_lshl_add_u64 v[138:139], v[138:139], 0, v[136:137]
	s_mov_b32 m0, s1
	s_addc_u32 s41, s41, 0
	global_load_lds_dwordx4 v[138:139], off
	v_lshl_add_u64 v[138:139], s[40:41], 0, v[130:131]
	v_readfirstlane_b32 s1, v151
	v_lshl_add_u64 v[138:139], v[138:139], 0, v[132:133]
	s_mov_b32 m0, s1
	v_readfirstlane_b32 s1, v175
	s_bitset1_b32 s0, 7
	global_load_lds_dwordx4 v[138:139], off
	s_mov_b32 m0, s1
	s_ashr_i32 s1, s0, 31
	s_lshl_b64 s[0:1], s[0:1], 11
	s_add_u32 s0, s39, s0
	v_lshl_add_u64 v[138:139], s[40:41], 0, v[134:135]
	s_addc_u32 s1, s46, s1
	v_lshl_add_u64 v[138:139], v[138:139], 0, v[136:137]
	v_lshl_add_u64 v[130:131], s[0:1], 0, v[130:131]
	v_readfirstlane_b32 s2, v176
	global_load_lds_dwordx4 v[138:139], off
	v_lshl_add_u64 v[130:131], v[130:131], 0, v[132:133]
	s_mov_b32 m0, s2
	s_nop 0
	global_load_lds_dwordx4 v[130:131], off
	v_lshl_add_u64 v[130:131], s[0:1], 0, v[134:135]
	v_readfirstlane_b32 s0, v177
	v_lshl_add_u64 v[130:131], v[130:131], 0, v[136:137]
	s_mov_b32 m0, s0
	s_nop 0
	global_load_lds_dwordx4 v[130:131], off

.LBB0_1720:
	ds_read_b128 v[176:179], v173
	ds_read_b128 v[180:183], v173 offset:1024
	ds_read_b128 v[184:187], v173 offset:2048
	ds_read_b128 v[188:191], v173 offset:3072
	v_add_u32_e32 v174, 0xc000, v157
	v_lshl_add_u64 v[240:241], s[6:7], 0, v[142:143]
	v_readfirstlane_b32 s2, v174
	v_add_u32_e32 v175, 0xe000, v157
	v_lshl_add_u64 v[224:225], v[240:241], 0, s[14:15]
	s_mov_b32 m0, s2
	v_lshl_add_u64 v[242:243], s[6:7], 0, v[144:145]
	v_readfirstlane_b32 s2, v175
	ds_read_b128 v[192:195], v155
	ds_read_b128 v[196:199], v155 offset:1024
	ds_read_b128 v[200:203], v154
	ds_read_b128 v[204:207], v154 offset:1024
	ds_read_b128 v[208:211], v153
	ds_read_b128 v[212:215], v153 offset:1024
	ds_read_b128 v[216:219], v152
	ds_read_b128 v[220:223], v152 offset:1024
	global_load_lds_dwordx4 v[224:225], off
	v_lshl_add_u64 v[224:225], v[242:243], 0, s[14:15]
	s_mov_b32 m0, s2
	s_nop 0
	global_load_lds_dwordx4 v[224:225], off
	s_waitcnt lgkmcnt(8)
	s_barrier
	s_waitcnt lgkmcnt(0)
	v_mfma_f32_16x16x32_bf16 v[124:127], v[176:179], v[192:195], v[124:127]
	v_mfma_f32_16x16x32_bf16 v[120:123], v[184:187], v[192:195], v[120:123]
	v_mfma_f32_16x16x32_bf16 v[116:119], v[176:179], v[200:203], v[116:119]
	v_mfma_f32_16x16x32_bf16 v[112:115], v[184:187], v[200:203], v[112:115]
	v_mfma_f32_16x16x32_bf16 v[108:111], v[176:179], v[208:211], v[108:111]
	v_mfma_f32_16x16x32_bf16 v[104:107], v[184:187], v[208:211], v[104:107]
	v_mfma_f32_16x16x32_bf16 v[100:103], v[176:179], v[216:219], v[100:103]
	v_mfma_f32_16x16x32_bf16 v[96:99], v[184:187], v[216:219], v[96:99]
	v_mfma_f32_16x16x32_bf16 v[124:127], v[180:183], v[196:199], v[124:127]
	v_mfma_f32_16x16x32_bf16 v[120:123], v[188:191], v[196:199], v[120:123]
	v_mfma_f32_16x16x32_bf16 v[116:119], v[180:183], v[204:207], v[116:119]
	v_mfma_f32_16x16x32_bf16 v[112:115], v[188:191], v[204:207], v[112:115]
	v_mfma_f32_16x16x32_bf16 v[108:111], v[180:183], v[212:215], v[108:111]
	v_mfma_f32_16x16x32_bf16 v[104:107], v[188:191], v[212:215], v[104:107]
	v_mfma_f32_16x16x32_bf16 v[100:103], v[180:183], v[220:223], v[100:103]
	v_mfma_f32_16x16x32_bf16 v[96:99], v[188:191], v[220:223], v[96:99]
	s_barrier
	v_lshl_add_u64 v[244:245], s[6:7], 0, v[138:139]
	v_readfirstlane_b32 s2, v151
	v_lshl_add_u64 v[246:247], v[244:245], 0, s[16:17]
	s_mov_b32 m0, s2
	v_add_u32_e32 v250, 0x2000, v151
	ds_read_b128 v[224:227], v170
	ds_read_b128 v[228:231], v170 offset:1024
	ds_read_b128 v[232:235], v170 offset:2048
	ds_read_b128 v[236:239], v170 offset:3072
	global_load_lds_dwordx4 v[246:247], off
	v_lshl_add_u64 v[246:247], s[6:7], 0, v[140:141]
	v_readfirstlane_b32 s2, v250
	v_lshl_add_u64 v[248:249], v[246:247], 0, s[16:17]
	s_mov_b32 m0, s2
	s_nop 0
	global_load_lds_dwordx4 v[248:249], off
	s_barrier
	s_waitcnt lgkmcnt(0)
	v_mfma_f32_16x16x32_bf16 v[92:95], v[224:227], v[192:195], v[92:95]
	v_mfma_f32_16x16x32_bf16 v[88:91], v[232:235], v[192:195], v[88:91]
	v_mfma_f32_16x16x32_bf16 v[84:87], v[224:227], v[200:203], v[84:87]
	v_mfma_f32_16x16x32_bf16 v[80:83], v[232:235], v[200:203], v[80:83]
	v_mfma_f32_16x16x32_bf16 v[76:79], v[224:227], v[208:211], v[76:79]
	v_mfma_f32_16x16x32_bf16 v[72:75], v[232:235], v[208:211], v[72:75]
	v_mfma_f32_16x16x32_bf16 v[68:71], v[224:227], v[216:219], v[68:71]
	v_mfma_f32_16x16x32_bf16 v[64:67], v[232:235], v[216:219], v[64:67]
	v_mfma_f32_16x16x32_bf16 v[92:95], v[228:231], v[196:199], v[92:95]
	v_mfma_f32_16x16x32_bf16 v[88:91], v[236:239], v[196:199], v[88:91]
	v_mfma_f32_16x16x32_bf16 v[84:87], v[228:231], v[204:207], v[84:87]
	v_mfma_f32_16x16x32_bf16 v[80:83], v[236:239], v[204:207], v[80:83]
	v_mfma_f32_16x16x32_bf16 v[76:79], v[228:231], v[212:215], v[76:79]
	v_mfma_f32_16x16x32_bf16 v[72:75], v[236:239], v[212:215], v[72:75]
	v_mfma_f32_16x16x32_bf16 v[68:71], v[228:231], v[220:223], v[68:71]
	v_mfma_f32_16x16x32_bf16 v[64:67], v[236:239], v[220:223], v[64:67]
	v_readfirstlane_b32 s2, v157
	v_lshl_add_u64 v[248:249], v[240:241], 0, s[18:19]
	s_mov_b32 m0, s2
	v_readfirstlane_b32 s2, v158
	s_barrier
	ds_read_b128 v[192:195], v155 offset:16384
	ds_read_b128 v[196:199], v155 offset:17408
	ds_read_b128 v[200:203], v154 offset:16384
	ds_read_b128 v[204:207], v154 offset:17408
	ds_read_b128 v[208:211], v153 offset:16384
	ds_read_b128 v[212:215], v153 offset:17408
	ds_read_b128 v[216:219], v152 offset:16384
	ds_read_b128 v[220:223], v152 offset:17408
	global_load_lds_dwordx4 v[248:249], off
	v_lshl_add_u64 v[248:249], v[242:243], 0, s[18:19]
	s_mov_b32 m0, s2
	s_nop 0
	global_load_lds_dwordx4 v[248:249], off
	s_barrier
	s_waitcnt lgkmcnt(0)
	v_mfma_f32_16x16x32_bf16 v[60:63], v[176:179], v[192:195], v[60:63]
	v_mfma_f32_16x16x32_bf16 v[56:59], v[184:187], v[192:195], v[56:59]
	v_mfma_f32_16x16x32_bf16 v[52:55], v[176:179], v[200:203], v[52:55]
	v_mfma_f32_16x16x32_bf16 v[48:51], v[184:187], v[200:203], v[48:51]
	v_mfma_f32_16x16x32_bf16 v[44:47], v[176:179], v[208:211], v[44:47]
	v_mfma_f32_16x16x32_bf16 v[40:43], v[184:187], v[208:211], v[40:43]
	v_mfma_f32_16x16x32_bf16 v[36:39], v[176:179], v[216:219], v[36:39]
	v_mfma_f32_16x16x32_bf16 v[32:35], v[184:187], v[216:219], v[32:35]
	v_mfma_f32_16x16x32_bf16 v[60:63], v[180:183], v[196:199], v[60:63]
	v_mfma_f32_16x16x32_bf16 v[56:59], v[188:191], v[196:199], v[56:59]
	v_mfma_f32_16x16x32_bf16 v[52:55], v[180:183], v[204:207], v[52:55]
	v_mfma_f32_16x16x32_bf16 v[48:51], v[188:191], v[204:207], v[48:51]
	v_mfma_f32_16x16x32_bf16 v[44:47], v[180:183], v[212:215], v[44:47]
	v_mfma_f32_16x16x32_bf16 v[40:43], v[188:191], v[212:215], v[40:43]
	v_mfma_f32_16x16x32_bf16 v[36:39], v[180:183], v[220:223], v[36:39]
	v_mfma_f32_16x16x32_bf16 v[32:35], v[188:191], v[220:223], v[32:35]
	s_barrier
	v_readfirstlane_b32 s2, v159
	v_add_u32_e32 v178, 0x2000, v159
	v_lshl_add_u64 v[176:177], v[244:245], 0, s[20:21]
	s_mov_b32 m0, s2
	v_readfirstlane_b32 s2, v178
	global_load_lds_dwordx4 v[176:177], off
	v_lshl_add_u64 v[176:177], v[246:247], 0, s[20:21]
	s_mov_b32 m0, s2
	s_nop 0
	global_load_lds_dwordx4 v[176:177], off
	s_waitcnt vmcnt(6)
	s_barrier
	v_mfma_f32_16x16x32_bf16 v[28:31], v[224:227], v[192:195], v[28:31]
	v_mfma_f32_16x16x32_bf16 v[24:27], v[232:235], v[192:195], v[24:27]
	v_mfma_f32_16x16x32_bf16 v[20:23], v[224:227], v[200:203], v[20:23]
	v_mfma_f32_16x16x32_bf16 v[16:19], v[232:235], v[200:203], v[16:19]
	v_mfma_f32_16x16x32_bf16 v[12:15], v[224:227], v[208:211], v[12:15]
	v_mfma_f32_16x16x32_bf16 v[8:11], v[232:235], v[208:211], v[8:11]
	v_mfma_f32_16x16x32_bf16 v[4:7], v[224:227], v[216:219], v[4:7]
	v_mfma_f32_16x16x32_bf16 v[0:3], v[232:235], v[216:219], v[0:3]
	v_mfma_f32_16x16x32_bf16 v[28:31], v[228:231], v[196:199], v[28:31]
	v_mfma_f32_16x16x32_bf16 v[24:27], v[236:239], v[196:199], v[24:27]
	v_mfma_f32_16x16x32_bf16 v[20:23], v[228:231], v[204:207], v[20:23]
	v_mfma_f32_16x16x32_bf16 v[16:19], v[236:239], v[204:207], v[16:19]
	v_mfma_f32_16x16x32_bf16 v[12:15], v[228:231], v[212:215], v[12:15]
	v_mfma_f32_16x16x32_bf16 v[8:11], v[236:239], v[212:215], v[8:11]
	v_mfma_f32_16x16x32_bf16 v[4:7], v[228:231], v[220:223], v[4:7]
	v_mfma_f32_16x16x32_bf16 v[0:3], v[236:239], v[220:223], v[0:3]
	s_barrier
	ds_read_b128 v[176:179], v160
	ds_read_b128 v[180:183], v160 offset:1024
	ds_read_b128 v[184:187], v160 offset:2048
	ds_read_b128 v[188:191], v160 offset:3072
	v_readfirstlane_b32 s2, v161
	v_lshl_add_u64 v[224:225], v[240:241], 0, s[24:25]
	s_mov_b32 m0, s2
	v_readfirstlane_b32 s2, v162
	ds_read_b128 v[192:195], v155 offset:32768
	ds_read_b128 v[196:199], v155 offset:33792
	ds_read_b128 v[200:203], v154 offset:32768
	ds_read_b128 v[204:207], v154 offset:33792
	ds_read_b128 v[208:211], v153 offset:32768
	ds_read_b128 v[212:215], v153 offset:33792
	ds_read_b128 v[216:219], v152 offset:32768
	ds_read_b128 v[220:223], v152 offset:33792
	global_load_lds_dwordx4 v[224:225], off
	v_lshl_add_u64 v[224:225], v[242:243], 0, s[24:25]
	s_mov_b32 m0, s2
	s_nop 0
	global_load_lds_dwordx4 v[224:225], off
	s_waitcnt lgkmcnt(8)
	s_barrier
	s_waitcnt lgkmcnt(0)
	v_mfma_f32_16x16x32_bf16 v[124:127], v[176:179], v[192:195], v[124:127]
	v_mfma_f32_16x16x32_bf16 v[120:123], v[184:187], v[192:195], v[120:123]
	v_mfma_f32_16x16x32_bf16 v[116:119], v[176:179], v[200:203], v[116:119]
	v_mfma_f32_16x16x32_bf16 v[112:115], v[184:187], v[200:203], v[112:115]
	v_mfma_f32_16x16x32_bf16 v[108:111], v[176:179], v[208:211], v[108:111]
	v_mfma_f32_16x16x32_bf16 v[104:107], v[184:187], v[208:211], v[104:107]
	v_mfma_f32_16x16x32_bf16 v[100:103], v[176:179], v[216:219], v[100:103]
	v_mfma_f32_16x16x32_bf16 v[96:99], v[184:187], v[216:219], v[96:99]
	v_mfma_f32_16x16x32_bf16 v[124:127], v[180:183], v[196:199], v[124:127]
	v_mfma_f32_16x16x32_bf16 v[120:123], v[188:191], v[196:199], v[120:123]
	v_mfma_f32_16x16x32_bf16 v[116:119], v[180:183], v[204:207], v[116:119]
	v_mfma_f32_16x16x32_bf16 v[112:115], v[188:191], v[204:207], v[112:115]
	v_mfma_f32_16x16x32_bf16 v[108:111], v[180:183], v[212:215], v[108:111]
	v_mfma_f32_16x16x32_bf16 v[104:107], v[188:191], v[212:215], v[104:107]
	v_mfma_f32_16x16x32_bf16 v[100:103], v[180:183], v[220:223], v[100:103]
	v_mfma_f32_16x16x32_bf16 v[96:99], v[188:191], v[220:223], v[96:99]
	s_barrier
	v_readfirstlane_b32 s2, v163
	v_lshl_add_u64 v[248:249], v[244:245], 0, s[26:27]
	s_mov_b32 m0, s2
	v_readfirstlane_b32 s2, v167
	ds_read_b128 v[224:227], v156
	ds_read_b128 v[228:231], v156 offset:1024
	ds_read_b128 v[232:235], v156 offset:2048
	ds_read_b128 v[236:239], v156 offset:3072
	global_load_lds_dwordx4 v[248:249], off
	v_lshl_add_u64 v[248:249], v[246:247], 0, s[26:27]
	s_mov_b32 m0, s2
	s_nop 0
	global_load_lds_dwordx4 v[248:249], off
	s_barrier
	s_waitcnt lgkmcnt(0)
	v_mfma_f32_16x16x32_bf16 v[92:95], v[224:227], v[192:195], v[92:95]
	v_mfma_f32_16x16x32_bf16 v[88:91], v[232:235], v[192:195], v[88:91]
	v_mfma_f32_16x16x32_bf16 v[84:87], v[224:227], v[200:203], v[84:87]
	v_mfma_f32_16x16x32_bf16 v[80:83], v[232:235], v[200:203], v[80:83]
	v_mfma_f32_16x16x32_bf16 v[76:79], v[224:227], v[208:211], v[76:79]
	v_mfma_f32_16x16x32_bf16 v[72:75], v[232:235], v[208:211], v[72:75]
	v_mfma_f32_16x16x32_bf16 v[68:71], v[224:227], v[216:219], v[68:71]
	v_mfma_f32_16x16x32_bf16 v[64:67], v[232:235], v[216:219], v[64:67]
	v_mfma_f32_16x16x32_bf16 v[92:95], v[228:231], v[196:199], v[92:95]
	v_mfma_f32_16x16x32_bf16 v[88:91], v[236:239], v[196:199], v[88:91]
	v_mfma_f32_16x16x32_bf16 v[84:87], v[228:231], v[204:207], v[84:87]
	v_mfma_f32_16x16x32_bf16 v[80:83], v[236:239], v[204:207], v[80:83]
	v_mfma_f32_16x16x32_bf16 v[76:79], v[228:231], v[212:215], v[76:79]
	v_mfma_f32_16x16x32_bf16 v[72:75], v[236:239], v[212:215], v[72:75]
	v_mfma_f32_16x16x32_bf16 v[68:71], v[228:231], v[220:223], v[68:71]
	v_mfma_f32_16x16x32_bf16 v[64:67], v[236:239], v[220:223], v[64:67]
	v_readfirstlane_b32 s2, v168
	v_lshl_add_u64 v[240:241], v[240:241], 0, s[28:29]
	s_mov_b32 m0, s2
	v_readfirstlane_b32 s2, v169
	s_barrier
	ds_read_b128 v[192:195], v155 offset:49152
	ds_read_b128 v[196:199], v155 offset:50176
	ds_read_b128 v[200:203], v154 offset:49152
	ds_read_b128 v[204:207], v154 offset:50176
	ds_read_b128 v[208:211], v153 offset:49152
	ds_read_b128 v[212:215], v153 offset:50176
	ds_read_b128 v[216:219], v152 offset:49152
	ds_read_b128 v[220:223], v152 offset:50176
	global_load_lds_dwordx4 v[240:241], off
	v_lshl_add_u64 v[240:241], v[242:243], 0, s[28:29]
	s_mov_b32 m0, s2
	s_nop 0
	global_load_lds_dwordx4 v[240:241], off
	s_barrier
	s_waitcnt lgkmcnt(0)
	v_mfma_f32_16x16x32_bf16 v[60:63], v[176:179], v[192:195], v[60:63]
	v_mfma_f32_16x16x32_bf16 v[56:59], v[184:187], v[192:195], v[56:59]
	v_mfma_f32_16x16x32_bf16 v[52:55], v[176:179], v[200:203], v[52:55]
	v_mfma_f32_16x16x32_bf16 v[48:51], v[184:187], v[200:203], v[48:51]
	v_mfma_f32_16x16x32_bf16 v[44:47], v[176:179], v[208:211], v[44:47]
	v_mfma_f32_16x16x32_bf16 v[40:43], v[184:187], v[208:211], v[40:43]
	v_mfma_f32_16x16x32_bf16 v[36:39], v[176:179], v[216:219], v[36:39]
	v_mfma_f32_16x16x32_bf16 v[32:35], v[184:187], v[216:219], v[32:35]
	v_mfma_f32_16x16x32_bf16 v[60:63], v[180:183], v[196:199], v[60:63]
	v_mfma_f32_16x16x32_bf16 v[56:59], v[188:191], v[196:199], v[56:59]
	v_mfma_f32_16x16x32_bf16 v[52:55], v[180:183], v[204:207], v[52:55]
	v_mfma_f32_16x16x32_bf16 v[48:51], v[188:191], v[204:207], v[48:51]
	v_mfma_f32_16x16x32_bf16 v[44:47], v[180:183], v[212:215], v[44:47]
	v_mfma_f32_16x16x32_bf16 v[40:43], v[188:191], v[212:215], v[40:43]
	v_mfma_f32_16x16x32_bf16 v[36:39], v[180:183], v[220:223], v[36:39]
	v_mfma_f32_16x16x32_bf16 v[32:35], v[188:191], v[220:223], v[32:35]
	s_barrier
	v_readfirstlane_b32 s2, v171
	v_lshl_add_u64 v[176:177], v[244:245], 0, s[30:31]
	s_mov_b32 m0, s2
	v_readfirstlane_b32 s2, v172
	global_load_lds_dwordx4 v[176:177], off
	v_lshl_add_u64 v[176:177], v[246:247], 0, s[30:31]
	s_mov_b32 m0, s2
	s_nop 0
	global_load_lds_dwordx4 v[176:177], off
	s_waitcnt vmcnt(6)
	s_barrier
	v_mfma_f32_16x16x32_bf16 v[28:31], v[224:227], v[192:195], v[28:31]
	v_mfma_f32_16x16x32_bf16 v[24:27], v[232:235], v[192:195], v[24:27]
	v_mfma_f32_16x16x32_bf16 v[20:23], v[224:227], v[200:203], v[20:23]
	v_mfma_f32_16x16x32_bf16 v[16:19], v[232:235], v[200:203], v[16:19]
	v_mfma_f32_16x16x32_bf16 v[12:15], v[224:227], v[208:211], v[12:15]
	v_mfma_f32_16x16x32_bf16 v[8:11], v[232:235], v[208:211], v[8:11]
	v_mfma_f32_16x16x32_bf16 v[4:7], v[224:227], v[216:219], v[4:7]
	v_mfma_f32_16x16x32_bf16 v[0:3], v[232:235], v[216:219], v[0:3]
	v_mfma_f32_16x16x32_bf16 v[28:31], v[228:231], v[196:199], v[28:31]
	v_mfma_f32_16x16x32_bf16 v[24:27], v[236:239], v[196:199], v[24:27]
	v_mfma_f32_16x16x32_bf16 v[20:23], v[228:231], v[204:207], v[20:23]
	v_mfma_f32_16x16x32_bf16 v[16:19], v[236:239], v[204:207], v[16:19]
	v_mfma_f32_16x16x32_bf16 v[12:15], v[228:231], v[212:215], v[12:15]
	v_mfma_f32_16x16x32_bf16 v[8:11], v[236:239], v[212:215], v[8:11]
	v_mfma_f32_16x16x32_bf16 v[4:7], v[228:231], v[220:223], v[4:7]
	v_mfma_f32_16x16x32_bf16 v[0:3], v[236:239], v[220:223], v[0:3]
	s_add_i32 s1, s1, 2
	v_lshl_add_u64 v[138:139], v[138:139], 0, s[34:35]
	v_lshl_add_u64 v[140:141], v[140:141], 0, s[34:35]
	v_lshl_add_u64 v[142:143], v[142:143], 0, s[34:35]
	s_cmp_lt_u32 s1, 60
	v_lshl_add_u64 v[144:145], v[144:145], 0, s[34:35]
	s_barrier
	s_cbranch_scc1 .LBB0_1720
	s_add_u32 s4, s38, 0x1f80
	s_addc_u32 s5, s39, 0
	v_lshl_add_u64 v[132:133], s[4:5], 0, v[132:133]
	v_readfirstlane_b32 s1, v174
	v_lshl_add_u64 v[130:131], v[130:131], 1, v[132:133]
	s_mov_b32 m0, s1
	ds_read_b128 v[138:141], v173
	ds_read_b128 v[142:145], v173 offset:1024
	ds_read_b128 v[176:179], v173 offset:2048
	ds_read_b128 v[180:183], v173 offset:3072
	ds_read_b128 v[184:187], v155
	ds_read_b128 v[188:191], v155 offset:1024
	ds_read_b128 v[192:195], v154
	ds_read_b128 v[196:199], v154 offset:1024
	ds_read_b128 v[200:203], v153
	ds_read_b128 v[204:207], v153 offset:1024
	ds_read_b128 v[208:211], v152
	ds_read_b128 v[212:215], v152 offset:1024
	global_load_lds_dwordx4 v[130:131], off
	v_lshl_add_u64 v[130:131], s[4:5], 0, v[136:137]
	v_readfirstlane_b32 s1, v175
	v_lshl_add_u64 v[130:131], v[134:135], 1, v[130:131]
	s_mov_b32 m0, s1
	s_nop 0
	global_load_lds_dwordx4 v[130:131], off
	s_barrier
	s_waitcnt lgkmcnt(0)
	v_mfma_f32_16x16x32_bf16 v[124:127], v[138:141], v[184:187], v[124:127]
	v_mfma_f32_16x16x32_bf16 v[116:119], v[138:141], v[192:195], v[116:119]
	v_mfma_f32_16x16x32_bf16 v[108:111], v[138:141], v[200:203], v[108:111]
	v_mfma_f32_16x16x32_bf16 v[100:103], v[138:141], v[208:211], v[100:103]
	v_mfma_f32_16x16x32_bf16 v[124:127], v[142:145], v[188:191], v[124:127]
	v_mfma_f32_16x16x32_bf16 v[120:123], v[176:179], v[184:187], v[120:123]
	v_mfma_f32_16x16x32_bf16 v[116:119], v[142:145], v[196:199], v[116:119]
	v_mfma_f32_16x16x32_bf16 v[112:115], v[176:179], v[192:195], v[112:115]
	v_mfma_f32_16x16x32_bf16 v[108:111], v[142:145], v[204:207], v[108:111]
	v_mfma_f32_16x16x32_bf16 v[104:107], v[176:179], v[200:203], v[104:107]
	v_mfma_f32_16x16x32_bf16 v[100:103], v[142:145], v[212:215], v[100:103]
	v_mfma_f32_16x16x32_bf16 v[96:99], v[176:179], v[208:211], v[96:99]
	v_mfma_f32_16x16x32_bf16 v[130:133], v[180:183], v[188:191], v[120:123]
	v_mfma_f32_16x16x32_bf16 v[134:137], v[180:183], v[196:199], v[112:115]
	v_mfma_f32_16x16x32_bf16 v[172:175], v[180:183], v[204:207], v[104:107]
	v_mfma_f32_16x16x32_bf16 v[216:219], v[180:183], v[212:215], v[96:99]
	s_barrier
	s_nop 1
	ds_read_b128 v[96:99], v170
	ds_read_b128 v[104:107], v170 offset:1024
	ds_read_b128 v[112:115], v170 offset:2048
	ds_read_b128 v[120:123], v170 offset:3072
	s_barrier
	s_waitcnt lgkmcnt(0)
	v_mfma_f32_16x16x32_bf16 v[92:95], v[96:99], v[184:187], v[92:95]
	v_mfma_f32_16x16x32_bf16 v[84:87], v[96:99], v[192:195], v[84:87]
	v_mfma_f32_16x16x32_bf16 v[76:79], v[96:99], v[200:203], v[76:79]
	v_mfma_f32_16x16x32_bf16 v[68:71], v[96:99], v[208:211], v[68:71]
	v_mfma_f32_16x16x32_bf16 v[92:95], v[104:107], v[188:191], v[92:95]
	v_mfma_f32_16x16x32_bf16 v[88:91], v[112:115], v[184:187], v[88:91]
	v_mfma_f32_16x16x32_bf16 v[84:87], v[104:107], v[196:199], v[84:87]
	v_mfma_f32_16x16x32_bf16 v[80:83], v[112:115], v[192:195], v[80:83]
	v_mfma_f32_16x16x32_bf16 v[76:79], v[104:107], v[204:207], v[76:79]
	v_mfma_f32_16x16x32_bf16 v[72:75], v[112:115], v[200:203], v[72:75]
	v_mfma_f32_16x16x32_bf16 v[68:71], v[104:107], v[212:215], v[68:71]
	v_mfma_f32_16x16x32_bf16 v[64:67], v[112:115], v[208:211], v[64:67]
	v_mfma_f32_16x16x32_bf16 v[168:171], v[120:123], v[188:191], v[88:91]
	v_mfma_f32_16x16x32_bf16 v[184:187], v[120:123], v[196:199], v[80:83]
	v_mfma_f32_16x16x32_bf16 v[188:191], v[120:123], v[204:207], v[72:75]
	v_mfma_f32_16x16x32_bf16 v[192:195], v[120:123], v[212:215], v[64:67]
	s_barrier
	s_nop 1
	ds_read_b128 v[64:67], v155 offset:16384
	ds_read_b128 v[72:75], v155 offset:17408
	ds_read_b128 v[80:83], v154 offset:16384
	ds_read_b128 v[88:91], v154 offset:17408
	ds_read_b128 v[196:199], v153 offset:16384
	ds_read_b128 v[200:203], v153 offset:17408
	ds_read_b128 v[204:207], v152 offset:16384
	ds_read_b128 v[208:211], v152 offset:17408
	s_waitcnt vmcnt(4)
	s_barrier
	s_waitcnt lgkmcnt(0)
	v_mfma_f32_16x16x32_bf16 v[60:63], v[138:141], v[64:67], v[60:63]
	v_mfma_f32_16x16x32_bf16 v[52:55], v[138:141], v[80:83], v[52:55]
	v_mfma_f32_16x16x32_bf16 v[44:47], v[138:141], v[196:199], v[44:47]
	v_mfma_f32_16x16x32_bf16 v[36:39], v[138:141], v[204:207], v[36:39]
	v_mfma_f32_16x16x32_bf16 v[60:63], v[142:145], v[72:75], v[60:63]
	v_mfma_f32_16x16x32_bf16 v[56:59], v[176:179], v[64:67], v[56:59]
	v_mfma_f32_16x16x32_bf16 v[52:55], v[142:145], v[88:91], v[52:55]
	v_mfma_f32_16x16x32_bf16 v[48:51], v[176:179], v[80:83], v[48:51]
	v_mfma_f32_16x16x32_bf16 v[44:47], v[142:145], v[200:203], v[44:47]
	v_mfma_f32_16x16x32_bf16 v[40:43], v[176:179], v[196:199], v[40:43]
	v_mfma_f32_16x16x32_bf16 v[36:39], v[142:145], v[208:211], v[36:39]
	v_mfma_f32_16x16x32_bf16 v[32:35], v[176:179], v[204:207], v[32:35]
	v_mfma_f32_16x16x32_bf16 v[212:215], v[180:183], v[72:75], v[56:59]
	v_mfma_f32_16x16x32_bf16 v[220:223], v[180:183], v[88:91], v[48:51]
	v_mfma_f32_16x16x32_bf16 v[224:227], v[180:183], v[200:203], v[40:43]
	v_mfma_f32_16x16x32_bf16 v[138:141], v[180:183], v[208:211], v[32:35]
	v_mfma_f32_16x16x32_bf16 v[28:31], v[96:99], v[64:67], v[28:31]
	v_mfma_f32_16x16x32_bf16 v[20:23], v[96:99], v[80:83], v[20:23]
	v_mfma_f32_16x16x32_bf16 v[12:15], v[96:99], v[196:199], v[12:15]
	v_mfma_f32_16x16x32_bf16 v[4:7], v[96:99], v[204:207], v[4:7]
	v_mfma_f32_16x16x32_bf16 v[28:31], v[104:107], v[72:75], v[28:31]
	v_mfma_f32_16x16x32_bf16 v[24:27], v[112:115], v[64:67], v[24:27]
	v_mfma_f32_16x16x32_bf16 v[20:23], v[104:107], v[88:91], v[20:23]
	v_mfma_f32_16x16x32_bf16 v[16:19], v[112:115], v[80:83], v[16:19]
	v_mfma_f32_16x16x32_bf16 v[12:15], v[104:107], v[200:203], v[12:15]
	v_mfma_f32_16x16x32_bf16 v[8:11], v[112:115], v[196:199], v[8:11]
	v_mfma_f32_16x16x32_bf16 v[4:7], v[104:107], v[208:211], v[4:7]
	v_mfma_f32_16x16x32_bf16 v[0:3], v[112:115], v[204:207], v[0:3]
	v_mfma_f32_16x16x32_bf16 v[142:145], v[120:123], v[72:75], v[24:27]
	v_mfma_f32_16x16x32_bf16 v[176:179], v[120:123], v[88:91], v[16:19]
	v_mfma_f32_16x16x32_bf16 v[180:183], v[120:123], v[200:203], v[8:11]
	v_mfma_f32_16x16x32_bf16 v[196:199], v[120:123], v[208:211], v[0:3]
	s_barrier
	s_nop 1
	ds_read_b128 v[0:3], v160
	ds_read_b128 v[8:11], v160 offset:1024
	ds_read_b128 v[16:19], v160 offset:2048
	ds_read_b128 v[24:27], v160 offset:3072
	ds_read_b128 v[32:35], v155 offset:32768
	ds_read_b128 v[40:43], v155 offset:33792
	ds_read_b128 v[48:51], v154 offset:32768
	ds_read_b128 v[56:59], v154 offset:33792
	ds_read_b128 v[64:67], v153 offset:32768
	ds_read_b128 v[158:161], v153 offset:33792
	ds_read_b128 v[200:203], v152 offset:32768
	ds_read_b128 v[204:207], v152 offset:33792
	s_waitcnt vmcnt(2)
	s_barrier
	s_waitcnt lgkmcnt(0)
	v_mfma_f32_16x16x32_bf16 v[72:75], v[0:3], v[32:35], v[124:127]
	v_mfma_f32_16x16x32_bf16 v[120:123], v[8:11], v[40:43], v[72:75]
	v_mfma_f32_16x16x32_bf16 v[72:75], v[16:19], v[32:35], v[130:133]
	v_mfma_f32_16x16x32_bf16 v[124:127], v[24:27], v[40:43], v[72:75]
	v_mfma_f32_16x16x32_bf16 v[72:75], v[0:3], v[48:51], v[116:119]
	v_mfma_f32_16x16x32_bf16 v[112:115], v[8:11], v[56:59], v[72:75]
	v_mfma_f32_16x16x32_bf16 v[72:75], v[16:19], v[48:51], v[134:137]
	v_mfma_f32_16x16x32_bf16 v[116:119], v[24:27], v[56:59], v[72:75]
	v_mfma_f32_16x16x32_bf16 v[72:75], v[0:3], v[64:67], v[108:111]
	v_mfma_f32_16x16x32_bf16 v[104:107], v[8:11], v[158:161], v[72:75]
	v_mfma_f32_16x16x32_bf16 v[72:75], v[16:19], v[64:67], v[172:175]
	v_mfma_f32_16x16x32_bf16 v[108:111], v[24:27], v[158:161], v[72:75]
	v_mfma_f32_16x16x32_bf16 v[72:75], v[0:3], v[200:203], v[100:103]
	v_mfma_f32_16x16x32_bf16 v[96:99], v[8:11], v[204:207], v[72:75]
	v_mfma_f32_16x16x32_bf16 v[72:75], v[16:19], v[200:203], v[216:219]
	v_mfma_f32_16x16x32_bf16 v[100:103], v[24:27], v[204:207], v[72:75]
	s_barrier
	ds_read_b128 v[130:133], v156
	ds_read_b128 v[134:137], v156 offset:1024
	ds_read_b128 v[172:175], v156 offset:2048
	ds_read_b128 v[208:211], v156 offset:3072
	s_waitcnt vmcnt(0)
	s_barrier
	s_waitcnt lgkmcnt(0)
	v_mfma_f32_16x16x32_bf16 v[72:75], v[130:133], v[32:35], v[92:95]
	v_mfma_f32_16x16x32_bf16 v[32:35], v[172:175], v[32:35], v[168:171]
	v_mfma_f32_16x16x32_bf16 v[92:95], v[208:211], v[40:43], v[32:35]
	v_mfma_f32_16x16x32_bf16 v[32:35], v[130:133], v[48:51], v[84:87]
	v_mfma_f32_16x16x32_bf16 v[80:83], v[134:137], v[56:59], v[32:35]
	v_mfma_f32_16x16x32_bf16 v[32:35], v[172:175], v[48:51], v[184:187]
	v_mfma_f32_16x16x32_bf16 v[84:87], v[208:211], v[56:59], v[32:35]
	v_mfma_f32_16x16x32_bf16 v[32:35], v[130:133], v[64:67], v[76:79]
	v_mfma_f32_16x16x32_bf16 v[88:91], v[134:137], v[40:43], v[72:75]
	v_mfma_f32_16x16x32_bf16 v[72:75], v[134:137], v[158:161], v[32:35]
	v_mfma_f32_16x16x32_bf16 v[32:35], v[172:175], v[64:67], v[188:191]
	v_mfma_f32_16x16x32_bf16 v[76:79], v[208:211], v[158:161], v[32:35]
	v_mfma_f32_16x16x32_bf16 v[32:35], v[130:133], v[200:203], v[68:71]
	v_mfma_f32_16x16x32_bf16 v[64:67], v[134:137], v[204:207], v[32:35]
	v_mfma_f32_16x16x32_bf16 v[32:35], v[172:175], v[200:203], v[192:195]
	v_mfma_f32_16x16x32_bf16 v[68:71], v[208:211], v[204:207], v[32:35]
	s_barrier
	ds_read_b128 v[156:159], v155 offset:49152
	ds_read_b128 v[160:163], v155 offset:50176
	ds_read_b128 v[168:171], v154 offset:49152
	ds_read_b128 v[184:187], v154 offset:50176
	ds_read_b128 v[188:191], v153 offset:49152
	ds_read_b128 v[192:195], v153 offset:50176
	ds_read_b128 v[200:203], v152 offset:49152
	ds_read_b128 v[152:155], v152 offset:50176
	s_barrier
	s_waitcnt lgkmcnt(0)
	v_mfma_f32_16x16x32_bf16 v[32:35], v[0:3], v[156:159], v[60:63]
	v_mfma_f32_16x16x32_bf16 v[56:59], v[8:11], v[160:163], v[32:35]
	v_mfma_f32_16x16x32_bf16 v[32:35], v[16:19], v[156:159], v[212:215]
	v_mfma_f32_16x16x32_bf16 v[60:63], v[24:27], v[160:163], v[32:35]
	v_mfma_f32_16x16x32_bf16 v[32:35], v[0:3], v[168:171], v[52:55]
	v_mfma_f32_16x16x32_bf16 v[48:51], v[8:11], v[184:187], v[32:35]
	v_mfma_f32_16x16x32_bf16 v[32:35], v[16:19], v[168:171], v[220:223]
	v_mfma_f32_16x16x32_bf16 v[52:55], v[24:27], v[184:187], v[32:35]
	v_mfma_f32_16x16x32_bf16 v[32:35], v[0:3], v[188:191], v[44:47]
	v_mfma_f32_16x16x32_bf16 v[40:43], v[8:11], v[192:195], v[32:35]
	v_mfma_f32_16x16x32_bf16 v[32:35], v[16:19], v[188:191], v[224:227]
	v_mfma_f32_16x16x32_bf16 v[0:3], v[0:3], v[200:203], v[36:39]
	v_mfma_f32_16x16x32_bf16 v[44:47], v[24:27], v[192:195], v[32:35]
	v_mfma_f32_16x16x32_bf16 v[32:35], v[8:11], v[152:155], v[0:3]
	v_mfma_f32_16x16x32_bf16 v[0:3], v[16:19], v[200:203], v[138:141]
	v_mfma_f32_16x16x32_bf16 v[36:39], v[24:27], v[152:155], v[0:3]
	v_mfma_f32_16x16x32_bf16 v[0:3], v[130:133], v[156:159], v[28:31]
	v_mfma_f32_16x16x32_bf16 v[24:27], v[134:137], v[160:163], v[0:3]
	v_mfma_f32_16x16x32_bf16 v[0:3], v[172:175], v[156:159], v[142:145]
	v_mfma_f32_16x16x32_bf16 v[28:31], v[208:211], v[160:163], v[0:3]
	v_mfma_f32_16x16x32_bf16 v[0:3], v[130:133], v[168:171], v[20:23]
	v_mfma_f32_16x16x32_bf16 v[16:19], v[134:137], v[184:187], v[0:3]
	v_mfma_f32_16x16x32_bf16 v[0:3], v[172:175], v[168:171], v[176:179]
	v_mfma_f32_16x16x32_bf16 v[20:23], v[208:211], v[184:187], v[0:3]
	v_mfma_f32_16x16x32_bf16 v[0:3], v[130:133], v[188:191], v[12:15]
	v_mfma_f32_16x16x32_bf16 v[8:11], v[134:137], v[192:195], v[0:3]
	v_mfma_f32_16x16x32_bf16 v[0:3], v[172:175], v[188:191], v[180:183]
	v_mfma_f32_16x16x32_bf16 v[12:15], v[208:211], v[192:195], v[0:3]
	v_mfma_f32_16x16x32_bf16 v[0:3], v[130:133], v[200:203], v[4:7]
	v_mfma_f32_16x16x32_bf16 v[4:7], v[172:175], v[200:203], v[196:199]
	v_mfma_f32_16x16x32_bf16 v[0:3], v[134:137], v[152:155], v[0:3]
	v_mfma_f32_16x16x32_bf16 v[4:7], v[208:211], v[152:155], v[4:7]
	v_cmp_gt_u32_e32 vcc, s75, v128
	s_barrier
	s_and_saveexec_b64 s[38:39], vcc
	s_cbranch_execz .LBB0_1716
	s_barrier
	s_branch .LBB0_1716

.LBB0_1842:
	ds_read_b128 v[180:183], v172
	ds_read_b128 v[184:187], v172 offset:1024
	ds_read_b128 v[188:191], v172 offset:2048
	ds_read_b128 v[192:195], v172 offset:3072
	v_add_u32_e32 v178, 0xc000, v152
	v_lshl_add_u64 v[244:245], s[12:13], 0, v[146:147]
	v_readfirstlane_b32 s1, v178
	v_add_u32_e32 v179, 0xe000, v152
	v_lshl_add_u64 v[224:225], v[244:245], 0, s[20:21]
	s_mov_b32 m0, s1
	v_lshl_add_u64 v[246:247], s[12:13], 0, v[148:149]
	v_readfirstlane_b32 s1, v179
	ds_read_b128 v[174:177], v161
	ds_read_b128 v[196:199], v161 offset:1024
	ds_read_b128 v[200:203], v160
	ds_read_b128 v[204:207], v160 offset:1024
	ds_read_b128 v[208:211], v159
	ds_read_b128 v[212:215], v159 offset:1024
	ds_read_b128 v[216:219], v158
	ds_read_b128 v[220:223], v158 offset:1024
	global_load_lds_dwordx4 v[224:225], off
	v_lshl_add_u64 v[224:225], v[246:247], 0, s[20:21]
	s_mov_b32 m0, s1
	s_nop 0
	global_load_lds_dwordx4 v[224:225], off
	s_waitcnt lgkmcnt(8)
	s_barrier
	s_waitcnt lgkmcnt(0)
	v_mfma_f32_16x16x32_bf16 v[124:127], v[180:183], v[174:177], v[124:127]
	v_mfma_f32_16x16x32_bf16 v[120:123], v[188:191], v[174:177], v[120:123]
	v_mfma_f32_16x16x32_bf16 v[116:119], v[180:183], v[200:203], v[116:119]
	v_mfma_f32_16x16x32_bf16 v[112:115], v[188:191], v[200:203], v[112:115]
	v_mfma_f32_16x16x32_bf16 v[108:111], v[180:183], v[208:211], v[108:111]
	v_mfma_f32_16x16x32_bf16 v[104:107], v[188:191], v[208:211], v[104:107]
	v_mfma_f32_16x16x32_bf16 v[100:103], v[180:183], v[216:219], v[100:103]
	v_mfma_f32_16x16x32_bf16 v[96:99], v[188:191], v[216:219], v[96:99]
	v_mfma_f32_16x16x32_bf16 v[124:127], v[184:187], v[196:199], v[124:127]
	v_mfma_f32_16x16x32_bf16 v[120:123], v[192:195], v[196:199], v[120:123]
	v_mfma_f32_16x16x32_bf16 v[116:119], v[184:187], v[204:207], v[116:119]
	v_mfma_f32_16x16x32_bf16 v[112:115], v[192:195], v[204:207], v[112:115]
	v_mfma_f32_16x16x32_bf16 v[108:111], v[184:187], v[212:215], v[108:111]
	v_mfma_f32_16x16x32_bf16 v[104:107], v[192:195], v[212:215], v[104:107]
	v_mfma_f32_16x16x32_bf16 v[100:103], v[184:187], v[220:223], v[100:103]
	v_mfma_f32_16x16x32_bf16 v[96:99], v[192:195], v[220:223], v[96:99]
	s_barrier
	v_lshl_add_u64 v[248:249], s[12:13], 0, v[142:143]
	v_readfirstlane_b32 s1, v153
	v_add_u32_e32 v173, 0x2000, v153
	v_lshl_add_u64 v[240:241], v[248:249], 0, s[24:25]
	s_mov_b32 m0, s1
	v_lshl_add_u64 v[250:251], s[12:13], 0, v[144:145]
	v_readfirstlane_b32 s1, v173
	ds_read_b128 v[224:227], v169
	ds_read_b128 v[228:231], v169 offset:1024
	ds_read_b128 v[232:235], v169 offset:2048
	ds_read_b128 v[236:239], v169 offset:3072
	global_load_lds_dwordx4 v[240:241], off
	v_lshl_add_u64 v[240:241], v[250:251], 0, s[24:25]
	s_mov_b32 m0, s1
	s_nop 0
	global_load_lds_dwordx4 v[240:241], off
	s_barrier
	s_waitcnt lgkmcnt(0)
	v_mfma_f32_16x16x32_bf16 v[92:95], v[224:227], v[174:177], v[92:95]
	v_mfma_f32_16x16x32_bf16 v[88:91], v[232:235], v[174:177], v[88:91]
	v_mfma_f32_16x16x32_bf16 v[84:87], v[224:227], v[200:203], v[84:87]
	v_mfma_f32_16x16x32_bf16 v[80:83], v[232:235], v[200:203], v[80:83]
	v_mfma_f32_16x16x32_bf16 v[76:79], v[224:227], v[208:211], v[76:79]
	v_mfma_f32_16x16x32_bf16 v[72:75], v[232:235], v[208:211], v[72:75]
	v_mfma_f32_16x16x32_bf16 v[68:71], v[224:227], v[216:219], v[68:71]
	v_mfma_f32_16x16x32_bf16 v[64:67], v[232:235], v[216:219], v[64:67]
	v_mfma_f32_16x16x32_bf16 v[92:95], v[228:231], v[196:199], v[92:95]
	v_mfma_f32_16x16x32_bf16 v[88:91], v[236:239], v[196:199], v[88:91]
	v_mfma_f32_16x16x32_bf16 v[84:87], v[228:231], v[204:207], v[84:87]
	v_mfma_f32_16x16x32_bf16 v[80:83], v[236:239], v[204:207], v[80:83]
	v_mfma_f32_16x16x32_bf16 v[76:79], v[228:231], v[212:215], v[76:79]
	v_mfma_f32_16x16x32_bf16 v[72:75], v[236:239], v[212:215], v[72:75]
	v_mfma_f32_16x16x32_bf16 v[68:71], v[228:231], v[220:223], v[68:71]
	v_mfma_f32_16x16x32_bf16 v[64:67], v[236:239], v[220:223], v[64:67]
	v_readfirstlane_b32 s1, v152
	v_lshl_add_u64 v[174:175], v[244:245], 0, s[26:27]
	s_mov_b32 m0, s1
	s_barrier
	ds_read_b128 v[196:199], v161 offset:16384
	ds_read_b128 v[200:203], v161 offset:17408
	ds_read_b128 v[204:207], v160 offset:16384
	ds_read_b128 v[208:211], v160 offset:17408
	ds_read_b128 v[212:215], v159 offset:16384
	ds_read_b128 v[216:219], v159 offset:17408
	ds_read_b128 v[220:223], v158 offset:16384
	ds_read_b128 v[240:243], v158 offset:17408
	global_load_lds_dwordx4 v[174:175], off
	v_add_u32_e32 v174, 0x2000, v152
	v_lshl_add_u64 v[176:177], v[246:247], 0, s[26:27]
	v_readfirstlane_b32 s1, v174
	s_mov_b32 m0, s1
	s_nop 0
	global_load_lds_dwordx4 v[176:177], off
	s_barrier
	s_waitcnt lgkmcnt(0)
	v_mfma_f32_16x16x32_bf16 v[60:63], v[180:183], v[196:199], v[60:63]
	v_mfma_f32_16x16x32_bf16 v[56:59], v[188:191], v[196:199], v[56:59]
	v_mfma_f32_16x16x32_bf16 v[52:55], v[180:183], v[204:207], v[52:55]
	v_mfma_f32_16x16x32_bf16 v[48:51], v[188:191], v[204:207], v[48:51]
	v_mfma_f32_16x16x32_bf16 v[44:47], v[180:183], v[212:215], v[44:47]
	v_mfma_f32_16x16x32_bf16 v[40:43], v[188:191], v[212:215], v[40:43]
	v_mfma_f32_16x16x32_bf16 v[36:39], v[180:183], v[220:223], v[36:39]
	v_mfma_f32_16x16x32_bf16 v[32:35], v[188:191], v[220:223], v[32:35]
	v_mfma_f32_16x16x32_bf16 v[60:63], v[184:187], v[200:203], v[60:63]
	v_mfma_f32_16x16x32_bf16 v[56:59], v[192:195], v[200:203], v[56:59]
	v_mfma_f32_16x16x32_bf16 v[52:55], v[184:187], v[208:211], v[52:55]
	v_mfma_f32_16x16x32_bf16 v[48:51], v[192:195], v[208:211], v[48:51]
	v_mfma_f32_16x16x32_bf16 v[44:47], v[184:187], v[216:219], v[44:47]
	v_mfma_f32_16x16x32_bf16 v[40:43], v[192:195], v[216:219], v[40:43]
	v_mfma_f32_16x16x32_bf16 v[36:39], v[184:187], v[240:243], v[36:39]
	v_mfma_f32_16x16x32_bf16 v[32:35], v[192:195], v[240:243], v[32:35]
	s_barrier
	v_readfirstlane_b32 s1, v151
	v_add_u32_e32 v175, 0x2000, v151
	v_lshl_add_u64 v[176:177], v[248:249], 0, s[28:29]
	s_mov_b32 m0, s1
	v_readfirstlane_b32 s1, v175
	global_load_lds_dwordx4 v[176:177], off
	v_lshl_add_u64 v[176:177], v[250:251], 0, s[28:29]
	s_mov_b32 m0, s1
	s_nop 0
	global_load_lds_dwordx4 v[176:177], off
	s_waitcnt vmcnt(6)
	s_barrier
	v_mfma_f32_16x16x32_bf16 v[28:31], v[224:227], v[196:199], v[28:31]
	v_mfma_f32_16x16x32_bf16 v[24:27], v[232:235], v[196:199], v[24:27]
	v_mfma_f32_16x16x32_bf16 v[20:23], v[224:227], v[204:207], v[20:23]
	v_mfma_f32_16x16x32_bf16 v[16:19], v[232:235], v[204:207], v[16:19]
	v_mfma_f32_16x16x32_bf16 v[12:15], v[224:227], v[212:215], v[12:15]
	v_mfma_f32_16x16x32_bf16 v[8:11], v[232:235], v[212:215], v[8:11]
	v_mfma_f32_16x16x32_bf16 v[4:7], v[224:227], v[220:223], v[4:7]
	v_mfma_f32_16x16x32_bf16 v[0:3], v[232:235], v[220:223], v[0:3]
	v_mfma_f32_16x16x32_bf16 v[28:31], v[228:231], v[200:203], v[28:31]
	v_mfma_f32_16x16x32_bf16 v[24:27], v[236:239], v[200:203], v[24:27]
	v_mfma_f32_16x16x32_bf16 v[20:23], v[228:231], v[208:211], v[20:23]
	v_mfma_f32_16x16x32_bf16 v[16:19], v[236:239], v[208:211], v[16:19]
	v_mfma_f32_16x16x32_bf16 v[12:15], v[228:231], v[216:219], v[12:15]
	v_mfma_f32_16x16x32_bf16 v[8:11], v[236:239], v[216:219], v[8:11]
	v_mfma_f32_16x16x32_bf16 v[4:7], v[228:231], v[240:243], v[4:7]
	v_mfma_f32_16x16x32_bf16 v[0:3], v[236:239], v[240:243], v[0:3]
	s_barrier
	ds_read_b128 v[180:183], v163
	ds_read_b128 v[184:187], v163 offset:1024
	ds_read_b128 v[188:191], v163 offset:2048
	ds_read_b128 v[192:195], v163 offset:3072
	v_add_u32_e32 v176, 0x4000, v152
	v_add_u32_e32 v177, 0x6000, v152
	v_readfirstlane_b32 s1, v176
	v_lshl_add_u64 v[228:229], v[244:245], 0, s[30:31]
	s_mov_b32 m0, s1
	v_readfirstlane_b32 s1, v177
	ds_read_b128 v[196:199], v161 offset:32768
	ds_read_b128 v[200:203], v161 offset:33792
	ds_read_b128 v[204:207], v160 offset:32768
	ds_read_b128 v[208:211], v160 offset:33792
	ds_read_b128 v[212:215], v159 offset:32768
	ds_read_b128 v[216:219], v159 offset:33792
	ds_read_b128 v[220:223], v158 offset:32768
	ds_read_b128 v[224:227], v158 offset:33792
	global_load_lds_dwordx4 v[228:229], off
	v_lshl_add_u64 v[228:229], v[246:247], 0, s[30:31]
	s_mov_b32 m0, s1
	s_nop 0
	global_load_lds_dwordx4 v[228:229], off
	s_waitcnt lgkmcnt(8)
	s_barrier
	s_waitcnt lgkmcnt(0)
	v_mfma_f32_16x16x32_bf16 v[124:127], v[180:183], v[196:199], v[124:127]
	v_mfma_f32_16x16x32_bf16 v[120:123], v[188:191], v[196:199], v[120:123]
	v_mfma_f32_16x16x32_bf16 v[116:119], v[180:183], v[204:207], v[116:119]
	v_mfma_f32_16x16x32_bf16 v[112:115], v[188:191], v[204:207], v[112:115]
	v_mfma_f32_16x16x32_bf16 v[108:111], v[180:183], v[212:215], v[108:111]
	v_mfma_f32_16x16x32_bf16 v[104:107], v[188:191], v[212:215], v[104:107]
	v_mfma_f32_16x16x32_bf16 v[100:103], v[180:183], v[220:223], v[100:103]
	v_mfma_f32_16x16x32_bf16 v[96:99], v[188:191], v[220:223], v[96:99]
	v_mfma_f32_16x16x32_bf16 v[124:127], v[184:187], v[200:203], v[124:127]
	v_mfma_f32_16x16x32_bf16 v[120:123], v[192:195], v[200:203], v[120:123]
	v_mfma_f32_16x16x32_bf16 v[116:119], v[184:187], v[208:211], v[116:119]
	v_mfma_f32_16x16x32_bf16 v[112:115], v[192:195], v[208:211], v[112:115]
	v_mfma_f32_16x16x32_bf16 v[108:111], v[184:187], v[216:219], v[108:111]
	v_mfma_f32_16x16x32_bf16 v[104:107], v[192:195], v[216:219], v[104:107]
	v_mfma_f32_16x16x32_bf16 v[100:103], v[184:187], v[224:227], v[100:103]
	v_mfma_f32_16x16x32_bf16 v[96:99], v[192:195], v[224:227], v[96:99]
	s_barrier
	v_readfirstlane_b32 s1, v167
	v_add_u32_e32 v254, 0x2000, v167
	v_lshl_add_u64 v[252:253], v[248:249], 0, s[34:35]
	s_mov_b32 m0, s1
	v_readfirstlane_b32 s1, v254
	ds_read_b128 v[228:231], v162
	ds_read_b128 v[232:235], v162 offset:1024
	ds_read_b128 v[236:239], v162 offset:2048
	ds_read_b128 v[240:243], v162 offset:3072
	global_load_lds_dwordx4 v[252:253], off
	v_lshl_add_u64 v[252:253], v[250:251], 0, s[34:35]
	s_mov_b32 m0, s1
	s_nop 0
	global_load_lds_dwordx4 v[252:253], off
	s_barrier
	s_waitcnt lgkmcnt(0)
	v_mfma_f32_16x16x32_bf16 v[92:95], v[228:231], v[196:199], v[92:95]
	v_mfma_f32_16x16x32_bf16 v[88:91], v[236:239], v[196:199], v[88:91]
	v_mfma_f32_16x16x32_bf16 v[84:87], v[228:231], v[204:207], v[84:87]
	v_mfma_f32_16x16x32_bf16 v[80:83], v[236:239], v[204:207], v[80:83]
	v_mfma_f32_16x16x32_bf16 v[76:79], v[228:231], v[212:215], v[76:79]
	v_mfma_f32_16x16x32_bf16 v[72:75], v[236:239], v[212:215], v[72:75]
	v_mfma_f32_16x16x32_bf16 v[68:71], v[228:231], v[220:223], v[68:71]
	v_mfma_f32_16x16x32_bf16 v[64:67], v[236:239], v[220:223], v[64:67]
	v_mfma_f32_16x16x32_bf16 v[92:95], v[232:235], v[200:203], v[92:95]
	v_mfma_f32_16x16x32_bf16 v[88:91], v[240:243], v[200:203], v[88:91]
	v_mfma_f32_16x16x32_bf16 v[84:87], v[232:235], v[208:211], v[84:87]
	v_mfma_f32_16x16x32_bf16 v[80:83], v[240:243], v[208:211], v[80:83]
	v_mfma_f32_16x16x32_bf16 v[76:79], v[232:235], v[216:219], v[76:79]
	v_mfma_f32_16x16x32_bf16 v[72:75], v[240:243], v[216:219], v[72:75]
	v_mfma_f32_16x16x32_bf16 v[68:71], v[232:235], v[224:227], v[68:71]
	v_mfma_f32_16x16x32_bf16 v[64:67], v[240:243], v[224:227], v[64:67]
	v_readfirstlane_b32 s1, v168
	v_lshl_add_u64 v[244:245], v[244:245], 0, s[36:37]
	s_mov_b32 m0, s1
	v_readfirstlane_b32 s1, v170
	s_barrier
	ds_read_b128 v[196:199], v161 offset:49152
	ds_read_b128 v[200:203], v161 offset:50176
	ds_read_b128 v[204:207], v160 offset:49152
	ds_read_b128 v[208:211], v160 offset:50176
	ds_read_b128 v[212:215], v159 offset:49152
	ds_read_b128 v[216:219], v159 offset:50176
	ds_read_b128 v[220:223], v158 offset:49152
	ds_read_b128 v[224:227], v158 offset:50176
	global_load_lds_dwordx4 v[244:245], off
	v_lshl_add_u64 v[244:245], v[246:247], 0, s[36:37]
	s_mov_b32 m0, s1
	s_nop 0
	global_load_lds_dwordx4 v[244:245], off
	s_barrier
	s_waitcnt lgkmcnt(0)
	v_mfma_f32_16x16x32_bf16 v[60:63], v[180:183], v[196:199], v[60:63]
	v_mfma_f32_16x16x32_bf16 v[56:59], v[188:191], v[196:199], v[56:59]
	v_mfma_f32_16x16x32_bf16 v[52:55], v[180:183], v[204:207], v[52:55]
	v_mfma_f32_16x16x32_bf16 v[48:51], v[188:191], v[204:207], v[48:51]
	v_mfma_f32_16x16x32_bf16 v[44:47], v[180:183], v[212:215], v[44:47]
	v_mfma_f32_16x16x32_bf16 v[40:43], v[188:191], v[212:215], v[40:43]
	v_mfma_f32_16x16x32_bf16 v[36:39], v[180:183], v[220:223], v[36:39]
	v_mfma_f32_16x16x32_bf16 v[32:35], v[188:191], v[220:223], v[32:35]
	v_mfma_f32_16x16x32_bf16 v[60:63], v[184:187], v[200:203], v[60:63]
	v_mfma_f32_16x16x32_bf16 v[56:59], v[192:195], v[200:203], v[56:59]
	v_mfma_f32_16x16x32_bf16 v[52:55], v[184:187], v[208:211], v[52:55]
	v_mfma_f32_16x16x32_bf16 v[48:51], v[192:195], v[208:211], v[48:51]
	v_mfma_f32_16x16x32_bf16 v[44:47], v[184:187], v[216:219], v[44:47]
	v_mfma_f32_16x16x32_bf16 v[40:43], v[192:195], v[216:219], v[40:43]
	v_mfma_f32_16x16x32_bf16 v[36:39], v[184:187], v[224:227], v[36:39]
	v_mfma_f32_16x16x32_bf16 v[32:35], v[192:195], v[224:227], v[32:35]
	s_barrier
	v_readfirstlane_b32 s1, v171
	v_add_u32_e32 v182, 0x2000, v171
	v_lshl_add_u64 v[180:181], v[248:249], 0, s[38:39]
	s_mov_b32 m0, s1
	v_readfirstlane_b32 s1, v182
	global_load_lds_dwordx4 v[180:181], off
	v_lshl_add_u64 v[180:181], v[250:251], 0, s[38:39]
	s_mov_b32 m0, s1
	s_nop 0
	global_load_lds_dwordx4 v[180:181], off
	s_waitcnt vmcnt(6)
	s_barrier
	v_mfma_f32_16x16x32_bf16 v[28:31], v[228:231], v[196:199], v[28:31]
	v_mfma_f32_16x16x32_bf16 v[24:27], v[236:239], v[196:199], v[24:27]
	v_mfma_f32_16x16x32_bf16 v[20:23], v[228:231], v[204:207], v[20:23]
	v_mfma_f32_16x16x32_bf16 v[16:19], v[236:239], v[204:207], v[16:19]
	v_mfma_f32_16x16x32_bf16 v[12:15], v[228:231], v[212:215], v[12:15]
	v_mfma_f32_16x16x32_bf16 v[8:11], v[236:239], v[212:215], v[8:11]
	v_mfma_f32_16x16x32_bf16 v[4:7], v[228:231], v[220:223], v[4:7]
	v_mfma_f32_16x16x32_bf16 v[0:3], v[236:239], v[220:223], v[0:3]
	v_mfma_f32_16x16x32_bf16 v[28:31], v[232:235], v[200:203], v[28:31]
	v_mfma_f32_16x16x32_bf16 v[24:27], v[240:243], v[200:203], v[24:27]
	v_mfma_f32_16x16x32_bf16 v[20:23], v[232:235], v[208:211], v[20:23]
	v_mfma_f32_16x16x32_bf16 v[16:19], v[240:243], v[208:211], v[16:19]
	v_mfma_f32_16x16x32_bf16 v[12:15], v[232:235], v[216:219], v[12:15]
	v_mfma_f32_16x16x32_bf16 v[8:11], v[240:243], v[216:219], v[8:11]
	v_mfma_f32_16x16x32_bf16 v[4:7], v[232:235], v[224:227], v[4:7]
	v_mfma_f32_16x16x32_bf16 v[0:3], v[240:243], v[224:227], v[0:3]
	s_add_i32 s0, s0, 2
	v_lshl_add_u64 v[142:143], v[142:143], 0, s[46:47]
	v_lshl_add_u64 v[144:145], v[144:145], 0, s[46:47]
	v_lshl_add_u64 v[146:147], v[146:147], 0, s[46:47]
	s_cmp_lt_u32 s0, 12
	v_lshl_add_u64 v[148:149], v[148:149], 0, s[46:47]
	s_barrier
	s_cbranch_scc1 .LBB0_1842
	s_or_b32 s0, s8, 0x80
	s_ashr_i32 s1, s0, 31
	s_lshl_b64 s[0:1], s[0:1], 11
	s_add_u32 s0, s45, s0
	s_addc_u32 s1, s64, s1
	v_lshl_add_u64 v[170:171], s[0:1], 0, v[130:131]
	v_lshl_add_u64 v[138:139], v[138:139], 1, v[170:171]
	v_readfirstlane_b32 s2, v178
	v_lshl_add_u64 v[138:139], v[138:139], 0, s[58:59]
	s_mov_b32 m0, s2
	ds_read_b128 v[142:145], v172
	ds_read_b128 v[146:149], v172 offset:1024
	ds_read_b128 v[180:183], v172 offset:2048
	ds_read_b128 v[184:187], v172 offset:3072
	ds_read_b128 v[188:191], v161
	ds_read_b128 v[192:195], v161 offset:1024
	ds_read_b128 v[196:199], v160
	ds_read_b128 v[200:203], v160 offset:1024
	ds_read_b128 v[204:207], v159
	ds_read_b128 v[208:211], v159 offset:1024
	ds_read_b128 v[212:215], v158
	ds_read_b128 v[216:219], v158 offset:1024
	global_load_lds_dwordx4 v[138:139], off
	v_lshl_add_u64 v[138:139], s[0:1], 0, v[134:135]
	v_lshl_add_u64 v[138:139], v[140:141], 1, v[138:139]
	v_readfirstlane_b32 s0, v179
	v_lshl_add_u64 v[138:139], v[138:139], 0, s[58:59]
	s_mov_b32 m0, s0
	v_readlane_b32 s0, v255, 11
	global_load_lds_dwordx4 v[138:139], off
	s_add_i32 s79, s79, s0
	s_barrier
	s_waitcnt lgkmcnt(0)
	s_cmpk_gt_i32 s79, 0x54
	s_cselect_b64 s[60:61], -1, 0
	s_waitcnt lgkmcnt(0)
	v_mfma_f32_16x16x32_bf16 v[124:127], v[142:145], v[188:191], v[124:127]
	v_mfma_f32_16x16x32_bf16 v[116:119], v[142:145], v[196:199], v[116:119]
	v_mfma_f32_16x16x32_bf16 v[108:111], v[142:145], v[204:207], v[108:111]
	v_mfma_f32_16x16x32_bf16 v[100:103], v[142:145], v[212:215], v[100:103]
	v_mfma_f32_16x16x32_bf16 v[124:127], v[146:149], v[192:195], v[124:127]
	v_mfma_f32_16x16x32_bf16 v[120:123], v[180:183], v[188:191], v[120:123]
	v_mfma_f32_16x16x32_bf16 v[116:119], v[146:149], v[200:203], v[116:119]
	v_mfma_f32_16x16x32_bf16 v[112:115], v[180:183], v[196:199], v[112:115]
	v_mfma_f32_16x16x32_bf16 v[108:111], v[146:149], v[208:211], v[108:111]
	v_mfma_f32_16x16x32_bf16 v[104:107], v[180:183], v[204:207], v[104:107]
	v_mfma_f32_16x16x32_bf16 v[100:103], v[146:149], v[216:219], v[100:103]
	v_mfma_f32_16x16x32_bf16 v[96:99], v[180:183], v[212:215], v[96:99]
	v_mfma_f32_16x16x32_bf16 v[138:141], v[184:187], v[192:195], v[120:123]
	v_mfma_f32_16x16x32_bf16 v[220:223], v[184:187], v[200:203], v[112:115]
	v_mfma_f32_16x16x32_bf16 v[224:227], v[184:187], v[208:211], v[104:107]
	v_mfma_f32_16x16x32_bf16 v[228:231], v[184:187], v[216:219], v[96:99]
	s_barrier
	s_nop 1
	ds_read_b128 v[96:99], v169
	ds_read_b128 v[104:107], v169 offset:1024
	ds_read_b128 v[112:115], v169 offset:2048
	ds_read_b128 v[120:123], v169 offset:3072
	s_barrier
	s_waitcnt lgkmcnt(0)
	v_mfma_f32_16x16x32_bf16 v[92:95], v[96:99], v[188:191], v[92:95]
	v_mfma_f32_16x16x32_bf16 v[88:91], v[112:115], v[188:191], v[88:91]
	v_mfma_f32_16x16x32_bf16 v[84:87], v[96:99], v[196:199], v[84:87]
	v_mfma_f32_16x16x32_bf16 v[80:83], v[112:115], v[196:199], v[80:83]
	v_mfma_f32_16x16x32_bf16 v[76:79], v[96:99], v[204:207], v[76:79]
	v_mfma_f32_16x16x32_bf16 v[72:75], v[112:115], v[204:207], v[72:75]
	v_mfma_f32_16x16x32_bf16 v[68:71], v[96:99], v[212:215], v[68:71]
	v_mfma_f32_16x16x32_bf16 v[64:67], v[112:115], v[212:215], v[64:67]
	v_mfma_f32_16x16x32_bf16 v[92:95], v[104:107], v[192:195], v[92:95]
	v_mfma_f32_16x16x32_bf16 v[88:91], v[120:123], v[192:195], v[88:91]
	v_mfma_f32_16x16x32_bf16 v[84:87], v[104:107], v[200:203], v[84:87]
	v_mfma_f32_16x16x32_bf16 v[80:83], v[120:123], v[200:203], v[80:83]
	v_mfma_f32_16x16x32_bf16 v[76:79], v[104:107], v[208:211], v[76:79]
	v_mfma_f32_16x16x32_bf16 v[72:75], v[120:123], v[208:211], v[72:75]
	v_mfma_f32_16x16x32_bf16 v[68:71], v[104:107], v[216:219], v[68:71]
	v_mfma_f32_16x16x32_bf16 v[64:67], v[120:123], v[216:219], v[64:67]
	s_barrier
	ds_read_b128 v[168:171], v161 offset:16384
	ds_read_b128 v[188:191], v161 offset:17408
	ds_read_b128 v[192:195], v160 offset:16384
	ds_read_b128 v[196:199], v160 offset:17408
	ds_read_b128 v[200:203], v159 offset:16384
	ds_read_b128 v[204:207], v159 offset:17408
	ds_read_b128 v[208:211], v158 offset:16384
	ds_read_b128 v[212:215], v158 offset:17408
	s_waitcnt vmcnt(4)
	s_barrier
	s_waitcnt lgkmcnt(0)
	v_mfma_f32_16x16x32_bf16 v[60:63], v[142:145], v[168:171], v[60:63]
	v_mfma_f32_16x16x32_bf16 v[52:55], v[142:145], v[192:195], v[52:55]
	v_mfma_f32_16x16x32_bf16 v[44:47], v[142:145], v[200:203], v[44:47]
	v_mfma_f32_16x16x32_bf16 v[36:39], v[142:145], v[208:211], v[36:39]
	v_mfma_f32_16x16x32_bf16 v[60:63], v[146:149], v[188:191], v[60:63]
	v_mfma_f32_16x16x32_bf16 v[56:59], v[180:183], v[168:171], v[56:59]
	v_mfma_f32_16x16x32_bf16 v[52:55], v[146:149], v[196:199], v[52:55]
	v_mfma_f32_16x16x32_bf16 v[48:51], v[180:183], v[192:195], v[48:51]
	v_mfma_f32_16x16x32_bf16 v[44:47], v[146:149], v[204:207], v[44:47]
	v_mfma_f32_16x16x32_bf16 v[40:43], v[180:183], v[200:203], v[40:43]
	v_mfma_f32_16x16x32_bf16 v[36:39], v[146:149], v[212:215], v[36:39]
	v_mfma_f32_16x16x32_bf16 v[32:35], v[180:183], v[208:211], v[32:35]
	v_mfma_f32_16x16x32_bf16 v[216:219], v[184:187], v[188:191], v[56:59]
	v_mfma_f32_16x16x32_bf16 v[232:235], v[184:187], v[196:199], v[48:51]
	v_mfma_f32_16x16x32_bf16 v[236:239], v[184:187], v[204:207], v[40:43]
	v_mfma_f32_16x16x32_bf16 v[142:145], v[184:187], v[212:215], v[32:35]
	v_mfma_f32_16x16x32_bf16 v[28:31], v[96:99], v[168:171], v[28:31]
	v_mfma_f32_16x16x32_bf16 v[24:27], v[112:115], v[168:171], v[24:27]
	v_mfma_f32_16x16x32_bf16 v[20:23], v[96:99], v[192:195], v[20:23]
	v_mfma_f32_16x16x32_bf16 v[16:19], v[112:115], v[192:195], v[16:19]
	v_mfma_f32_16x16x32_bf16 v[12:15], v[96:99], v[200:203], v[12:15]
	v_mfma_f32_16x16x32_bf16 v[8:11], v[112:115], v[200:203], v[8:11]
	v_mfma_f32_16x16x32_bf16 v[4:7], v[96:99], v[208:211], v[4:7]
	v_mfma_f32_16x16x32_bf16 v[0:3], v[112:115], v[208:211], v[0:3]
	v_mfma_f32_16x16x32_bf16 v[28:31], v[104:107], v[188:191], v[28:31]
	v_mfma_f32_16x16x32_bf16 v[24:27], v[120:123], v[188:191], v[24:27]
	v_mfma_f32_16x16x32_bf16 v[20:23], v[104:107], v[196:199], v[20:23]
	v_mfma_f32_16x16x32_bf16 v[16:19], v[120:123], v[196:199], v[16:19]
	v_mfma_f32_16x16x32_bf16 v[12:15], v[104:107], v[204:207], v[12:15]
	v_mfma_f32_16x16x32_bf16 v[8:11], v[120:123], v[204:207], v[8:11]
	v_mfma_f32_16x16x32_bf16 v[4:7], v[104:107], v[212:215], v[4:7]
	v_mfma_f32_16x16x32_bf16 v[0:3], v[120:123], v[212:215], v[0:3]
	s_barrier
	ds_read_b128 v[32:35], v163
	ds_read_b128 v[146:149], v163 offset:1024
	ds_read_b128 v[168:171], v163 offset:2048
	ds_read_b128 v[178:181], v163 offset:3072
	ds_read_b128 v[40:43], v161 offset:32768
	ds_read_b128 v[48:51], v161 offset:33792
	ds_read_b128 v[56:59], v160 offset:32768
	ds_read_b128 v[182:185], v160 offset:33792
	ds_read_b128 v[186:189], v159 offset:32768
	ds_read_b128 v[190:193], v159 offset:33792
	ds_read_b128 v[194:197], v158 offset:32768
	ds_read_b128 v[198:201], v158 offset:33792
	s_waitcnt vmcnt(2)
	s_barrier
	s_waitcnt lgkmcnt(0)
	v_mfma_f32_16x16x32_bf16 v[96:99], v[32:35], v[40:43], v[124:127]
	v_mfma_f32_16x16x32_bf16 v[120:123], v[146:149], v[48:51], v[96:99]
	v_mfma_f32_16x16x32_bf16 v[96:99], v[168:171], v[40:43], v[138:141]
	v_mfma_f32_16x16x32_bf16 v[124:127], v[178:181], v[48:51], v[96:99]
	v_mfma_f32_16x16x32_bf16 v[96:99], v[32:35], v[56:59], v[116:119]
	v_mfma_f32_16x16x32_bf16 v[112:115], v[146:149], v[182:185], v[96:99]
	v_mfma_f32_16x16x32_bf16 v[96:99], v[168:171], v[56:59], v[220:223]
	v_mfma_f32_16x16x32_bf16 v[116:119], v[178:181], v[182:185], v[96:99]
	v_mfma_f32_16x16x32_bf16 v[96:99], v[32:35], v[186:189], v[108:111]
	v_mfma_f32_16x16x32_bf16 v[104:107], v[146:149], v[190:193], v[96:99]
	v_mfma_f32_16x16x32_bf16 v[96:99], v[168:171], v[186:189], v[224:227]
	v_mfma_f32_16x16x32_bf16 v[108:111], v[178:181], v[190:193], v[96:99]
	v_mfma_f32_16x16x32_bf16 v[96:99], v[32:35], v[194:197], v[100:103]
	v_mfma_f32_16x16x32_bf16 v[100:103], v[168:171], v[194:197], v[228:231]
	v_mfma_f32_16x16x32_bf16 v[96:99], v[146:149], v[198:201], v[96:99]
	v_mfma_f32_16x16x32_bf16 v[100:103], v[178:181], v[198:201], v[100:103]
	s_barrier
	ds_read_b128 v[138:141], v162
	ds_read_b128 v[202:205], v162 offset:1024
	ds_read_b128 v[206:209], v162 offset:2048
	ds_read_b128 v[210:213], v162 offset:3072
	s_waitcnt vmcnt(0)
	s_barrier
	s_waitcnt lgkmcnt(0)
	v_mfma_f32_16x16x32_bf16 v[92:95], v[138:141], v[40:43], v[92:95]
	v_mfma_f32_16x16x32_bf16 v[40:43], v[206:209], v[40:43], v[88:91]
	v_mfma_f32_16x16x32_bf16 v[88:91], v[210:213], v[48:51], v[40:43]
	v_mfma_f32_16x16x32_bf16 v[40:43], v[138:141], v[56:59], v[84:87]
	v_mfma_f32_16x16x32_bf16 v[84:87], v[202:205], v[182:185], v[40:43]
	v_mfma_f32_16x16x32_bf16 v[40:43], v[206:209], v[56:59], v[80:83]
	v_mfma_f32_16x16x32_bf16 v[80:83], v[210:213], v[182:185], v[40:43]
	v_mfma_f32_16x16x32_bf16 v[40:43], v[138:141], v[186:189], v[76:79]
	v_mfma_f32_16x16x32_bf16 v[76:79], v[202:205], v[190:193], v[40:43]
	v_mfma_f32_16x16x32_bf16 v[40:43], v[206:209], v[186:189], v[72:75]
	v_mfma_f32_16x16x32_bf16 v[72:75], v[210:213], v[190:193], v[40:43]
	v_mfma_f32_16x16x32_bf16 v[40:43], v[138:141], v[194:197], v[68:71]
	v_mfma_f32_16x16x32_bf16 v[68:71], v[202:205], v[198:201], v[40:43]
	v_mfma_f32_16x16x32_bf16 v[40:43], v[206:209], v[194:197], v[64:67]
	v_mfma_f32_16x16x32_bf16 v[92:95], v[202:205], v[48:51], v[92:95]
	v_mfma_f32_16x16x32_bf16 v[64:67], v[210:213], v[198:201], v[40:43]
	s_barrier
	ds_read_b128 v[182:185], v161 offset:49152
	ds_read_b128 v[186:189], v161 offset:50176
	ds_read_b128 v[190:193], v160 offset:49152
	ds_read_b128 v[160:163], v160 offset:50176
	ds_read_b128 v[194:197], v159 offset:49152
	ds_read_b128 v[198:201], v159 offset:50176
	ds_read_b128 v[220:223], v158 offset:49152
	ds_read_b128 v[224:227], v158 offset:50176
	s_barrier
	s_waitcnt lgkmcnt(0)
	v_mfma_f32_16x16x32_bf16 v[40:43], v[32:35], v[182:185], v[60:63]
	v_mfma_f32_16x16x32_bf16 v[56:59], v[146:149], v[186:189], v[40:43]
	v_mfma_f32_16x16x32_bf16 v[40:43], v[168:171], v[182:185], v[216:219]
	v_mfma_f32_16x16x32_bf16 v[60:63], v[178:181], v[186:189], v[40:43]
	v_mfma_f32_16x16x32_bf16 v[40:43], v[32:35], v[190:193], v[52:55]
	v_mfma_f32_16x16x32_bf16 v[48:51], v[146:149], v[160:163], v[40:43]
	v_mfma_f32_16x16x32_bf16 v[40:43], v[168:171], v[190:193], v[232:235]
	v_mfma_f32_16x16x32_bf16 v[52:55], v[178:181], v[160:163], v[40:43]
	v_mfma_f32_16x16x32_bf16 v[40:43], v[32:35], v[194:197], v[44:47]
	v_mfma_f32_16x16x32_bf16 v[44:47], v[168:171], v[194:197], v[236:239]
	v_mfma_f32_16x16x32_bf16 v[32:35], v[32:35], v[220:223], v[36:39]
	v_mfma_f32_16x16x32_bf16 v[36:39], v[168:171], v[220:223], v[142:145]
	v_mfma_f32_16x16x32_bf16 v[40:43], v[146:149], v[198:201], v[40:43]
	v_mfma_f32_16x16x32_bf16 v[44:47], v[178:181], v[198:201], v[44:47]
	v_mfma_f32_16x16x32_bf16 v[32:35], v[146:149], v[224:227], v[32:35]
	v_mfma_f32_16x16x32_bf16 v[36:39], v[178:181], v[224:227], v[36:39]
	v_mfma_f32_16x16x32_bf16 v[28:31], v[138:141], v[182:185], v[28:31]
	v_mfma_f32_16x16x32_bf16 v[24:27], v[206:209], v[182:185], v[24:27]
	v_mfma_f32_16x16x32_bf16 v[20:23], v[138:141], v[190:193], v[20:23]
	v_mfma_f32_16x16x32_bf16 v[16:19], v[206:209], v[190:193], v[16:19]
	v_mfma_f32_16x16x32_bf16 v[12:15], v[138:141], v[194:197], v[12:15]
	v_mfma_f32_16x16x32_bf16 v[8:11], v[206:209], v[194:197], v[8:11]
	v_mfma_f32_16x16x32_bf16 v[4:7], v[138:141], v[220:223], v[4:7]
	v_mfma_f32_16x16x32_bf16 v[0:3], v[206:209], v[220:223], v[0:3]
	v_mfma_f32_16x16x32_bf16 v[28:31], v[202:205], v[186:189], v[28:31]
	v_mfma_f32_16x16x32_bf16 v[24:27], v[210:213], v[186:189], v[24:27]
	v_mfma_f32_16x16x32_bf16 v[20:23], v[202:205], v[160:163], v[20:23]
	v_mfma_f32_16x16x32_bf16 v[16:19], v[210:213], v[160:163], v[16:19]
	v_mfma_f32_16x16x32_bf16 v[12:15], v[202:205], v[198:201], v[12:15]
	v_mfma_f32_16x16x32_bf16 v[8:11], v[210:213], v[198:201], v[8:11]
	v_mfma_f32_16x16x32_bf16 v[4:7], v[202:205], v[224:227], v[4:7]
	v_mfma_f32_16x16x32_bf16 v[0:3], v[210:213], v[224:227], v[0:3]
	s_and_b64 vcc, exec, s[60:61]
	s_barrier
	s_cbranch_vccnz .LBB0_1845
	s_mul_hi_i32 s0, s79, 0x66666667
	s_lshr_b32 s1, s0, 31
	s_ashr_i32 s0, s0, 1
	s_add_i32 s0, s0, s1
	v_readlane_b32 s1, v255, 15
	s_add_i32 s1, s0, s1
	s_mul_i32 s0, s0, 5
	s_sub_i32 s0, s79, s0
	v_readlane_b32 s2, v255, 14
	s_add_i32 s2, s0, s2
	s_lshl_b32 s4, s2, 8
	s_ashr_i32 s5, s4, 31
	s_lshl_b32 s0, s1, 8
	s_lshl_b64 s[10:11], s[4:5], 11
	s_add_u32 s10, s65, s10
	s_addc_u32 s11, s66, s11
	v_lshl_add_u64 v[138:139], s[10:11], 0, v[130:131]
	v_readfirstlane_b32 s1, v153
	v_lshl_add_u64 v[138:139], v[138:139], 0, v[132:133]
	s_mov_b32 m0, s1
	v_readfirstlane_b32 s1, v173
	global_load_lds_dwordx4 v[138:139], off
	s_mov_b32 m0, s1
	s_ashr_i32 s1, s0, 31
	v_lshl_add_u64 v[138:139], s[10:11], 0, v[134:135]
	s_lshl_b64 s[10:11], s[0:1], 11
	s_add_u32 s10, s45, s10
	v_lshl_add_u64 v[138:139], v[138:139], 0, v[136:137]
	s_addc_u32 s11, s64, s11
	s_bitset1_b32 s4, 7
	global_load_lds_dwordx4 v[138:139], off
	v_lshl_add_u64 v[138:139], s[10:11], 0, v[130:131]
	v_readfirstlane_b32 s1, v152
	s_ashr_i32 s5, s4, 31
	v_lshl_add_u64 v[138:139], v[138:139], 0, v[132:133]
	s_mov_b32 m0, s1
	s_lshl_b64 s[4:5], s[4:5], 11
	global_load_lds_dwordx4 v[138:139], off
	v_lshl_add_u64 v[138:139], s[10:11], 0, v[134:135]
	v_readfirstlane_b32 s1, v174
	s_add_u32 s4, s65, s4
	v_lshl_add_u64 v[138:139], v[138:139], 0, v[136:137]
	s_mov_b32 m0, s1
	s_addc_u32 s5, s66, s5
	global_load_lds_dwordx4 v[138:139], off
	v_lshl_add_u64 v[138:139], s[4:5], 0, v[130:131]
	v_readfirstlane_b32 s1, v151
	v_lshl_add_u64 v[138:139], v[138:139], 0, v[132:133]
	s_mov_b32 m0, s1
	v_readfirstlane_b32 s1, v175
	s_bitset1_b32 s0, 7
	global_load_lds_dwordx4 v[138:139], off
	s_mov_b32 m0, s1
	s_ashr_i32 s1, s0, 31
	s_lshl_b64 s[0:1], s[0:1], 11
	s_add_u32 s0, s45, s0
	v_lshl_add_u64 v[138:139], s[4:5], 0, v[134:135]
	s_addc_u32 s1, s64, s1
	v_lshl_add_u64 v[138:139], v[138:139], 0, v[136:137]
	v_lshl_add_u64 v[130:131], s[0:1], 0, v[130:131]
	v_readfirstlane_b32 s2, v176
	global_load_lds_dwordx4 v[138:139], off
	v_lshl_add_u64 v[130:131], v[130:131], 0, v[132:133]
	s_mov_b32 m0, s2
	s_nop 0
	global_load_lds_dwordx4 v[130:131], off
	v_lshl_add_u64 v[130:131], s[0:1], 0, v[134:135]
	v_readfirstlane_b32 s0, v177
	v_lshl_add_u64 v[130:131], v[130:131], 0, v[136:137]
	s_mov_b32 m0, s0
	s_nop 0
	global_load_lds_dwordx4 v[130:131], off

.LBB0_2799:
	ds_read_b128 v[182:185], v180
	ds_read_b128 v[186:189], v180 offset:1024
	ds_read_b128 v[190:193], v180 offset:2048
	ds_read_b128 v[194:197], v180 offset:3072
	v_add_u32_e32 v0, 0xc000, v162
	v_lshl_add_u64 v[246:247], v[142:143], 0, s[48:49]
	v_readfirstlane_b32 s4, v0
	v_lshl_add_u64 v[2:3], v[246:247], 0, s[20:21]
	s_mov_b32 m0, s4
	ds_read_b128 v[198:201], v161
	ds_read_b128 v[202:205], v161 offset:1024
	ds_read_b128 v[206:209], v160
	ds_read_b128 v[210:213], v160 offset:1024
	ds_read_b128 v[214:217], v159
	ds_read_b128 v[218:221], v159 offset:1024
	ds_read_b128 v[222:225], v158
	ds_read_b128 v[226:229], v158 offset:1024
	global_load_lds_dwordx4 v[2:3], off
	v_add_u32_e32 v2, 0xe000, v162
	v_lshl_add_u64 v[248:249], v[144:145], 0, s[48:49]
	v_readfirstlane_b32 s4, v2
	v_lshl_add_u64 v[230:231], v[248:249], 0, s[20:21]
	s_mov_b32 m0, s4
	s_nop 0
	global_load_lds_dwordx4 v[230:231], off
	s_waitcnt lgkmcnt(8)
	s_barrier
	s_waitcnt lgkmcnt(0)
	v_mfma_f32_16x16x32_bf16 v[128:131], v[182:185], v[198:201], v[128:131]
	v_mfma_f32_16x16x32_bf16 v[124:127], v[190:193], v[198:201], v[124:127]
	v_mfma_f32_16x16x32_bf16 v[120:123], v[182:185], v[206:209], v[120:123]
	v_mfma_f32_16x16x32_bf16 v[116:119], v[190:193], v[206:209], v[116:119]
	v_mfma_f32_16x16x32_bf16 v[112:115], v[182:185], v[214:217], v[112:115]
	v_mfma_f32_16x16x32_bf16 v[108:111], v[190:193], v[214:217], v[108:111]
	v_mfma_f32_16x16x32_bf16 v[104:107], v[182:185], v[222:225], v[104:107]
	v_mfma_f32_16x16x32_bf16 v[100:103], v[190:193], v[222:225], v[100:103]
	v_mfma_f32_16x16x32_bf16 v[128:131], v[186:189], v[202:205], v[128:131]
	v_mfma_f32_16x16x32_bf16 v[124:127], v[194:197], v[202:205], v[124:127]
	v_mfma_f32_16x16x32_bf16 v[120:123], v[186:189], v[210:213], v[120:123]
	v_mfma_f32_16x16x32_bf16 v[116:119], v[194:197], v[210:213], v[116:119]
	v_mfma_f32_16x16x32_bf16 v[112:115], v[186:189], v[218:221], v[112:115]
	v_mfma_f32_16x16x32_bf16 v[108:111], v[194:197], v[218:221], v[108:111]
	v_mfma_f32_16x16x32_bf16 v[104:107], v[186:189], v[226:229], v[104:107]
	v_mfma_f32_16x16x32_bf16 v[100:103], v[194:197], v[226:229], v[100:103]
	s_barrier
	v_lshl_add_u64 v[250:251], v[138:139], 0, s[48:49]
	v_readfirstlane_b32 s4, v147
	v_lshl_add_u64 v[252:253], v[250:251], 0, s[24:25]
	s_mov_b32 m0, s4
	v_add_u32_e32 v3, 0x2000, v147
	ds_read_b128 v[230:233], v178
	ds_read_b128 v[234:237], v178 offset:1024
	ds_read_b128 v[238:241], v178 offset:2048
	ds_read_b128 v[242:245], v178 offset:3072
	global_load_lds_dwordx4 v[252:253], off
	v_lshl_add_u64 v[252:253], v[140:141], 0, s[48:49]
	v_readfirstlane_b32 s4, v3
	v_lshl_add_u64 v[132:133], v[252:253], 0, s[24:25]
	s_mov_b32 m0, s4
	s_add_i32 s4, s2, 2
	global_load_lds_dwordx4 v[132:133], off
	s_barrier
	s_waitcnt lgkmcnt(0)
	v_mfma_f32_16x16x32_bf16 v[96:99], v[230:233], v[198:201], v[96:99]
	v_mfma_f32_16x16x32_bf16 v[92:95], v[238:241], v[198:201], v[92:95]
	v_mfma_f32_16x16x32_bf16 v[88:91], v[230:233], v[206:209], v[88:91]
	v_mfma_f32_16x16x32_bf16 v[84:87], v[238:241], v[206:209], v[84:87]
	v_mfma_f32_16x16x32_bf16 v[80:83], v[230:233], v[214:217], v[80:83]
	v_mfma_f32_16x16x32_bf16 v[76:79], v[238:241], v[214:217], v[76:79]
	v_mfma_f32_16x16x32_bf16 v[72:75], v[230:233], v[222:225], v[72:75]
	v_mfma_f32_16x16x32_bf16 v[68:71], v[238:241], v[222:225], v[68:71]
	v_mfma_f32_16x16x32_bf16 v[96:99], v[234:237], v[202:205], v[96:99]
	v_mfma_f32_16x16x32_bf16 v[92:95], v[242:245], v[202:205], v[92:95]
	v_mfma_f32_16x16x32_bf16 v[88:91], v[234:237], v[210:213], v[88:91]
	v_mfma_f32_16x16x32_bf16 v[84:87], v[242:245], v[210:213], v[84:87]
	v_mfma_f32_16x16x32_bf16 v[80:83], v[234:237], v[218:221], v[80:83]
	v_mfma_f32_16x16x32_bf16 v[76:79], v[242:245], v[218:221], v[76:79]
	v_mfma_f32_16x16x32_bf16 v[72:75], v[234:237], v[226:229], v[72:75]
	v_mfma_f32_16x16x32_bf16 v[68:71], v[242:245], v[226:229], v[68:71]
	v_readfirstlane_b32 s5, v162
	v_lshl_add_u64 v[132:133], v[246:247], 0, s[26:27]
	s_mov_b32 m0, s5
	v_readfirstlane_b32 s5, v163
	s_barrier
	ds_read_b128 v[198:201], v161 offset:16384
	ds_read_b128 v[202:205], v161 offset:17408
	ds_read_b128 v[206:209], v160 offset:16384
	ds_read_b128 v[210:213], v160 offset:17408
	ds_read_b128 v[214:217], v159 offset:16384
	ds_read_b128 v[218:221], v159 offset:17408
	ds_read_b128 v[222:225], v158 offset:16384
	ds_read_b128 v[226:229], v158 offset:17408
	global_load_lds_dwordx4 v[132:133], off
	v_lshl_add_u64 v[132:133], v[248:249], 0, s[26:27]
	s_mov_b32 m0, s5
	s_nop 0
	global_load_lds_dwordx4 v[132:133], off
	s_barrier
	s_waitcnt lgkmcnt(0)
	v_mfma_f32_16x16x32_bf16 v[64:67], v[182:185], v[198:201], v[64:67]
	v_mfma_f32_16x16x32_bf16 v[60:63], v[190:193], v[198:201], v[60:63]
	v_mfma_f32_16x16x32_bf16 v[56:59], v[182:185], v[206:209], v[56:59]
	v_mfma_f32_16x16x32_bf16 v[52:55], v[190:193], v[206:209], v[52:55]
	v_mfma_f32_16x16x32_bf16 v[48:51], v[182:185], v[214:217], v[48:51]
	v_mfma_f32_16x16x32_bf16 v[44:47], v[190:193], v[214:217], v[44:47]
	v_mfma_f32_16x16x32_bf16 v[40:43], v[182:185], v[222:225], v[40:43]
	v_mfma_f32_16x16x32_bf16 v[36:39], v[190:193], v[222:225], v[36:39]
	v_mfma_f32_16x16x32_bf16 v[64:67], v[186:189], v[202:205], v[64:67]
	v_mfma_f32_16x16x32_bf16 v[60:63], v[194:197], v[202:205], v[60:63]
	v_mfma_f32_16x16x32_bf16 v[56:59], v[186:189], v[210:213], v[56:59]
	v_mfma_f32_16x16x32_bf16 v[52:55], v[194:197], v[210:213], v[52:55]
	v_mfma_f32_16x16x32_bf16 v[48:51], v[186:189], v[218:221], v[48:51]
	v_mfma_f32_16x16x32_bf16 v[44:47], v[194:197], v[218:221], v[44:47]
	v_mfma_f32_16x16x32_bf16 v[40:43], v[186:189], v[226:229], v[40:43]
	v_mfma_f32_16x16x32_bf16 v[36:39], v[194:197], v[226:229], v[36:39]
	s_barrier
	v_readfirstlane_b32 s5, v168
	v_add_u32_e32 v3, 0x2000, v168
	v_lshl_add_u64 v[132:133], v[250:251], 0, s[28:29]
	s_mov_b32 m0, s5
	v_readfirstlane_b32 s5, v3
	global_load_lds_dwordx4 v[132:133], off
	v_lshl_add_u64 v[132:133], v[252:253], 0, s[28:29]
	s_mov_b32 m0, s5
	s_nop 0
	global_load_lds_dwordx4 v[132:133], off
	s_waitcnt vmcnt(6)
	s_barrier
	v_mfma_f32_16x16x32_bf16 v[32:35], v[230:233], v[198:201], v[32:35]
	v_mfma_f32_16x16x32_bf16 v[28:31], v[238:241], v[198:201], v[28:31]
	v_mfma_f32_16x16x32_bf16 v[24:27], v[230:233], v[206:209], v[24:27]
	v_mfma_f32_16x16x32_bf16 v[20:23], v[238:241], v[206:209], v[20:23]
	v_mfma_f32_16x16x32_bf16 v[16:19], v[230:233], v[214:217], v[16:19]
	v_mfma_f32_16x16x32_bf16 v[12:15], v[238:241], v[214:217], v[12:15]
	v_mfma_f32_16x16x32_bf16 v[8:11], v[230:233], v[222:225], v[8:11]
	v_mfma_f32_16x16x32_bf16 v[4:7], v[238:241], v[222:225], v[4:7]
	v_mfma_f32_16x16x32_bf16 v[32:35], v[234:237], v[202:205], v[32:35]
	v_mfma_f32_16x16x32_bf16 v[28:31], v[242:245], v[202:205], v[28:31]
	v_mfma_f32_16x16x32_bf16 v[24:27], v[234:237], v[210:213], v[24:27]
	v_mfma_f32_16x16x32_bf16 v[20:23], v[242:245], v[210:213], v[20:23]
	v_mfma_f32_16x16x32_bf16 v[16:19], v[234:237], v[218:221], v[16:19]
	v_mfma_f32_16x16x32_bf16 v[12:15], v[242:245], v[218:221], v[12:15]
	v_mfma_f32_16x16x32_bf16 v[8:11], v[234:237], v[226:229], v[8:11]
	v_mfma_f32_16x16x32_bf16 v[4:7], v[242:245], v[226:229], v[4:7]
	s_barrier
	ds_read_b128 v[182:185], v170
	ds_read_b128 v[186:189], v170 offset:1024
	ds_read_b128 v[190:193], v170 offset:2048
	ds_read_b128 v[194:197], v170 offset:3072
	v_readfirstlane_b32 s5, v169
	v_lshl_add_u64 v[132:133], v[246:247], 0, s[30:31]
	s_mov_b32 m0, s5
	v_readfirstlane_b32 s5, v171
	ds_read_b128 v[198:201], v161 offset:32768
	ds_read_b128 v[202:205], v161 offset:33792
	ds_read_b128 v[206:209], v160 offset:32768
	ds_read_b128 v[210:213], v160 offset:33792
	ds_read_b128 v[214:217], v159 offset:32768
	ds_read_b128 v[218:221], v159 offset:33792
	ds_read_b128 v[222:225], v158 offset:32768
	ds_read_b128 v[226:229], v158 offset:33792
	global_load_lds_dwordx4 v[132:133], off
	v_lshl_add_u64 v[132:133], v[248:249], 0, s[30:31]
	s_mov_b32 m0, s5
	s_nop 0
	global_load_lds_dwordx4 v[132:133], off
	s_waitcnt lgkmcnt(8)
	s_barrier
	s_waitcnt lgkmcnt(0)
	v_mfma_f32_16x16x32_bf16 v[128:131], v[182:185], v[198:201], v[128:131]
	v_mfma_f32_16x16x32_bf16 v[124:127], v[190:193], v[198:201], v[124:127]
	v_mfma_f32_16x16x32_bf16 v[120:123], v[182:185], v[206:209], v[120:123]
	v_mfma_f32_16x16x32_bf16 v[116:119], v[190:193], v[206:209], v[116:119]
	v_mfma_f32_16x16x32_bf16 v[112:115], v[182:185], v[214:217], v[112:115]
	v_mfma_f32_16x16x32_bf16 v[108:111], v[190:193], v[214:217], v[108:111]
	v_mfma_f32_16x16x32_bf16 v[104:107], v[182:185], v[222:225], v[104:107]
	v_mfma_f32_16x16x32_bf16 v[100:103], v[190:193], v[222:225], v[100:103]
	v_mfma_f32_16x16x32_bf16 v[128:131], v[186:189], v[202:205], v[128:131]
	v_mfma_f32_16x16x32_bf16 v[124:127], v[194:197], v[202:205], v[124:127]
	v_mfma_f32_16x16x32_bf16 v[120:123], v[186:189], v[210:213], v[120:123]
	v_mfma_f32_16x16x32_bf16 v[116:119], v[194:197], v[210:213], v[116:119]
	v_mfma_f32_16x16x32_bf16 v[112:115], v[186:189], v[218:221], v[112:115]
	v_mfma_f32_16x16x32_bf16 v[108:111], v[194:197], v[218:221], v[108:111]
	v_mfma_f32_16x16x32_bf16 v[104:107], v[186:189], v[226:229], v[104:107]
	v_mfma_f32_16x16x32_bf16 v[100:103], v[194:197], v[226:229], v[100:103]
	s_barrier
	v_readfirstlane_b32 s5, v172
	v_lshl_add_u64 v[132:133], v[250:251], 0, s[34:35]
	s_mov_b32 m0, s5
	v_readfirstlane_b32 s5, v173
	ds_read_b128 v[230:233], v167
	ds_read_b128 v[234:237], v167 offset:1024
	ds_read_b128 v[238:241], v167 offset:2048
	ds_read_b128 v[242:245], v167 offset:3072
	global_load_lds_dwordx4 v[132:133], off
	v_lshl_add_u64 v[132:133], v[252:253], 0, s[34:35]
	s_mov_b32 m0, s5
	s_nop 0
	global_load_lds_dwordx4 v[132:133], off
	s_barrier
	s_waitcnt lgkmcnt(0)
	v_mfma_f32_16x16x32_bf16 v[96:99], v[230:233], v[198:201], v[96:99]
	v_mfma_f32_16x16x32_bf16 v[92:95], v[238:241], v[198:201], v[92:95]
	v_mfma_f32_16x16x32_bf16 v[88:91], v[230:233], v[206:209], v[88:91]
	v_mfma_f32_16x16x32_bf16 v[84:87], v[238:241], v[206:209], v[84:87]
	v_mfma_f32_16x16x32_bf16 v[80:83], v[230:233], v[214:217], v[80:83]
	v_mfma_f32_16x16x32_bf16 v[76:79], v[238:241], v[214:217], v[76:79]
	v_mfma_f32_16x16x32_bf16 v[72:75], v[230:233], v[222:225], v[72:75]
	v_mfma_f32_16x16x32_bf16 v[68:71], v[238:241], v[222:225], v[68:71]
	v_mfma_f32_16x16x32_bf16 v[96:99], v[234:237], v[202:205], v[96:99]
	v_mfma_f32_16x16x32_bf16 v[92:95], v[242:245], v[202:205], v[92:95]
	v_mfma_f32_16x16x32_bf16 v[88:91], v[234:237], v[210:213], v[88:91]
	v_mfma_f32_16x16x32_bf16 v[84:87], v[242:245], v[210:213], v[84:87]
	v_mfma_f32_16x16x32_bf16 v[80:83], v[234:237], v[218:221], v[80:83]
	v_mfma_f32_16x16x32_bf16 v[76:79], v[242:245], v[218:221], v[76:79]
	v_mfma_f32_16x16x32_bf16 v[72:75], v[234:237], v[226:229], v[72:75]
	v_mfma_f32_16x16x32_bf16 v[68:71], v[242:245], v[226:229], v[68:71]
	v_readfirstlane_b32 s5, v174
	v_lshl_add_u64 v[132:133], v[246:247], 0, s[36:37]
	s_mov_b32 m0, s5
	v_readfirstlane_b32 s5, v175
	s_barrier
	ds_read_b128 v[198:201], v161 offset:49152
	ds_read_b128 v[202:205], v161 offset:50176
	ds_read_b128 v[206:209], v160 offset:49152
	ds_read_b128 v[210:213], v160 offset:50176
	ds_read_b128 v[214:217], v159 offset:49152
	ds_read_b128 v[218:221], v159 offset:50176
	ds_read_b128 v[222:225], v158 offset:49152
	ds_read_b128 v[226:229], v158 offset:50176
	global_load_lds_dwordx4 v[132:133], off
	v_lshl_add_u64 v[132:133], v[248:249], 0, s[36:37]
	s_mov_b32 m0, s5
	s_nop 0
	global_load_lds_dwordx4 v[132:133], off
	s_barrier
	s_waitcnt lgkmcnt(0)
	v_mfma_f32_16x16x32_bf16 v[64:67], v[182:185], v[198:201], v[64:67]
	v_mfma_f32_16x16x32_bf16 v[60:63], v[190:193], v[198:201], v[60:63]
	v_mfma_f32_16x16x32_bf16 v[56:59], v[182:185], v[206:209], v[56:59]
	v_mfma_f32_16x16x32_bf16 v[52:55], v[190:193], v[206:209], v[52:55]
	v_mfma_f32_16x16x32_bf16 v[48:51], v[182:185], v[214:217], v[48:51]
	v_mfma_f32_16x16x32_bf16 v[44:47], v[190:193], v[214:217], v[44:47]
	v_mfma_f32_16x16x32_bf16 v[40:43], v[182:185], v[222:225], v[40:43]
	v_mfma_f32_16x16x32_bf16 v[36:39], v[190:193], v[222:225], v[36:39]
	v_mfma_f32_16x16x32_bf16 v[64:67], v[186:189], v[202:205], v[64:67]
	v_mfma_f32_16x16x32_bf16 v[60:63], v[194:197], v[202:205], v[60:63]
	v_mfma_f32_16x16x32_bf16 v[56:59], v[186:189], v[210:213], v[56:59]
	v_mfma_f32_16x16x32_bf16 v[52:55], v[194:197], v[210:213], v[52:55]
	v_mfma_f32_16x16x32_bf16 v[48:51], v[186:189], v[218:221], v[48:51]
	v_mfma_f32_16x16x32_bf16 v[44:47], v[194:197], v[218:221], v[44:47]
	v_mfma_f32_16x16x32_bf16 v[40:43], v[186:189], v[226:229], v[40:43]
	v_mfma_f32_16x16x32_bf16 v[36:39], v[194:197], v[226:229], v[36:39]
	s_barrier
	v_readfirstlane_b32 s5, v176
	v_lshl_add_u64 v[132:133], v[250:251], 0, s[38:39]
	s_mov_b32 m0, s5
	v_readfirstlane_b32 s5, v177
	global_load_lds_dwordx4 v[132:133], off
	v_lshl_add_u64 v[132:133], v[252:253], 0, s[38:39]
	s_mov_b32 m0, s5
	s_nop 0
	global_load_lds_dwordx4 v[132:133], off
	s_waitcnt vmcnt(6)
	s_barrier
	v_mfma_f32_16x16x32_bf16 v[32:35], v[230:233], v[198:201], v[32:35]
	v_mfma_f32_16x16x32_bf16 v[28:31], v[238:241], v[198:201], v[28:31]
	v_mfma_f32_16x16x32_bf16 v[24:27], v[230:233], v[206:209], v[24:27]
	v_mfma_f32_16x16x32_bf16 v[20:23], v[238:241], v[206:209], v[20:23]
	v_mfma_f32_16x16x32_bf16 v[16:19], v[230:233], v[214:217], v[16:19]
	v_mfma_f32_16x16x32_bf16 v[12:15], v[238:241], v[214:217], v[12:15]
	v_mfma_f32_16x16x32_bf16 v[8:11], v[230:233], v[222:225], v[8:11]
	v_mfma_f32_16x16x32_bf16 v[4:7], v[238:241], v[222:225], v[4:7]
	v_mfma_f32_16x16x32_bf16 v[32:35], v[234:237], v[202:205], v[32:35]
	v_mfma_f32_16x16x32_bf16 v[28:31], v[242:245], v[202:205], v[28:31]
	v_mfma_f32_16x16x32_bf16 v[24:27], v[234:237], v[210:213], v[24:27]
	v_mfma_f32_16x16x32_bf16 v[20:23], v[242:245], v[210:213], v[20:23]
	v_mfma_f32_16x16x32_bf16 v[16:19], v[234:237], v[218:221], v[16:19]
	v_mfma_f32_16x16x32_bf16 v[12:15], v[242:245], v[218:221], v[12:15]
	v_mfma_f32_16x16x32_bf16 v[8:11], v[234:237], v[226:229], v[8:11]
	v_mfma_f32_16x16x32_bf16 v[4:7], v[242:245], v[226:229], v[4:7]
	s_add_u32 s48, s48, 0x100
	s_addc_u32 s49, s49, 0
	s_cmp_gt_u32 s2, 11
	s_barrier
	s_cbranch_scc1 .LBB0_2802
	s_mov_b32 s2, s4
	s_cmp_lt_i32 s2, 12
	s_cbranch_scc1 .LBB0_2763

.LBB0_2802:
	v_readfirstlane_b32 s2, v0
	v_lshl_add_u64 v[134:135], v[134:135], 0, s[44:45]
	s_mov_b32 m0, s2
	v_readfirstlane_b32 s2, v2
	ds_read_b128 v[138:141], v180
	ds_read_b128 v[142:145], v180 offset:1024
	ds_read_b128 v[172:175], v180 offset:2048
	ds_read_b128 v[180:183], v180 offset:3072
	ds_read_b128 v[184:187], v161
	ds_read_b128 v[188:191], v161 offset:1024
	ds_read_b128 v[192:195], v160
	ds_read_b128 v[196:199], v160 offset:1024
	ds_read_b128 v[200:203], v159
	ds_read_b128 v[204:207], v159 offset:1024
	ds_read_b128 v[208:211], v158
	ds_read_b128 v[212:215], v158 offset:1024
	global_load_lds_dwordx4 v[134:135], off
	v_lshl_add_u64 v[134:135], v[136:137], 0, s[44:45]
	s_mov_b32 m0, s2
	s_nop 0
	global_load_lds_dwordx4 v[134:135], off
	s_barrier
	s_waitcnt lgkmcnt(0)
	v_mfma_f32_16x16x32_bf16 v[128:131], v[138:141], v[184:187], v[128:131]
	v_mfma_f32_16x16x32_bf16 v[124:127], v[172:175], v[184:187], v[124:127]
	v_mfma_f32_16x16x32_bf16 v[120:123], v[138:141], v[192:195], v[120:123]
	v_mfma_f32_16x16x32_bf16 v[116:119], v[172:175], v[192:195], v[116:119]
	v_mfma_f32_16x16x32_bf16 v[112:115], v[138:141], v[200:203], v[112:115]
	v_mfma_f32_16x16x32_bf16 v[108:111], v[172:175], v[200:203], v[108:111]
	v_mfma_f32_16x16x32_bf16 v[104:107], v[138:141], v[208:211], v[104:107]
	v_mfma_f32_16x16x32_bf16 v[100:103], v[172:175], v[208:211], v[100:103]
	v_mfma_f32_16x16x32_bf16 v[128:131], v[142:145], v[188:191], v[128:131]
	v_mfma_f32_16x16x32_bf16 v[124:127], v[180:183], v[188:191], v[124:127]
	v_mfma_f32_16x16x32_bf16 v[120:123], v[142:145], v[196:199], v[120:123]
	v_mfma_f32_16x16x32_bf16 v[116:119], v[180:183], v[196:199], v[116:119]
	v_mfma_f32_16x16x32_bf16 v[112:115], v[142:145], v[204:207], v[112:115]
	v_mfma_f32_16x16x32_bf16 v[108:111], v[180:183], v[204:207], v[108:111]
	v_mfma_f32_16x16x32_bf16 v[104:107], v[142:145], v[212:215], v[104:107]
	v_mfma_f32_16x16x32_bf16 v[100:103], v[180:183], v[212:215], v[100:103]
	s_barrier
	ds_read_b128 v[134:137], v178
	ds_read_b128 v[216:219], v178 offset:1024
	ds_read_b128 v[220:223], v178 offset:2048
	ds_read_b128 v[176:179], v178 offset:3072
	s_barrier
	s_waitcnt lgkmcnt(0)
	v_mfma_f32_16x16x32_bf16 v[96:99], v[134:137], v[184:187], v[96:99]
	v_mfma_f32_16x16x32_bf16 v[92:95], v[220:223], v[184:187], v[92:95]
	v_mfma_f32_16x16x32_bf16 v[88:91], v[134:137], v[192:195], v[88:91]
	v_mfma_f32_16x16x32_bf16 v[84:87], v[220:223], v[192:195], v[84:87]
	v_mfma_f32_16x16x32_bf16 v[80:83], v[134:137], v[200:203], v[80:83]
	v_mfma_f32_16x16x32_bf16 v[76:79], v[220:223], v[200:203], v[76:79]
	v_mfma_f32_16x16x32_bf16 v[72:75], v[134:137], v[208:211], v[72:75]
	v_mfma_f32_16x16x32_bf16 v[68:71], v[220:223], v[208:211], v[68:71]
	v_mfma_f32_16x16x32_bf16 v[96:99], v[216:219], v[188:191], v[96:99]
	v_mfma_f32_16x16x32_bf16 v[92:95], v[176:179], v[188:191], v[92:95]
	v_mfma_f32_16x16x32_bf16 v[88:91], v[216:219], v[196:199], v[88:91]
	v_mfma_f32_16x16x32_bf16 v[84:87], v[176:179], v[196:199], v[84:87]
	v_mfma_f32_16x16x32_bf16 v[80:83], v[216:219], v[204:207], v[80:83]
	v_mfma_f32_16x16x32_bf16 v[76:79], v[176:179], v[204:207], v[76:79]
	v_mfma_f32_16x16x32_bf16 v[72:75], v[216:219], v[212:215], v[72:75]
	v_mfma_f32_16x16x32_bf16 v[68:71], v[176:179], v[212:215], v[68:71]
	s_barrier
	ds_read_b128 v[184:187], v161 offset:16384
	ds_read_b128 v[188:191], v161 offset:17408
	ds_read_b128 v[192:195], v160 offset:16384
	ds_read_b128 v[196:199], v160 offset:17408
	ds_read_b128 v[200:203], v159 offset:16384
	ds_read_b128 v[204:207], v159 offset:17408
	ds_read_b128 v[208:211], v158 offset:16384
	ds_read_b128 v[212:215], v158 offset:17408
	s_waitcnt vmcnt(4)
	s_barrier
	s_waitcnt lgkmcnt(0)
	v_mfma_f32_16x16x32_bf16 v[64:67], v[138:141], v[184:187], v[64:67]
	v_mfma_f32_16x16x32_bf16 v[56:59], v[138:141], v[192:195], v[56:59]
	v_mfma_f32_16x16x32_bf16 v[48:51], v[138:141], v[200:203], v[48:51]
	v_mfma_f32_16x16x32_bf16 v[40:43], v[138:141], v[208:211], v[40:43]
	v_mfma_f32_16x16x32_bf16 v[36:39], v[172:175], v[208:211], v[36:39]
	v_mfma_f32_16x16x32_bf16 v[224:227], v[142:145], v[188:191], v[64:67]
	v_mfma_f32_16x16x32_bf16 v[60:63], v[172:175], v[184:187], v[60:63]
	v_mfma_f32_16x16x32_bf16 v[232:235], v[142:145], v[196:199], v[56:59]
	v_mfma_f32_16x16x32_bf16 v[52:55], v[172:175], v[192:195], v[52:55]
	v_mfma_f32_16x16x32_bf16 v[240:243], v[142:145], v[204:207], v[48:51]
	v_mfma_f32_16x16x32_bf16 v[44:47], v[172:175], v[200:203], v[44:47]
	v_mfma_f32_16x16x32_bf16 v[138:141], v[142:145], v[212:215], v[40:43]
	v_mfma_f32_16x16x32_bf16 v[142:145], v[180:183], v[212:215], v[36:39]
	v_mfma_f32_16x16x32_bf16 v[228:231], v[180:183], v[188:191], v[60:63]
	v_mfma_f32_16x16x32_bf16 v[236:239], v[180:183], v[196:199], v[52:55]
	v_mfma_f32_16x16x32_bf16 v[244:247], v[180:183], v[204:207], v[44:47]
	v_mfma_f32_16x16x32_bf16 v[8:11], v[134:137], v[208:211], v[8:11]
	v_mfma_f32_16x16x32_bf16 v[32:35], v[134:137], v[184:187], v[32:35]
	v_mfma_f32_16x16x32_bf16 v[28:31], v[220:223], v[184:187], v[28:31]
	v_mfma_f32_16x16x32_bf16 v[24:27], v[134:137], v[192:195], v[24:27]
	v_mfma_f32_16x16x32_bf16 v[20:23], v[220:223], v[192:195], v[20:23]
	v_mfma_f32_16x16x32_bf16 v[16:19], v[134:137], v[200:203], v[16:19]
	v_mfma_f32_16x16x32_bf16 v[12:15], v[220:223], v[200:203], v[12:15]
	v_mfma_f32_16x16x32_bf16 v[134:137], v[216:219], v[212:215], v[8:11]
	v_mfma_f32_16x16x32_bf16 v[2:5], v[220:223], v[208:211], v[4:7]
	v_mfma_f32_16x16x32_bf16 v[172:175], v[216:219], v[188:191], v[32:35]
	v_mfma_f32_16x16x32_bf16 v[180:183], v[176:179], v[188:191], v[28:31]
	v_mfma_f32_16x16x32_bf16 v[184:187], v[216:219], v[196:199], v[24:27]
	v_mfma_f32_16x16x32_bf16 v[188:191], v[176:179], v[196:199], v[20:23]
	v_mfma_f32_16x16x32_bf16 v[192:195], v[216:219], v[204:207], v[16:19]
	v_mfma_f32_16x16x32_bf16 v[196:199], v[176:179], v[204:207], v[12:15]
	v_mfma_f32_16x16x32_bf16 v[176:179], v[176:179], v[212:215], v[2:5]
	s_barrier
	ds_read_b128 v[200:203], v170
	ds_read_b128 v[204:207], v170 offset:1024
	ds_read_b128 v[208:211], v170 offset:2048
	ds_read_b128 v[168:171], v170 offset:3072
	ds_read_b128 v[22:25], v161 offset:32768
	ds_read_b128 v[34:37], v161 offset:33792
	ds_read_b128 v[38:41], v160 offset:32768
	ds_read_b128 v[50:53], v160 offset:33792
	ds_read_b128 v[54:57], v159 offset:32768
	ds_read_b128 v[58:61], v159 offset:33792
	ds_read_b128 v[62:65], v158 offset:32768
	ds_read_b128 v[212:215], v158 offset:33792
	s_waitcnt vmcnt(2)
	s_barrier
	s_waitcnt lgkmcnt(0)
	v_mfma_f32_16x16x32_bf16 v[18:21], v[200:203], v[54:57], v[112:115]
	v_mfma_f32_16x16x32_bf16 v[26:29], v[204:207], v[58:61], v[18:21]
	v_mfma_f32_16x16x32_bf16 v[18:21], v[208:211], v[54:57], v[108:111]
	v_mfma_f32_16x16x32_bf16 v[30:33], v[168:171], v[58:61], v[18:21]
	v_mfma_f32_16x16x32_bf16 v[18:21], v[200:203], v[62:65], v[104:107]
	v_mfma_f32_16x16x32_bf16 v[2:5], v[200:203], v[22:25], v[128:131]
	v_mfma_f32_16x16x32_bf16 v[6:9], v[208:211], v[22:25], v[124:127]
	v_mfma_f32_16x16x32_bf16 v[10:13], v[200:203], v[38:41], v[120:123]
	v_mfma_f32_16x16x32_bf16 v[14:17], v[208:211], v[38:41], v[116:119]
	v_mfma_f32_16x16x32_bf16 v[42:45], v[204:207], v[212:215], v[18:21]
	v_mfma_f32_16x16x32_bf16 v[18:21], v[208:211], v[62:65], v[100:103]
	v_mfma_f32_16x16x32_bf16 v[2:5], v[204:207], v[34:37], v[2:5]
	v_mfma_f32_16x16x32_bf16 v[6:9], v[168:171], v[34:37], v[6:9]
	v_mfma_f32_16x16x32_bf16 v[10:13], v[204:207], v[50:53], v[10:13]
	v_mfma_f32_16x16x32_bf16 v[14:17], v[168:171], v[50:53], v[14:17]
	v_mfma_f32_16x16x32_bf16 v[46:49], v[168:171], v[212:215], v[18:21]
	s_barrier
	ds_read_b128 v[122:125], v167
	ds_read_b128 v[126:129], v167 offset:1024
	ds_read_b128 v[216:219], v167 offset:2048
	ds_read_b128 v[220:223], v167 offset:3072
	s_waitcnt vmcnt(0)
	s_barrier
	s_waitcnt lgkmcnt(0)
	v_mfma_f32_16x16x32_bf16 v[18:21], v[122:125], v[22:25], v[96:99]
	v_mfma_f32_16x16x32_bf16 v[22:25], v[216:219], v[22:25], v[92:95]
	v_mfma_f32_16x16x32_bf16 v[18:21], v[126:129], v[34:37], v[18:21]
	v_mfma_f32_16x16x32_bf16 v[22:25], v[220:223], v[34:37], v[22:25]
	v_mfma_f32_16x16x32_bf16 v[34:37], v[122:125], v[38:41], v[88:91]
	v_mfma_f32_16x16x32_bf16 v[38:41], v[216:219], v[38:41], v[84:87]
	v_mfma_f32_16x16x32_bf16 v[34:37], v[126:129], v[50:53], v[34:37]
	v_mfma_f32_16x16x32_bf16 v[38:41], v[220:223], v[50:53], v[38:41]
	v_mfma_f32_16x16x32_bf16 v[50:53], v[122:125], v[54:57], v[80:83]
	v_mfma_f32_16x16x32_bf16 v[54:57], v[216:219], v[54:57], v[76:79]
	v_mfma_f32_16x16x32_bf16 v[50:53], v[126:129], v[58:61], v[50:53]
	v_mfma_f32_16x16x32_bf16 v[54:57], v[220:223], v[58:61], v[54:57]
	v_mfma_f32_16x16x32_bf16 v[58:61], v[122:125], v[62:65], v[72:75]
	v_mfma_f32_16x16x32_bf16 v[62:65], v[216:219], v[62:65], v[68:71]
	v_mfma_f32_16x16x32_bf16 v[58:61], v[126:129], v[212:215], v[58:61]
	v_mfma_f32_16x16x32_bf16 v[62:65], v[220:223], v[212:215], v[62:65]
	s_barrier
	ds_read_b128 v[86:89], v161 offset:49152
	ds_read_b128 v[94:97], v161 offset:50176
	ds_read_b128 v[102:105], v160 offset:49152
	ds_read_b128 v[110:113], v160 offset:50176
	ds_read_b128 v[118:121], v159 offset:49152
	ds_read_b128 v[160:163], v159 offset:50176
	ds_read_b128 v[212:215], v158 offset:49152
	ds_read_b128 v[248:251], v158 offset:50176
	s_barrier
	s_waitcnt lgkmcnt(0)
	v_mfma_f32_16x16x32_bf16 v[78:81], v[208:211], v[102:105], v[236:239]
	v_mfma_f32_16x16x32_bf16 v[82:85], v[168:171], v[110:113], v[78:81]
	v_mfma_f32_16x16x32_bf16 v[78:81], v[200:203], v[118:121], v[240:243]
	v_mfma_f32_16x16x32_bf16 v[90:93], v[204:207], v[160:163], v[78:81]
	v_mfma_f32_16x16x32_bf16 v[78:81], v[208:211], v[118:121], v[244:247]
	v_mfma_f32_16x16x32_bf16 v[98:101], v[168:171], v[160:163], v[78:81]
	v_mfma_f32_16x16x32_bf16 v[78:81], v[200:203], v[212:215], v[138:141]
	v_mfma_f32_16x16x32_bf16 v[66:69], v[200:203], v[86:89], v[224:227]
	v_mfma_f32_16x16x32_bf16 v[70:73], v[208:211], v[86:89], v[228:231]
	v_mfma_f32_16x16x32_bf16 v[74:77], v[200:203], v[102:105], v[232:235]
	v_mfma_f32_16x16x32_bf16 v[106:109], v[204:207], v[248:251], v[78:81]
	v_mfma_f32_16x16x32_bf16 v[78:81], v[208:211], v[212:215], v[142:145]
	v_mfma_f32_16x16x32_bf16 v[66:69], v[204:207], v[94:97], v[66:69]
	v_mfma_f32_16x16x32_bf16 v[70:73], v[168:171], v[94:97], v[70:73]
	v_mfma_f32_16x16x32_bf16 v[74:77], v[204:207], v[110:113], v[74:77]
	v_mfma_f32_16x16x32_bf16 v[114:117], v[168:171], v[248:251], v[78:81]
	v_mfma_f32_16x16x32_bf16 v[78:81], v[122:125], v[86:89], v[172:175]
	v_mfma_f32_16x16x32_bf16 v[86:89], v[216:219], v[86:89], v[180:183]
	v_mfma_f32_16x16x32_bf16 v[78:81], v[126:129], v[94:97], v[78:81]
	v_mfma_f32_16x16x32_bf16 v[86:89], v[220:223], v[94:97], v[86:89]
	v_mfma_f32_16x16x32_bf16 v[94:97], v[122:125], v[102:105], v[184:187]
	v_mfma_f32_16x16x32_bf16 v[102:105], v[216:219], v[102:105], v[188:191]
	v_mfma_f32_16x16x32_bf16 v[94:97], v[126:129], v[110:113], v[94:97]
	v_mfma_f32_16x16x32_bf16 v[102:105], v[220:223], v[110:113], v[102:105]
	v_mfma_f32_16x16x32_bf16 v[110:113], v[122:125], v[118:121], v[192:195]
	v_mfma_f32_16x16x32_bf16 v[122:125], v[122:125], v[212:215], v[134:137]
	v_mfma_f32_16x16x32_bf16 v[110:113], v[126:129], v[160:163], v[110:113]
	v_mfma_f32_16x16x32_bf16 v[118:121], v[216:219], v[118:121], v[196:199]
	v_mfma_f32_16x16x32_bf16 v[122:125], v[126:129], v[248:251], v[122:125]
	v_mfma_f32_16x16x32_bf16 v[126:129], v[216:219], v[212:215], v[176:179]
	v_mfma_f32_16x16x32_bf16 v[118:121], v[220:223], v[160:163], v[118:121]
	v_mfma_f32_16x16x32_bf16 v[126:129], v[220:223], v[248:251], v[126:129]
	v_and_b32_e32 v0, 0xffffff00, v149
	v_lshlrev_b32_e32 v130, 2, v155
	v_add3_u32 v131, s67, v0, v130
	v_add3_u32 v0, s68, v0, v130
	s_barrier
	ds_read2_b32 v[136:137], v131 offset1:16
	ds_read2_b32 v[138:139], v131 offset0:32 offset1:48
	ds_read2_b32 v[142:143], v0 offset1:16
	ds_read2_b32 v[146:147], v0 offset0:32 offset1:48
	v_cmp_gt_u32_e32 vcc, s60, v149
	s_waitcnt lgkmcnt(0)
	v_mov_b32_e32 v0, v137
	v_mov_b32_e32 v140, v139
	v_mov_b32_e32 v144, v143
	v_mov_b32_e32 v134, v147
	s_and_saveexec_b64 s[6:7], vcc
	s_cbranch_execz .LBB0_2757
	s_barrier
	s_branch .LBB0_2757

.LBB0_2916:
	ds_read_b128 v[180:183], v172
	ds_read_b128 v[184:187], v172 offset:1024
	ds_read_b128 v[188:191], v172 offset:2048
	ds_read_b128 v[192:195], v172 offset:3072
	v_add_u32_e32 v178, 0xc000, v152
	v_lshl_add_u64 v[244:245], s[6:7], 0, v[146:147]
	v_readfirstlane_b32 s4, v178
	v_add_u32_e32 v179, 0xe000, v152
	v_lshl_add_u64 v[224:225], v[244:245], 0, s[12:13]
	s_mov_b32 m0, s4
	v_lshl_add_u64 v[246:247], s[6:7], 0, v[148:149]
	v_readfirstlane_b32 s4, v179
	ds_read_b128 v[174:177], v161
	ds_read_b128 v[196:199], v161 offset:1024
	ds_read_b128 v[200:203], v160
	ds_read_b128 v[204:207], v160 offset:1024
	ds_read_b128 v[208:211], v159
	ds_read_b128 v[212:215], v159 offset:1024
	ds_read_b128 v[216:219], v158
	ds_read_b128 v[220:223], v158 offset:1024
	global_load_lds_dwordx4 v[224:225], off
	v_lshl_add_u64 v[224:225], v[246:247], 0, s[12:13]
	s_mov_b32 m0, s4
	s_nop 0
	global_load_lds_dwordx4 v[224:225], off
	s_waitcnt lgkmcnt(8)
	s_barrier
	s_waitcnt lgkmcnt(0)
	v_mfma_f32_16x16x32_bf16 v[124:127], v[180:183], v[174:177], v[124:127]
	v_mfma_f32_16x16x32_bf16 v[120:123], v[188:191], v[174:177], v[120:123]
	v_mfma_f32_16x16x32_bf16 v[116:119], v[180:183], v[200:203], v[116:119]
	v_mfma_f32_16x16x32_bf16 v[112:115], v[188:191], v[200:203], v[112:115]
	v_mfma_f32_16x16x32_bf16 v[108:111], v[180:183], v[208:211], v[108:111]
	v_mfma_f32_16x16x32_bf16 v[104:107], v[188:191], v[208:211], v[104:107]
	v_mfma_f32_16x16x32_bf16 v[100:103], v[180:183], v[216:219], v[100:103]
	v_mfma_f32_16x16x32_bf16 v[96:99], v[188:191], v[216:219], v[96:99]
	v_mfma_f32_16x16x32_bf16 v[124:127], v[184:187], v[196:199], v[124:127]
	v_mfma_f32_16x16x32_bf16 v[120:123], v[192:195], v[196:199], v[120:123]
	v_mfma_f32_16x16x32_bf16 v[116:119], v[184:187], v[204:207], v[116:119]
	v_mfma_f32_16x16x32_bf16 v[112:115], v[192:195], v[204:207], v[112:115]
	v_mfma_f32_16x16x32_bf16 v[108:111], v[184:187], v[212:215], v[108:111]
	v_mfma_f32_16x16x32_bf16 v[104:107], v[192:195], v[212:215], v[104:107]
	v_mfma_f32_16x16x32_bf16 v[100:103], v[184:187], v[220:223], v[100:103]
	v_mfma_f32_16x16x32_bf16 v[96:99], v[192:195], v[220:223], v[96:99]
	s_barrier
	v_lshl_add_u64 v[248:249], s[6:7], 0, v[142:143]
	v_readfirstlane_b32 s4, v153
	v_add_u32_e32 v173, 0x2000, v153
	v_lshl_add_u64 v[240:241], v[248:249], 0, s[14:15]
	s_mov_b32 m0, s4
	v_lshl_add_u64 v[250:251], s[6:7], 0, v[144:145]
	v_readfirstlane_b32 s4, v173
	ds_read_b128 v[224:227], v168
	ds_read_b128 v[228:231], v168 offset:1024
	ds_read_b128 v[232:235], v168 offset:2048
	ds_read_b128 v[236:239], v168 offset:3072
	global_load_lds_dwordx4 v[240:241], off
	v_lshl_add_u64 v[240:241], v[250:251], 0, s[14:15]
	s_mov_b32 m0, s4
	s_nop 0
	global_load_lds_dwordx4 v[240:241], off
	s_barrier
	s_waitcnt lgkmcnt(0)
	v_mfma_f32_16x16x32_bf16 v[92:95], v[224:227], v[174:177], v[92:95]
	v_mfma_f32_16x16x32_bf16 v[88:91], v[232:235], v[174:177], v[88:91]
	v_mfma_f32_16x16x32_bf16 v[84:87], v[224:227], v[200:203], v[84:87]
	v_mfma_f32_16x16x32_bf16 v[80:83], v[232:235], v[200:203], v[80:83]
	v_mfma_f32_16x16x32_bf16 v[76:79], v[224:227], v[208:211], v[76:79]
	v_mfma_f32_16x16x32_bf16 v[72:75], v[232:235], v[208:211], v[72:75]
	v_mfma_f32_16x16x32_bf16 v[68:71], v[224:227], v[216:219], v[68:71]
	v_mfma_f32_16x16x32_bf16 v[64:67], v[232:235], v[216:219], v[64:67]
	v_mfma_f32_16x16x32_bf16 v[92:95], v[228:231], v[196:199], v[92:95]
	v_mfma_f32_16x16x32_bf16 v[88:91], v[236:239], v[196:199], v[88:91]
	v_mfma_f32_16x16x32_bf16 v[84:87], v[228:231], v[204:207], v[84:87]
	v_mfma_f32_16x16x32_bf16 v[80:83], v[236:239], v[204:207], v[80:83]
	v_mfma_f32_16x16x32_bf16 v[76:79], v[228:231], v[212:215], v[76:79]
	v_mfma_f32_16x16x32_bf16 v[72:75], v[236:239], v[212:215], v[72:75]
	v_mfma_f32_16x16x32_bf16 v[68:71], v[228:231], v[220:223], v[68:71]
	v_mfma_f32_16x16x32_bf16 v[64:67], v[236:239], v[220:223], v[64:67]
	v_readfirstlane_b32 s4, v152
	v_lshl_add_u64 v[174:175], v[244:245], 0, s[16:17]
	s_mov_b32 m0, s4
	s_barrier
	ds_read_b128 v[196:199], v161 offset:16384
	ds_read_b128 v[200:203], v161 offset:17408
	ds_read_b128 v[204:207], v160 offset:16384
	ds_read_b128 v[208:211], v160 offset:17408
	ds_read_b128 v[212:215], v159 offset:16384
	ds_read_b128 v[216:219], v159 offset:17408
	ds_read_b128 v[220:223], v158 offset:16384
	ds_read_b128 v[240:243], v158 offset:17408
	global_load_lds_dwordx4 v[174:175], off
	v_add_u32_e32 v174, 0x2000, v152
	v_lshl_add_u64 v[176:177], v[246:247], 0, s[16:17]
	v_readfirstlane_b32 s4, v174
	s_mov_b32 m0, s4
	s_nop 0
	global_load_lds_dwordx4 v[176:177], off
	s_barrier
	s_waitcnt lgkmcnt(0)
	v_mfma_f32_16x16x32_bf16 v[60:63], v[180:183], v[196:199], v[60:63]
	v_mfma_f32_16x16x32_bf16 v[56:59], v[188:191], v[196:199], v[56:59]
	v_mfma_f32_16x16x32_bf16 v[52:55], v[180:183], v[204:207], v[52:55]
	v_mfma_f32_16x16x32_bf16 v[48:51], v[188:191], v[204:207], v[48:51]
	v_mfma_f32_16x16x32_bf16 v[44:47], v[180:183], v[212:215], v[44:47]
	v_mfma_f32_16x16x32_bf16 v[40:43], v[188:191], v[212:215], v[40:43]
	v_mfma_f32_16x16x32_bf16 v[36:39], v[180:183], v[220:223], v[36:39]
	v_mfma_f32_16x16x32_bf16 v[32:35], v[188:191], v[220:223], v[32:35]
	v_mfma_f32_16x16x32_bf16 v[60:63], v[184:187], v[200:203], v[60:63]
	v_mfma_f32_16x16x32_bf16 v[56:59], v[192:195], v[200:203], v[56:59]
	v_mfma_f32_16x16x32_bf16 v[52:55], v[184:187], v[208:211], v[52:55]
	v_mfma_f32_16x16x32_bf16 v[48:51], v[192:195], v[208:211], v[48:51]
	v_mfma_f32_16x16x32_bf16 v[44:47], v[184:187], v[216:219], v[44:47]
	v_mfma_f32_16x16x32_bf16 v[40:43], v[192:195], v[216:219], v[40:43]
	v_mfma_f32_16x16x32_bf16 v[36:39], v[184:187], v[240:243], v[36:39]
	v_mfma_f32_16x16x32_bf16 v[32:35], v[192:195], v[240:243], v[32:35]
	s_barrier
	v_readfirstlane_b32 s4, v151
	v_add_u32_e32 v175, 0x2000, v151
	v_lshl_add_u64 v[176:177], v[248:249], 0, s[18:19]
	s_mov_b32 m0, s4
	v_readfirstlane_b32 s4, v175
	global_load_lds_dwordx4 v[176:177], off
	v_lshl_add_u64 v[176:177], v[250:251], 0, s[18:19]
	s_mov_b32 m0, s4
	s_nop 0
	global_load_lds_dwordx4 v[176:177], off
	s_waitcnt vmcnt(6)
	s_barrier
	v_mfma_f32_16x16x32_bf16 v[28:31], v[224:227], v[196:199], v[28:31]
	v_mfma_f32_16x16x32_bf16 v[24:27], v[232:235], v[196:199], v[24:27]
	v_mfma_f32_16x16x32_bf16 v[20:23], v[224:227], v[204:207], v[20:23]
	v_mfma_f32_16x16x32_bf16 v[16:19], v[232:235], v[204:207], v[16:19]
	v_mfma_f32_16x16x32_bf16 v[12:15], v[224:227], v[212:215], v[12:15]
	v_mfma_f32_16x16x32_bf16 v[8:11], v[232:235], v[212:215], v[8:11]
	v_mfma_f32_16x16x32_bf16 v[4:7], v[224:227], v[220:223], v[4:7]
	v_mfma_f32_16x16x32_bf16 v[0:3], v[232:235], v[220:223], v[0:3]
	v_mfma_f32_16x16x32_bf16 v[28:31], v[228:231], v[200:203], v[28:31]
	v_mfma_f32_16x16x32_bf16 v[24:27], v[236:239], v[200:203], v[24:27]
	v_mfma_f32_16x16x32_bf16 v[20:23], v[228:231], v[208:211], v[20:23]
	v_mfma_f32_16x16x32_bf16 v[16:19], v[236:239], v[208:211], v[16:19]
	v_mfma_f32_16x16x32_bf16 v[12:15], v[228:231], v[216:219], v[12:15]
	v_mfma_f32_16x16x32_bf16 v[8:11], v[236:239], v[216:219], v[8:11]
	v_mfma_f32_16x16x32_bf16 v[4:7], v[228:231], v[240:243], v[4:7]
	v_mfma_f32_16x16x32_bf16 v[0:3], v[236:239], v[240:243], v[0:3]
	s_barrier
	ds_read_b128 v[180:183], v163
	ds_read_b128 v[184:187], v163 offset:1024
	ds_read_b128 v[188:191], v163 offset:2048
	ds_read_b128 v[192:195], v163 offset:3072
	v_add_u32_e32 v176, 0x4000, v152
	v_add_u32_e32 v177, 0x6000, v152
	v_readfirstlane_b32 s4, v176
	v_lshl_add_u64 v[228:229], v[244:245], 0, s[20:21]
	s_mov_b32 m0, s4
	v_readfirstlane_b32 s4, v177
	ds_read_b128 v[196:199], v161 offset:32768
	ds_read_b128 v[200:203], v161 offset:33792
	ds_read_b128 v[204:207], v160 offset:32768
	ds_read_b128 v[208:211], v160 offset:33792
	ds_read_b128 v[212:215], v159 offset:32768
	ds_read_b128 v[216:219], v159 offset:33792
	ds_read_b128 v[220:223], v158 offset:32768
	ds_read_b128 v[224:227], v158 offset:33792
	global_load_lds_dwordx4 v[228:229], off
	v_lshl_add_u64 v[228:229], v[246:247], 0, s[20:21]
	s_mov_b32 m0, s4
	s_nop 0
	global_load_lds_dwordx4 v[228:229], off
	s_waitcnt lgkmcnt(8)
	s_barrier
	s_waitcnt lgkmcnt(0)
	v_mfma_f32_16x16x32_bf16 v[124:127], v[180:183], v[196:199], v[124:127]
	v_mfma_f32_16x16x32_bf16 v[120:123], v[188:191], v[196:199], v[120:123]
	v_mfma_f32_16x16x32_bf16 v[116:119], v[180:183], v[204:207], v[116:119]
	v_mfma_f32_16x16x32_bf16 v[112:115], v[188:191], v[204:207], v[112:115]
	v_mfma_f32_16x16x32_bf16 v[108:111], v[180:183], v[212:215], v[108:111]
	v_mfma_f32_16x16x32_bf16 v[104:107], v[188:191], v[212:215], v[104:107]
	v_mfma_f32_16x16x32_bf16 v[100:103], v[180:183], v[220:223], v[100:103]
	v_mfma_f32_16x16x32_bf16 v[96:99], v[188:191], v[220:223], v[96:99]
	v_mfma_f32_16x16x32_bf16 v[124:127], v[184:187], v[200:203], v[124:127]
	v_mfma_f32_16x16x32_bf16 v[120:123], v[192:195], v[200:203], v[120:123]
	v_mfma_f32_16x16x32_bf16 v[116:119], v[184:187], v[208:211], v[116:119]
	v_mfma_f32_16x16x32_bf16 v[112:115], v[192:195], v[208:211], v[112:115]
	v_mfma_f32_16x16x32_bf16 v[108:111], v[184:187], v[216:219], v[108:111]
	v_mfma_f32_16x16x32_bf16 v[104:107], v[192:195], v[216:219], v[104:107]
	v_mfma_f32_16x16x32_bf16 v[100:103], v[184:187], v[224:227], v[100:103]
	v_mfma_f32_16x16x32_bf16 v[96:99], v[192:195], v[224:227], v[96:99]
	s_barrier
	v_readfirstlane_b32 s4, v167
	v_add_u32_e32 v254, 0x2000, v167
	v_lshl_add_u64 v[252:253], v[248:249], 0, s[24:25]
	s_mov_b32 m0, s4
	v_readfirstlane_b32 s4, v254
	ds_read_b128 v[228:231], v162
	ds_read_b128 v[232:235], v162 offset:1024
	ds_read_b128 v[236:239], v162 offset:2048
	ds_read_b128 v[240:243], v162 offset:3072
	global_load_lds_dwordx4 v[252:253], off
	v_lshl_add_u64 v[252:253], v[250:251], 0, s[24:25]
	s_mov_b32 m0, s4
	s_nop 0
	global_load_lds_dwordx4 v[252:253], off
	s_barrier
	s_waitcnt lgkmcnt(0)
	v_mfma_f32_16x16x32_bf16 v[92:95], v[228:231], v[196:199], v[92:95]
	v_mfma_f32_16x16x32_bf16 v[88:91], v[236:239], v[196:199], v[88:91]
	v_mfma_f32_16x16x32_bf16 v[84:87], v[228:231], v[204:207], v[84:87]
	v_mfma_f32_16x16x32_bf16 v[80:83], v[236:239], v[204:207], v[80:83]
	v_mfma_f32_16x16x32_bf16 v[76:79], v[228:231], v[212:215], v[76:79]
	v_mfma_f32_16x16x32_bf16 v[72:75], v[236:239], v[212:215], v[72:75]
	v_mfma_f32_16x16x32_bf16 v[68:71], v[228:231], v[220:223], v[68:71]
	v_mfma_f32_16x16x32_bf16 v[64:67], v[236:239], v[220:223], v[64:67]
	v_mfma_f32_16x16x32_bf16 v[92:95], v[232:235], v[200:203], v[92:95]
	v_mfma_f32_16x16x32_bf16 v[88:91], v[240:243], v[200:203], v[88:91]
	v_mfma_f32_16x16x32_bf16 v[84:87], v[232:235], v[208:211], v[84:87]
	v_mfma_f32_16x16x32_bf16 v[80:83], v[240:243], v[208:211], v[80:83]
	v_mfma_f32_16x16x32_bf16 v[76:79], v[232:235], v[216:219], v[76:79]
	v_mfma_f32_16x16x32_bf16 v[72:75], v[240:243], v[216:219], v[72:75]
	v_mfma_f32_16x16x32_bf16 v[68:71], v[232:235], v[224:227], v[68:71]
	v_mfma_f32_16x16x32_bf16 v[64:67], v[240:243], v[224:227], v[64:67]
	v_readfirstlane_b32 s4, v169
	v_lshl_add_u64 v[244:245], v[244:245], 0, s[26:27]
	s_mov_b32 m0, s4
	v_readfirstlane_b32 s4, v170
	s_barrier
	ds_read_b128 v[196:199], v161 offset:49152
	ds_read_b128 v[200:203], v161 offset:50176
	ds_read_b128 v[204:207], v160 offset:49152
	ds_read_b128 v[208:211], v160 offset:50176
	ds_read_b128 v[212:215], v159 offset:49152
	ds_read_b128 v[216:219], v159 offset:50176
	ds_read_b128 v[220:223], v158 offset:49152
	ds_read_b128 v[224:227], v158 offset:50176
	global_load_lds_dwordx4 v[244:245], off
	v_lshl_add_u64 v[244:245], v[246:247], 0, s[26:27]
	s_mov_b32 m0, s4
	s_nop 0
	global_load_lds_dwordx4 v[244:245], off
	s_barrier
	s_waitcnt lgkmcnt(0)
	v_mfma_f32_16x16x32_bf16 v[60:63], v[180:183], v[196:199], v[60:63]
	v_mfma_f32_16x16x32_bf16 v[56:59], v[188:191], v[196:199], v[56:59]
	v_mfma_f32_16x16x32_bf16 v[52:55], v[180:183], v[204:207], v[52:55]
	v_mfma_f32_16x16x32_bf16 v[48:51], v[188:191], v[204:207], v[48:51]
	v_mfma_f32_16x16x32_bf16 v[44:47], v[180:183], v[212:215], v[44:47]
	v_mfma_f32_16x16x32_bf16 v[40:43], v[188:191], v[212:215], v[40:43]
	v_mfma_f32_16x16x32_bf16 v[36:39], v[180:183], v[220:223], v[36:39]
	v_mfma_f32_16x16x32_bf16 v[32:35], v[188:191], v[220:223], v[32:35]
	v_mfma_f32_16x16x32_bf16 v[60:63], v[184:187], v[200:203], v[60:63]
	v_mfma_f32_16x16x32_bf16 v[56:59], v[192:195], v[200:203], v[56:59]
	v_mfma_f32_16x16x32_bf16 v[52:55], v[184:187], v[208:211], v[52:55]
	v_mfma_f32_16x16x32_bf16 v[48:51], v[192:195], v[208:211], v[48:51]
	v_mfma_f32_16x16x32_bf16 v[44:47], v[184:187], v[216:219], v[44:47]
	v_mfma_f32_16x16x32_bf16 v[40:43], v[192:195], v[216:219], v[40:43]
	v_mfma_f32_16x16x32_bf16 v[36:39], v[184:187], v[224:227], v[36:39]
	v_mfma_f32_16x16x32_bf16 v[32:35], v[192:195], v[224:227], v[32:35]
	s_barrier
	v_readfirstlane_b32 s4, v171
	v_add_u32_e32 v182, 0x2000, v171
	v_lshl_add_u64 v[180:181], v[248:249], 0, s[28:29]
	s_mov_b32 m0, s4
	v_readfirstlane_b32 s4, v182
	global_load_lds_dwordx4 v[180:181], off
	v_lshl_add_u64 v[180:181], v[250:251], 0, s[28:29]
	s_mov_b32 m0, s4
	s_nop 0
	global_load_lds_dwordx4 v[180:181], off
	s_waitcnt vmcnt(6)
	s_barrier
	v_mfma_f32_16x16x32_bf16 v[28:31], v[228:231], v[196:199], v[28:31]
	v_mfma_f32_16x16x32_bf16 v[24:27], v[236:239], v[196:199], v[24:27]
	v_mfma_f32_16x16x32_bf16 v[20:23], v[228:231], v[204:207], v[20:23]
	v_mfma_f32_16x16x32_bf16 v[16:19], v[236:239], v[204:207], v[16:19]
	v_mfma_f32_16x16x32_bf16 v[12:15], v[228:231], v[212:215], v[12:15]
	v_mfma_f32_16x16x32_bf16 v[8:11], v[236:239], v[212:215], v[8:11]
	v_mfma_f32_16x16x32_bf16 v[4:7], v[228:231], v[220:223], v[4:7]
	v_mfma_f32_16x16x32_bf16 v[0:3], v[236:239], v[220:223], v[0:3]
	v_mfma_f32_16x16x32_bf16 v[28:31], v[232:235], v[200:203], v[28:31]
	v_mfma_f32_16x16x32_bf16 v[24:27], v[240:243], v[200:203], v[24:27]
	v_mfma_f32_16x16x32_bf16 v[20:23], v[232:235], v[208:211], v[20:23]
	v_mfma_f32_16x16x32_bf16 v[16:19], v[240:243], v[208:211], v[16:19]
	v_mfma_f32_16x16x32_bf16 v[12:15], v[232:235], v[216:219], v[12:15]
	v_mfma_f32_16x16x32_bf16 v[8:11], v[240:243], v[216:219], v[8:11]
	v_mfma_f32_16x16x32_bf16 v[4:7], v[232:235], v[224:227], v[4:7]
	v_mfma_f32_16x16x32_bf16 v[0:3], v[240:243], v[224:227], v[0:3]
	s_add_i32 s2, s2, 2
	v_lshl_add_u64 v[142:143], v[142:143], 0, s[30:31]
	v_lshl_add_u64 v[144:145], v[144:145], 0, s[30:31]
	v_lshl_add_u64 v[146:147], v[146:147], 0, s[30:31]
	s_cmp_lt_u32 s2, 12
	v_lshl_add_u64 v[148:149], v[148:149], 0, s[30:31]
	s_barrier
	s_cbranch_scc1 .LBB0_2916
	s_or_b32 s4, s36, 0x80
	s_ashr_i32 s5, s4, 31
	s_lshl_b64 s[4:5], s[4:5], 11
	s_add_u32 s4, s1, s4
	s_addc_u32 s5, s23, s5
	v_lshl_add_u64 v[170:171], s[4:5], 0, v[130:131]
	v_lshl_add_u64 v[138:139], v[138:139], 1, v[170:171]
	v_readfirstlane_b32 s2, v178
	v_lshl_add_u64 v[138:139], v[138:139], 0, s[34:35]
	s_mov_b32 m0, s2
	ds_read_b128 v[142:145], v172
	ds_read_b128 v[146:149], v172 offset:1024
	ds_read_b128 v[180:183], v172 offset:2048
	ds_read_b128 v[184:187], v172 offset:3072
	ds_read_b128 v[188:191], v161
	ds_read_b128 v[192:195], v161 offset:1024
	ds_read_b128 v[196:199], v160
	ds_read_b128 v[200:203], v160 offset:1024
	ds_read_b128 v[204:207], v159
	ds_read_b128 v[208:211], v159 offset:1024
	ds_read_b128 v[212:215], v158
	ds_read_b128 v[216:219], v158 offset:1024
	global_load_lds_dwordx4 v[138:139], off
	v_lshl_add_u64 v[138:139], s[4:5], 0, v[134:135]
	v_lshl_add_u64 v[138:139], v[140:141], 1, v[138:139]
	v_readfirstlane_b32 s2, v179
	v_lshl_add_u64 v[138:139], v[138:139], 0, s[34:35]
	s_mov_b32 m0, s2
	v_readlane_b32 s2, v255, 11
	global_load_lds_dwordx4 v[138:139], off
	s_add_i32 s60, s60, s2
	s_barrier
	s_waitcnt lgkmcnt(0)
	s_cmpk_gt_i32 s60, 0x7f
	s_cselect_b64 s[38:39], -1, 0
	s_waitcnt lgkmcnt(0)
	v_mfma_f32_16x16x32_bf16 v[124:127], v[142:145], v[188:191], v[124:127]
	v_mfma_f32_16x16x32_bf16 v[120:123], v[180:183], v[188:191], v[120:123]
	v_mfma_f32_16x16x32_bf16 v[116:119], v[142:145], v[196:199], v[116:119]
	v_mfma_f32_16x16x32_bf16 v[112:115], v[180:183], v[196:199], v[112:115]
	v_mfma_f32_16x16x32_bf16 v[108:111], v[142:145], v[204:207], v[108:111]
	v_mfma_f32_16x16x32_bf16 v[104:107], v[180:183], v[204:207], v[104:107]
	v_mfma_f32_16x16x32_bf16 v[100:103], v[142:145], v[212:215], v[100:103]
	v_mfma_f32_16x16x32_bf16 v[96:99], v[180:183], v[212:215], v[96:99]
	v_mfma_f32_16x16x32_bf16 v[124:127], v[146:149], v[192:195], v[124:127]
	v_mfma_f32_16x16x32_bf16 v[120:123], v[184:187], v[192:195], v[120:123]
	v_mfma_f32_16x16x32_bf16 v[116:119], v[146:149], v[200:203], v[116:119]
	v_mfma_f32_16x16x32_bf16 v[112:115], v[184:187], v[200:203], v[112:115]
	v_mfma_f32_16x16x32_bf16 v[108:111], v[146:149], v[208:211], v[108:111]
	v_mfma_f32_16x16x32_bf16 v[104:107], v[184:187], v[208:211], v[104:107]
	v_mfma_f32_16x16x32_bf16 v[100:103], v[146:149], v[216:219], v[100:103]
	v_mfma_f32_16x16x32_bf16 v[96:99], v[184:187], v[216:219], v[96:99]
	s_barrier
	ds_read_b128 v[138:141], v168
	ds_read_b128 v[220:223], v168 offset:1024
	ds_read_b128 v[224:227], v168 offset:2048
	ds_read_b128 v[168:171], v168 offset:3072
	s_barrier
	s_waitcnt lgkmcnt(0)
	v_mfma_f32_16x16x32_bf16 v[92:95], v[138:141], v[188:191], v[92:95]
	v_mfma_f32_16x16x32_bf16 v[88:91], v[224:227], v[188:191], v[88:91]
	v_mfma_f32_16x16x32_bf16 v[84:87], v[138:141], v[196:199], v[84:87]
	v_mfma_f32_16x16x32_bf16 v[80:83], v[224:227], v[196:199], v[80:83]
	v_mfma_f32_16x16x32_bf16 v[76:79], v[138:141], v[204:207], v[76:79]
	v_mfma_f32_16x16x32_bf16 v[72:75], v[224:227], v[204:207], v[72:75]
	v_mfma_f32_16x16x32_bf16 v[68:71], v[138:141], v[212:215], v[68:71]
	v_mfma_f32_16x16x32_bf16 v[64:67], v[224:227], v[212:215], v[64:67]
	v_mfma_f32_16x16x32_bf16 v[92:95], v[220:223], v[192:195], v[92:95]
	v_mfma_f32_16x16x32_bf16 v[88:91], v[168:171], v[192:195], v[88:91]
	v_mfma_f32_16x16x32_bf16 v[84:87], v[220:223], v[200:203], v[84:87]
	v_mfma_f32_16x16x32_bf16 v[80:83], v[168:171], v[200:203], v[80:83]
	v_mfma_f32_16x16x32_bf16 v[76:79], v[220:223], v[208:211], v[76:79]
	v_mfma_f32_16x16x32_bf16 v[72:75], v[168:171], v[208:211], v[72:75]
	v_mfma_f32_16x16x32_bf16 v[68:71], v[220:223], v[216:219], v[68:71]
	v_mfma_f32_16x16x32_bf16 v[64:67], v[168:171], v[216:219], v[64:67]
	s_barrier
	ds_read_b128 v[188:191], v161 offset:16384
	ds_read_b128 v[192:195], v161 offset:17408
	ds_read_b128 v[196:199], v160 offset:16384
	ds_read_b128 v[200:203], v160 offset:17408
	ds_read_b128 v[204:207], v159 offset:16384
	ds_read_b128 v[208:211], v159 offset:17408
	ds_read_b128 v[212:215], v158 offset:16384
	ds_read_b128 v[216:219], v158 offset:17408
	s_waitcnt vmcnt(4)
	s_barrier
	s_waitcnt lgkmcnt(0)
	v_mfma_f32_16x16x32_bf16 v[60:63], v[142:145], v[188:191], v[60:63]
	v_mfma_f32_16x16x32_bf16 v[56:59], v[180:183], v[188:191], v[56:59]
	v_mfma_f32_16x16x32_bf16 v[52:55], v[142:145], v[196:199], v[52:55]
	v_mfma_f32_16x16x32_bf16 v[48:51], v[180:183], v[196:199], v[48:51]
	v_mfma_f32_16x16x32_bf16 v[44:47], v[142:145], v[204:207], v[44:47]
	v_mfma_f32_16x16x32_bf16 v[40:43], v[180:183], v[204:207], v[40:43]
	v_mfma_f32_16x16x32_bf16 v[36:39], v[142:145], v[212:215], v[36:39]
	v_mfma_f32_16x16x32_bf16 v[32:35], v[180:183], v[212:215], v[32:35]
	v_mfma_f32_16x16x32_bf16 v[60:63], v[146:149], v[192:195], v[60:63]
	v_mfma_f32_16x16x32_bf16 v[56:59], v[184:187], v[192:195], v[56:59]
	v_mfma_f32_16x16x32_bf16 v[52:55], v[146:149], v[200:203], v[52:55]
	v_mfma_f32_16x16x32_bf16 v[48:51], v[184:187], v[200:203], v[48:51]
	v_mfma_f32_16x16x32_bf16 v[44:47], v[146:149], v[208:211], v[44:47]
	v_mfma_f32_16x16x32_bf16 v[40:43], v[184:187], v[208:211], v[40:43]
	v_mfma_f32_16x16x32_bf16 v[36:39], v[146:149], v[216:219], v[36:39]
	v_mfma_f32_16x16x32_bf16 v[32:35], v[184:187], v[216:219], v[32:35]
	v_mfma_f32_16x16x32_bf16 v[28:31], v[138:141], v[188:191], v[28:31]
	v_mfma_f32_16x16x32_bf16 v[24:27], v[224:227], v[188:191], v[24:27]
	v_mfma_f32_16x16x32_bf16 v[20:23], v[138:141], v[196:199], v[20:23]
	v_mfma_f32_16x16x32_bf16 v[16:19], v[224:227], v[196:199], v[16:19]
	v_mfma_f32_16x16x32_bf16 v[12:15], v[138:141], v[204:207], v[12:15]
	v_mfma_f32_16x16x32_bf16 v[8:11], v[224:227], v[204:207], v[8:11]
	v_mfma_f32_16x16x32_bf16 v[4:7], v[138:141], v[212:215], v[4:7]
	v_mfma_f32_16x16x32_bf16 v[0:3], v[224:227], v[212:215], v[0:3]
	v_mfma_f32_16x16x32_bf16 v[28:31], v[220:223], v[192:195], v[28:31]
	v_mfma_f32_16x16x32_bf16 v[24:27], v[168:171], v[192:195], v[24:27]
	v_mfma_f32_16x16x32_bf16 v[20:23], v[220:223], v[200:203], v[20:23]
	v_mfma_f32_16x16x32_bf16 v[16:19], v[168:171], v[200:203], v[16:19]
	v_mfma_f32_16x16x32_bf16 v[12:15], v[220:223], v[208:211], v[12:15]
	v_mfma_f32_16x16x32_bf16 v[8:11], v[168:171], v[208:211], v[8:11]
	v_mfma_f32_16x16x32_bf16 v[4:7], v[220:223], v[216:219], v[4:7]
	v_mfma_f32_16x16x32_bf16 v[0:3], v[168:171], v[216:219], v[0:3]
	s_barrier
	ds_read_b128 v[138:141], v163
	ds_read_b128 v[142:145], v163 offset:1024
	ds_read_b128 v[146:149], v163 offset:2048
	ds_read_b128 v[168:171], v163 offset:3072
	ds_read_b128 v[178:181], v161 offset:32768
	ds_read_b128 v[182:185], v161 offset:33792
	ds_read_b128 v[186:189], v160 offset:32768
	ds_read_b128 v[190:193], v160 offset:33792
	ds_read_b128 v[194:197], v159 offset:32768
	ds_read_b128 v[198:201], v159 offset:33792
	ds_read_b128 v[202:205], v158 offset:32768
	ds_read_b128 v[206:209], v158 offset:33792
	s_waitcnt vmcnt(2)
	s_barrier
	s_waitcnt lgkmcnt(0)
	v_mfma_f32_16x16x32_bf16 v[124:127], v[138:141], v[178:181], v[124:127]
	v_mfma_f32_16x16x32_bf16 v[120:123], v[146:149], v[178:181], v[120:123]
	v_mfma_f32_16x16x32_bf16 v[116:119], v[138:141], v[186:189], v[116:119]
	v_mfma_f32_16x16x32_bf16 v[112:115], v[146:149], v[186:189], v[112:115]
	v_mfma_f32_16x16x32_bf16 v[108:111], v[138:141], v[194:197], v[108:111]
	v_mfma_f32_16x16x32_bf16 v[104:107], v[146:149], v[194:197], v[104:107]
	v_mfma_f32_16x16x32_bf16 v[100:103], v[138:141], v[202:205], v[100:103]
	v_mfma_f32_16x16x32_bf16 v[96:99], v[146:149], v[202:205], v[96:99]
	v_mfma_f32_16x16x32_bf16 v[124:127], v[142:145], v[182:185], v[124:127]
	v_mfma_f32_16x16x32_bf16 v[120:123], v[168:171], v[182:185], v[120:123]
	v_mfma_f32_16x16x32_bf16 v[116:119], v[142:145], v[190:193], v[116:119]
	v_mfma_f32_16x16x32_bf16 v[112:115], v[168:171], v[190:193], v[112:115]
	v_mfma_f32_16x16x32_bf16 v[108:111], v[142:145], v[198:201], v[108:111]
	v_mfma_f32_16x16x32_bf16 v[104:107], v[168:171], v[198:201], v[104:107]
	v_mfma_f32_16x16x32_bf16 v[100:103], v[142:145], v[206:209], v[100:103]
	v_mfma_f32_16x16x32_bf16 v[96:99], v[168:171], v[206:209], v[96:99]
	s_barrier
	ds_read_b128 v[210:213], v162
	ds_read_b128 v[214:217], v162 offset:1024
	ds_read_b128 v[218:221], v162 offset:2048
	ds_read_b128 v[222:225], v162 offset:3072
	s_waitcnt vmcnt(0)
	s_barrier
	s_waitcnt lgkmcnt(0)
	v_mfma_f32_16x16x32_bf16 v[92:95], v[210:213], v[178:181], v[92:95]
	v_mfma_f32_16x16x32_bf16 v[88:91], v[218:221], v[178:181], v[88:91]
	v_mfma_f32_16x16x32_bf16 v[84:87], v[210:213], v[186:189], v[84:87]
	v_mfma_f32_16x16x32_bf16 v[80:83], v[218:221], v[186:189], v[80:83]
	v_mfma_f32_16x16x32_bf16 v[76:79], v[210:213], v[194:197], v[76:79]
	v_mfma_f32_16x16x32_bf16 v[72:75], v[218:221], v[194:197], v[72:75]
	v_mfma_f32_16x16x32_bf16 v[68:71], v[210:213], v[202:205], v[68:71]
	v_mfma_f32_16x16x32_bf16 v[64:67], v[218:221], v[202:205], v[64:67]
	v_mfma_f32_16x16x32_bf16 v[92:95], v[214:217], v[182:185], v[92:95]
	v_mfma_f32_16x16x32_bf16 v[88:91], v[222:225], v[182:185], v[88:91]
	v_mfma_f32_16x16x32_bf16 v[84:87], v[214:217], v[190:193], v[84:87]
	v_mfma_f32_16x16x32_bf16 v[80:83], v[222:225], v[190:193], v[80:83]
	v_mfma_f32_16x16x32_bf16 v[76:79], v[214:217], v[198:201], v[76:79]
	v_mfma_f32_16x16x32_bf16 v[72:75], v[222:225], v[198:201], v[72:75]
	v_mfma_f32_16x16x32_bf16 v[68:71], v[214:217], v[206:209], v[68:71]
	v_mfma_f32_16x16x32_bf16 v[64:67], v[222:225], v[206:209], v[64:67]
	s_barrier
	ds_read_b128 v[178:181], v161 offset:49152
	ds_read_b128 v[182:185], v161 offset:50176
	ds_read_b128 v[186:189], v160 offset:49152
	ds_read_b128 v[160:163], v160 offset:50176
	ds_read_b128 v[190:193], v159 offset:49152
	ds_read_b128 v[194:197], v159 offset:50176
	ds_read_b128 v[198:201], v158 offset:49152
	ds_read_b128 v[202:205], v158 offset:50176
	s_barrier
	s_waitcnt lgkmcnt(0)
	v_mfma_f32_16x16x32_bf16 v[60:63], v[138:141], v[178:181], v[60:63]
	v_mfma_f32_16x16x32_bf16 v[56:59], v[146:149], v[178:181], v[56:59]
	v_mfma_f32_16x16x32_bf16 v[52:55], v[138:141], v[186:189], v[52:55]
	v_mfma_f32_16x16x32_bf16 v[48:51], v[146:149], v[186:189], v[48:51]
	v_mfma_f32_16x16x32_bf16 v[44:47], v[138:141], v[190:193], v[44:47]
	v_mfma_f32_16x16x32_bf16 v[40:43], v[146:149], v[190:193], v[40:43]
	v_mfma_f32_16x16x32_bf16 v[36:39], v[138:141], v[198:201], v[36:39]
	v_mfma_f32_16x16x32_bf16 v[32:35], v[146:149], v[198:201], v[32:35]
	v_mfma_f32_16x16x32_bf16 v[60:63], v[142:145], v[182:185], v[60:63]
	v_mfma_f32_16x16x32_bf16 v[56:59], v[168:171], v[182:185], v[56:59]
	v_mfma_f32_16x16x32_bf16 v[52:55], v[142:145], v[160:163], v[52:55]
	v_mfma_f32_16x16x32_bf16 v[48:51], v[168:171], v[160:163], v[48:51]
	v_mfma_f32_16x16x32_bf16 v[44:47], v[142:145], v[194:197], v[44:47]
	v_mfma_f32_16x16x32_bf16 v[40:43], v[168:171], v[194:197], v[40:43]
	v_mfma_f32_16x16x32_bf16 v[36:39], v[142:145], v[202:205], v[36:39]
	v_mfma_f32_16x16x32_bf16 v[32:35], v[168:171], v[202:205], v[32:35]
	v_mfma_f32_16x16x32_bf16 v[28:31], v[210:213], v[178:181], v[28:31]
	v_mfma_f32_16x16x32_bf16 v[24:27], v[218:221], v[178:181], v[24:27]
	v_mfma_f32_16x16x32_bf16 v[20:23], v[210:213], v[186:189], v[20:23]
	v_mfma_f32_16x16x32_bf16 v[16:19], v[218:221], v[186:189], v[16:19]
	v_mfma_f32_16x16x32_bf16 v[12:15], v[210:213], v[190:193], v[12:15]
	v_mfma_f32_16x16x32_bf16 v[8:11], v[218:221], v[190:193], v[8:11]
	v_mfma_f32_16x16x32_bf16 v[4:7], v[210:213], v[198:201], v[4:7]
	v_mfma_f32_16x16x32_bf16 v[0:3], v[218:221], v[198:201], v[0:3]
	v_mfma_f32_16x16x32_bf16 v[28:31], v[214:217], v[182:185], v[28:31]
	v_mfma_f32_16x16x32_bf16 v[24:27], v[222:225], v[182:185], v[24:27]
	v_mfma_f32_16x16x32_bf16 v[20:23], v[214:217], v[160:163], v[20:23]
	v_mfma_f32_16x16x32_bf16 v[16:19], v[222:225], v[160:163], v[16:19]
	v_mfma_f32_16x16x32_bf16 v[12:15], v[214:217], v[194:197], v[12:15]
	v_mfma_f32_16x16x32_bf16 v[8:11], v[222:225], v[194:197], v[8:11]
	v_mfma_f32_16x16x32_bf16 v[4:7], v[214:217], v[202:205], v[4:7]
	v_mfma_f32_16x16x32_bf16 v[0:3], v[222:225], v[202:205], v[0:3]
	s_and_b64 vcc, exec, s[38:39]
	s_barrier
	s_cbranch_vccnz .LBB0_2919
	s_lshr_b32 s2, s60, 2
	s_and_b32 s4, s60, 3
	s_add_i32 s2, s2, s56
	s_or_b32 s5, s4, s53
	s_lshl_b32 s4, s2, 8
	s_lshl_b32 s2, s5, 19
	s_add_u32 s42, s40, s2
	s_addc_u32 s43, s46, 0
	v_lshl_add_u64 v[138:139], s[42:43], 0, v[130:131]
	v_readfirstlane_b32 s2, v153
	s_ashr_i32 s5, s4, 31
	v_lshl_add_u64 v[138:139], v[138:139], 0, v[132:133]
	s_mov_b32 m0, s2
	s_lshl_b64 s[44:45], s[4:5], 11
	global_load_lds_dwordx4 v[138:139], off
	v_lshl_add_u64 v[138:139], s[42:43], 0, v[134:135]
	v_readfirstlane_b32 s2, v173
	s_add_u32 s44, s1, s44
	v_lshl_add_u64 v[138:139], v[138:139], 0, v[136:137]
	s_mov_b32 m0, s2
	s_addc_u32 s45, s23, s45
	global_load_lds_dwordx4 v[138:139], off
	v_lshl_add_u64 v[138:139], s[44:45], 0, v[130:131]
	v_readfirstlane_b32 s2, v152
	v_lshl_add_u64 v[138:139], v[138:139], 0, v[132:133]
	s_mov_b32 m0, s2
	s_add_u32 s42, s42, 0x40000
	global_load_lds_dwordx4 v[138:139], off
	v_lshl_add_u64 v[138:139], s[44:45], 0, v[134:135]
	v_readfirstlane_b32 s2, v174
	s_addc_u32 s43, s43, 0
	s_bitset1_b32 s4, 7
	v_lshl_add_u64 v[138:139], v[138:139], 0, v[136:137]
	s_mov_b32 m0, s2
	s_ashr_i32 s5, s4, 31
	global_load_lds_dwordx4 v[138:139], off
	v_lshl_add_u64 v[138:139], s[42:43], 0, v[130:131]
	v_readfirstlane_b32 s2, v151
	s_lshl_b64 s[4:5], s[4:5], 11
	v_lshl_add_u64 v[138:139], v[138:139], 0, v[132:133]
	s_mov_b32 m0, s2
	s_add_u32 s4, s1, s4
	global_load_lds_dwordx4 v[138:139], off
	v_lshl_add_u64 v[138:139], s[42:43], 0, v[134:135]
	v_readfirstlane_b32 s2, v175
	s_addc_u32 s5, s23, s5
	v_lshl_add_u64 v[138:139], v[138:139], 0, v[136:137]
	s_mov_b32 m0, s2
	v_lshl_add_u64 v[130:131], s[4:5], 0, v[130:131]
	v_readfirstlane_b32 s2, v176
	global_load_lds_dwordx4 v[138:139], off
	v_lshl_add_u64 v[130:131], v[130:131], 0, v[132:133]
	s_mov_b32 m0, s2
	v_readfirstlane_b32 s2, v177
	global_load_lds_dwordx4 v[130:131], off
	v_lshl_add_u64 v[130:131], s[4:5], 0, v[134:135]
	v_lshl_add_u64 v[130:131], v[130:131], 0, v[136:137]
	s_mov_b32 m0, s2
	s_nop 0
	global_load_lds_dwordx4 v[130:131], off

.LBB0_2971:
	ds_read_b128 v[176:179], v173
	ds_read_b128 v[180:183], v173 offset:1024
	ds_read_b128 v[184:187], v173 offset:2048
	ds_read_b128 v[188:191], v173 offset:3072
	v_add_u32_e32 v174, 0xc000, v157
	v_lshl_add_u64 v[240:241], s[2:3], 0, v[142:143]
	v_readfirstlane_b32 s31, v174
	v_add_u32_e32 v175, 0xe000, v157
	v_lshl_add_u64 v[224:225], v[240:241], 0, s[10:11]
	s_mov_b32 m0, s31
	v_lshl_add_u64 v[242:243], s[2:3], 0, v[144:145]
	v_readfirstlane_b32 s31, v175
	ds_read_b128 v[192:195], v155
	ds_read_b128 v[196:199], v155 offset:1024
	ds_read_b128 v[200:203], v154
	ds_read_b128 v[204:207], v154 offset:1024
	ds_read_b128 v[208:211], v153
	ds_read_b128 v[212:215], v153 offset:1024
	ds_read_b128 v[216:219], v152
	ds_read_b128 v[220:223], v152 offset:1024
	global_load_lds_dwordx4 v[224:225], off
	v_lshl_add_u64 v[224:225], v[242:243], 0, s[10:11]
	s_mov_b32 m0, s31
	s_nop 0
	global_load_lds_dwordx4 v[224:225], off
	s_waitcnt lgkmcnt(8)
	s_barrier
	s_waitcnt lgkmcnt(0)
	v_mfma_f32_16x16x32_bf16 v[124:127], v[176:179], v[192:195], v[124:127]
	v_mfma_f32_16x16x32_bf16 v[120:123], v[184:187], v[192:195], v[120:123]
	v_mfma_f32_16x16x32_bf16 v[116:119], v[176:179], v[200:203], v[116:119]
	v_mfma_f32_16x16x32_bf16 v[112:115], v[184:187], v[200:203], v[112:115]
	v_mfma_f32_16x16x32_bf16 v[108:111], v[176:179], v[208:211], v[108:111]
	v_mfma_f32_16x16x32_bf16 v[104:107], v[184:187], v[208:211], v[104:107]
	v_mfma_f32_16x16x32_bf16 v[100:103], v[176:179], v[216:219], v[100:103]
	v_mfma_f32_16x16x32_bf16 v[96:99], v[184:187], v[216:219], v[96:99]
	v_mfma_f32_16x16x32_bf16 v[124:127], v[180:183], v[196:199], v[124:127]
	v_mfma_f32_16x16x32_bf16 v[120:123], v[188:191], v[196:199], v[120:123]
	v_mfma_f32_16x16x32_bf16 v[116:119], v[180:183], v[204:207], v[116:119]
	v_mfma_f32_16x16x32_bf16 v[112:115], v[188:191], v[204:207], v[112:115]
	v_mfma_f32_16x16x32_bf16 v[108:111], v[180:183], v[212:215], v[108:111]
	v_mfma_f32_16x16x32_bf16 v[104:107], v[188:191], v[212:215], v[104:107]
	v_mfma_f32_16x16x32_bf16 v[100:103], v[180:183], v[220:223], v[100:103]
	v_mfma_f32_16x16x32_bf16 v[96:99], v[188:191], v[220:223], v[96:99]
	s_barrier
	v_lshl_add_u64 v[244:245], s[2:3], 0, v[138:139]
	v_readfirstlane_b32 s31, v151
	v_lshl_add_u64 v[246:247], v[244:245], 0, s[12:13]
	s_mov_b32 m0, s31
	v_add_u32_e32 v250, 0x2000, v151
	ds_read_b128 v[224:227], v170
	ds_read_b128 v[228:231], v170 offset:1024
	ds_read_b128 v[232:235], v170 offset:2048
	ds_read_b128 v[236:239], v170 offset:3072
	global_load_lds_dwordx4 v[246:247], off
	v_lshl_add_u64 v[246:247], s[2:3], 0, v[140:141]
	v_readfirstlane_b32 s31, v250
	v_lshl_add_u64 v[248:249], v[246:247], 0, s[12:13]
	s_mov_b32 m0, s31
	s_nop 0
	global_load_lds_dwordx4 v[248:249], off
	s_barrier
	s_waitcnt lgkmcnt(0)
	v_mfma_f32_16x16x32_bf16 v[92:95], v[224:227], v[192:195], v[92:95]
	v_mfma_f32_16x16x32_bf16 v[88:91], v[232:235], v[192:195], v[88:91]
	v_mfma_f32_16x16x32_bf16 v[84:87], v[224:227], v[200:203], v[84:87]
	v_mfma_f32_16x16x32_bf16 v[80:83], v[232:235], v[200:203], v[80:83]
	v_mfma_f32_16x16x32_bf16 v[76:79], v[224:227], v[208:211], v[76:79]
	v_mfma_f32_16x16x32_bf16 v[72:75], v[232:235], v[208:211], v[72:75]
	v_mfma_f32_16x16x32_bf16 v[68:71], v[224:227], v[216:219], v[68:71]
	v_mfma_f32_16x16x32_bf16 v[64:67], v[232:235], v[216:219], v[64:67]
	v_mfma_f32_16x16x32_bf16 v[92:95], v[228:231], v[196:199], v[92:95]
	v_mfma_f32_16x16x32_bf16 v[88:91], v[236:239], v[196:199], v[88:91]
	v_mfma_f32_16x16x32_bf16 v[84:87], v[228:231], v[204:207], v[84:87]
	v_mfma_f32_16x16x32_bf16 v[80:83], v[236:239], v[204:207], v[80:83]
	v_mfma_f32_16x16x32_bf16 v[76:79], v[228:231], v[212:215], v[76:79]
	v_mfma_f32_16x16x32_bf16 v[72:75], v[236:239], v[212:215], v[72:75]
	v_mfma_f32_16x16x32_bf16 v[68:71], v[228:231], v[220:223], v[68:71]
	v_mfma_f32_16x16x32_bf16 v[64:67], v[236:239], v[220:223], v[64:67]
	v_readfirstlane_b32 s31, v157
	v_lshl_add_u64 v[248:249], v[240:241], 0, s[14:15]
	s_mov_b32 m0, s31
	v_readfirstlane_b32 s31, v158
	s_barrier
	ds_read_b128 v[192:195], v155 offset:16384
	ds_read_b128 v[196:199], v155 offset:17408
	ds_read_b128 v[200:203], v154 offset:16384
	ds_read_b128 v[204:207], v154 offset:17408
	ds_read_b128 v[208:211], v153 offset:16384
	ds_read_b128 v[212:215], v153 offset:17408
	ds_read_b128 v[216:219], v152 offset:16384
	ds_read_b128 v[220:223], v152 offset:17408
	global_load_lds_dwordx4 v[248:249], off
	v_lshl_add_u64 v[248:249], v[242:243], 0, s[14:15]
	s_mov_b32 m0, s31
	s_nop 0
	global_load_lds_dwordx4 v[248:249], off
	s_barrier
	s_waitcnt lgkmcnt(0)
	v_mfma_f32_16x16x32_bf16 v[60:63], v[176:179], v[192:195], v[60:63]
	v_mfma_f32_16x16x32_bf16 v[56:59], v[184:187], v[192:195], v[56:59]
	v_mfma_f32_16x16x32_bf16 v[52:55], v[176:179], v[200:203], v[52:55]
	v_mfma_f32_16x16x32_bf16 v[48:51], v[184:187], v[200:203], v[48:51]
	v_mfma_f32_16x16x32_bf16 v[44:47], v[176:179], v[208:211], v[44:47]
	v_mfma_f32_16x16x32_bf16 v[40:43], v[184:187], v[208:211], v[40:43]
	v_mfma_f32_16x16x32_bf16 v[36:39], v[176:179], v[216:219], v[36:39]
	v_mfma_f32_16x16x32_bf16 v[32:35], v[184:187], v[216:219], v[32:35]
	v_mfma_f32_16x16x32_bf16 v[60:63], v[180:183], v[196:199], v[60:63]
	v_mfma_f32_16x16x32_bf16 v[56:59], v[188:191], v[196:199], v[56:59]
	v_mfma_f32_16x16x32_bf16 v[52:55], v[180:183], v[204:207], v[52:55]
	v_mfma_f32_16x16x32_bf16 v[48:51], v[188:191], v[204:207], v[48:51]
	v_mfma_f32_16x16x32_bf16 v[44:47], v[180:183], v[212:215], v[44:47]
	v_mfma_f32_16x16x32_bf16 v[40:43], v[188:191], v[212:215], v[40:43]
	v_mfma_f32_16x16x32_bf16 v[36:39], v[180:183], v[220:223], v[36:39]
	v_mfma_f32_16x16x32_bf16 v[32:35], v[188:191], v[220:223], v[32:35]
	s_barrier
	v_readfirstlane_b32 s31, v159
	v_add_u32_e32 v178, 0x2000, v159
	v_lshl_add_u64 v[176:177], v[244:245], 0, s[16:17]
	s_mov_b32 m0, s31
	v_readfirstlane_b32 s31, v178
	global_load_lds_dwordx4 v[176:177], off
	v_lshl_add_u64 v[176:177], v[246:247], 0, s[16:17]
	s_mov_b32 m0, s31
	s_nop 0
	global_load_lds_dwordx4 v[176:177], off
	s_waitcnt vmcnt(6)
	s_barrier
	v_mfma_f32_16x16x32_bf16 v[28:31], v[224:227], v[192:195], v[28:31]
	v_mfma_f32_16x16x32_bf16 v[24:27], v[232:235], v[192:195], v[24:27]
	v_mfma_f32_16x16x32_bf16 v[20:23], v[224:227], v[200:203], v[20:23]
	v_mfma_f32_16x16x32_bf16 v[16:19], v[232:235], v[200:203], v[16:19]
	v_mfma_f32_16x16x32_bf16 v[12:15], v[224:227], v[208:211], v[12:15]
	v_mfma_f32_16x16x32_bf16 v[8:11], v[232:235], v[208:211], v[8:11]
	v_mfma_f32_16x16x32_bf16 v[4:7], v[224:227], v[216:219], v[4:7]
	v_mfma_f32_16x16x32_bf16 v[0:3], v[232:235], v[216:219], v[0:3]
	v_mfma_f32_16x16x32_bf16 v[28:31], v[228:231], v[196:199], v[28:31]
	v_mfma_f32_16x16x32_bf16 v[24:27], v[236:239], v[196:199], v[24:27]
	v_mfma_f32_16x16x32_bf16 v[20:23], v[228:231], v[204:207], v[20:23]
	v_mfma_f32_16x16x32_bf16 v[16:19], v[236:239], v[204:207], v[16:19]
	v_mfma_f32_16x16x32_bf16 v[12:15], v[228:231], v[212:215], v[12:15]
	v_mfma_f32_16x16x32_bf16 v[8:11], v[236:239], v[212:215], v[8:11]
	v_mfma_f32_16x16x32_bf16 v[4:7], v[228:231], v[220:223], v[4:7]
	v_mfma_f32_16x16x32_bf16 v[0:3], v[236:239], v[220:223], v[0:3]
	s_barrier
	ds_read_b128 v[176:179], v160
	ds_read_b128 v[180:183], v160 offset:1024
	ds_read_b128 v[184:187], v160 offset:2048
	ds_read_b128 v[188:191], v160 offset:3072
	v_readfirstlane_b32 s31, v161
	v_lshl_add_u64 v[224:225], v[240:241], 0, s[18:19]
	s_mov_b32 m0, s31
	v_readfirstlane_b32 s31, v162
	ds_read_b128 v[192:195], v155 offset:32768
	ds_read_b128 v[196:199], v155 offset:33792
	ds_read_b128 v[200:203], v154 offset:32768
	ds_read_b128 v[204:207], v154 offset:33792
	ds_read_b128 v[208:211], v153 offset:32768
	ds_read_b128 v[212:215], v153 offset:33792
	ds_read_b128 v[216:219], v152 offset:32768
	ds_read_b128 v[220:223], v152 offset:33792
	global_load_lds_dwordx4 v[224:225], off
	v_lshl_add_u64 v[224:225], v[242:243], 0, s[18:19]
	s_mov_b32 m0, s31
	s_nop 0
	global_load_lds_dwordx4 v[224:225], off
	s_waitcnt lgkmcnt(8)
	s_barrier
	s_waitcnt lgkmcnt(0)
	v_mfma_f32_16x16x32_bf16 v[124:127], v[176:179], v[192:195], v[124:127]
	v_mfma_f32_16x16x32_bf16 v[120:123], v[184:187], v[192:195], v[120:123]
	v_mfma_f32_16x16x32_bf16 v[116:119], v[176:179], v[200:203], v[116:119]
	v_mfma_f32_16x16x32_bf16 v[112:115], v[184:187], v[200:203], v[112:115]
	v_mfma_f32_16x16x32_bf16 v[108:111], v[176:179], v[208:211], v[108:111]
	v_mfma_f32_16x16x32_bf16 v[104:107], v[184:187], v[208:211], v[104:107]
	v_mfma_f32_16x16x32_bf16 v[100:103], v[176:179], v[216:219], v[100:103]
	v_mfma_f32_16x16x32_bf16 v[96:99], v[184:187], v[216:219], v[96:99]
	v_mfma_f32_16x16x32_bf16 v[124:127], v[180:183], v[196:199], v[124:127]
	v_mfma_f32_16x16x32_bf16 v[120:123], v[188:191], v[196:199], v[120:123]
	v_mfma_f32_16x16x32_bf16 v[116:119], v[180:183], v[204:207], v[116:119]
	v_mfma_f32_16x16x32_bf16 v[112:115], v[188:191], v[204:207], v[112:115]
	v_mfma_f32_16x16x32_bf16 v[108:111], v[180:183], v[212:215], v[108:111]
	v_mfma_f32_16x16x32_bf16 v[104:107], v[188:191], v[212:215], v[104:107]
	v_mfma_f32_16x16x32_bf16 v[100:103], v[180:183], v[220:223], v[100:103]
	v_mfma_f32_16x16x32_bf16 v[96:99], v[188:191], v[220:223], v[96:99]
	s_barrier
	v_readfirstlane_b32 s31, v163
	v_lshl_add_u64 v[248:249], v[244:245], 0, s[20:21]
	s_mov_b32 m0, s31
	v_readfirstlane_b32 s31, v167
	ds_read_b128 v[224:227], v156
	ds_read_b128 v[228:231], v156 offset:1024
	ds_read_b128 v[232:235], v156 offset:2048
	ds_read_b128 v[236:239], v156 offset:3072
	global_load_lds_dwordx4 v[248:249], off
	v_lshl_add_u64 v[248:249], v[246:247], 0, s[20:21]
	s_mov_b32 m0, s31
	s_nop 0
	global_load_lds_dwordx4 v[248:249], off
	s_barrier
	s_waitcnt lgkmcnt(0)
	v_mfma_f32_16x16x32_bf16 v[92:95], v[224:227], v[192:195], v[92:95]
	v_mfma_f32_16x16x32_bf16 v[88:91], v[232:235], v[192:195], v[88:91]
	v_mfma_f32_16x16x32_bf16 v[84:87], v[224:227], v[200:203], v[84:87]
	v_mfma_f32_16x16x32_bf16 v[80:83], v[232:235], v[200:203], v[80:83]
	v_mfma_f32_16x16x32_bf16 v[76:79], v[224:227], v[208:211], v[76:79]
	v_mfma_f32_16x16x32_bf16 v[72:75], v[232:235], v[208:211], v[72:75]
	v_mfma_f32_16x16x32_bf16 v[68:71], v[224:227], v[216:219], v[68:71]
	v_mfma_f32_16x16x32_bf16 v[64:67], v[232:235], v[216:219], v[64:67]
	v_mfma_f32_16x16x32_bf16 v[92:95], v[228:231], v[196:199], v[92:95]
	v_mfma_f32_16x16x32_bf16 v[88:91], v[236:239], v[196:199], v[88:91]
	v_mfma_f32_16x16x32_bf16 v[84:87], v[228:231], v[204:207], v[84:87]
	v_mfma_f32_16x16x32_bf16 v[80:83], v[236:239], v[204:207], v[80:83]
	v_mfma_f32_16x16x32_bf16 v[76:79], v[228:231], v[212:215], v[76:79]
	v_mfma_f32_16x16x32_bf16 v[72:75], v[236:239], v[212:215], v[72:75]
	v_mfma_f32_16x16x32_bf16 v[68:71], v[228:231], v[220:223], v[68:71]
	v_mfma_f32_16x16x32_bf16 v[64:67], v[236:239], v[220:223], v[64:67]
	v_readfirstlane_b32 s31, v168
	v_lshl_add_u64 v[240:241], v[240:241], 0, s[24:25]
	s_mov_b32 m0, s31
	v_readfirstlane_b32 s31, v169
	s_barrier
	ds_read_b128 v[192:195], v155 offset:49152
	ds_read_b128 v[196:199], v155 offset:50176
	ds_read_b128 v[200:203], v154 offset:49152
	ds_read_b128 v[204:207], v154 offset:50176
	ds_read_b128 v[208:211], v153 offset:49152
	ds_read_b128 v[212:215], v153 offset:50176
	ds_read_b128 v[216:219], v152 offset:49152
	ds_read_b128 v[220:223], v152 offset:50176
	global_load_lds_dwordx4 v[240:241], off
	v_lshl_add_u64 v[240:241], v[242:243], 0, s[24:25]
	s_mov_b32 m0, s31
	s_nop 0
	global_load_lds_dwordx4 v[240:241], off
	s_barrier
	s_waitcnt lgkmcnt(0)
	v_mfma_f32_16x16x32_bf16 v[60:63], v[176:179], v[192:195], v[60:63]
	v_mfma_f32_16x16x32_bf16 v[56:59], v[184:187], v[192:195], v[56:59]
	v_mfma_f32_16x16x32_bf16 v[52:55], v[176:179], v[200:203], v[52:55]
	v_mfma_f32_16x16x32_bf16 v[48:51], v[184:187], v[200:203], v[48:51]
	v_mfma_f32_16x16x32_bf16 v[44:47], v[176:179], v[208:211], v[44:47]
	v_mfma_f32_16x16x32_bf16 v[40:43], v[184:187], v[208:211], v[40:43]
	v_mfma_f32_16x16x32_bf16 v[36:39], v[176:179], v[216:219], v[36:39]
	v_mfma_f32_16x16x32_bf16 v[32:35], v[184:187], v[216:219], v[32:35]
	v_mfma_f32_16x16x32_bf16 v[60:63], v[180:183], v[196:199], v[60:63]
	v_mfma_f32_16x16x32_bf16 v[56:59], v[188:191], v[196:199], v[56:59]
	v_mfma_f32_16x16x32_bf16 v[52:55], v[180:183], v[204:207], v[52:55]
	v_mfma_f32_16x16x32_bf16 v[48:51], v[188:191], v[204:207], v[48:51]
	v_mfma_f32_16x16x32_bf16 v[44:47], v[180:183], v[212:215], v[44:47]
	v_mfma_f32_16x16x32_bf16 v[40:43], v[188:191], v[212:215], v[40:43]
	v_mfma_f32_16x16x32_bf16 v[36:39], v[180:183], v[220:223], v[36:39]
	v_mfma_f32_16x16x32_bf16 v[32:35], v[188:191], v[220:223], v[32:35]
	s_barrier
	v_readfirstlane_b32 s31, v171
	v_lshl_add_u64 v[176:177], v[244:245], 0, s[26:27]
	s_mov_b32 m0, s31
	v_readfirstlane_b32 s31, v172
	global_load_lds_dwordx4 v[176:177], off
	v_lshl_add_u64 v[176:177], v[246:247], 0, s[26:27]
	s_mov_b32 m0, s31
	s_nop 0
	global_load_lds_dwordx4 v[176:177], off
	s_waitcnt vmcnt(6)
	s_barrier
	v_mfma_f32_16x16x32_bf16 v[28:31], v[224:227], v[192:195], v[28:31]
	v_mfma_f32_16x16x32_bf16 v[24:27], v[232:235], v[192:195], v[24:27]
	v_mfma_f32_16x16x32_bf16 v[20:23], v[224:227], v[200:203], v[20:23]
	v_mfma_f32_16x16x32_bf16 v[16:19], v[232:235], v[200:203], v[16:19]
	v_mfma_f32_16x16x32_bf16 v[12:15], v[224:227], v[208:211], v[12:15]
	v_mfma_f32_16x16x32_bf16 v[8:11], v[232:235], v[208:211], v[8:11]
	v_mfma_f32_16x16x32_bf16 v[4:7], v[224:227], v[216:219], v[4:7]
	v_mfma_f32_16x16x32_bf16 v[0:3], v[232:235], v[216:219], v[0:3]
	v_mfma_f32_16x16x32_bf16 v[28:31], v[228:231], v[196:199], v[28:31]
	v_mfma_f32_16x16x32_bf16 v[24:27], v[236:239], v[196:199], v[24:27]
	v_mfma_f32_16x16x32_bf16 v[20:23], v[228:231], v[204:207], v[20:23]
	v_mfma_f32_16x16x32_bf16 v[16:19], v[236:239], v[204:207], v[16:19]
	v_mfma_f32_16x16x32_bf16 v[12:15], v[228:231], v[212:215], v[12:15]
	v_mfma_f32_16x16x32_bf16 v[8:11], v[236:239], v[212:215], v[8:11]
	v_mfma_f32_16x16x32_bf16 v[4:7], v[228:231], v[220:223], v[4:7]
	v_mfma_f32_16x16x32_bf16 v[0:3], v[236:239], v[220:223], v[0:3]
	s_add_i32 s6, s6, 2
	v_lshl_add_u64 v[138:139], v[138:139], 0, s[28:29]
	v_lshl_add_u64 v[140:141], v[140:141], 0, s[28:29]
	v_lshl_add_u64 v[142:143], v[142:143], 0, s[28:29]
	s_cmp_lt_u32 s6, 60
	v_lshl_add_u64 v[144:145], v[144:145], 0, s[28:29]
	s_barrier
	s_cbranch_scc1 .LBB0_2971
	s_add_u32 s34, s34, 0x1f80
	s_addc_u32 s35, s35, 0
	v_lshl_add_u64 v[132:133], s[34:35], 0, v[132:133]
	v_readfirstlane_b32 s6, v174
	v_lshl_add_u64 v[130:131], v[130:131], 1, v[132:133]
	s_mov_b32 m0, s6
	ds_read_b128 v[138:141], v173
	ds_read_b128 v[142:145], v173 offset:1024
	ds_read_b128 v[176:179], v173 offset:2048
	ds_read_b128 v[180:183], v173 offset:3072
	ds_read_b128 v[184:187], v155
	ds_read_b128 v[188:191], v155 offset:1024
	ds_read_b128 v[192:195], v154
	ds_read_b128 v[196:199], v154 offset:1024
	ds_read_b128 v[200:203], v153
	ds_read_b128 v[204:207], v153 offset:1024
	ds_read_b128 v[208:211], v152
	ds_read_b128 v[212:215], v152 offset:1024
	global_load_lds_dwordx4 v[130:131], off
	v_lshl_add_u64 v[130:131], s[34:35], 0, v[136:137]
	v_readfirstlane_b32 s6, v175
	v_lshl_add_u64 v[130:131], v[134:135], 1, v[130:131]
	s_mov_b32 m0, s6
	s_nop 0
	global_load_lds_dwordx4 v[130:131], off
	s_barrier
	s_waitcnt lgkmcnt(0)
	v_mfma_f32_16x16x32_bf16 v[124:127], v[138:141], v[184:187], v[124:127]
	v_mfma_f32_16x16x32_bf16 v[116:119], v[138:141], v[192:195], v[116:119]
	v_mfma_f32_16x16x32_bf16 v[108:111], v[138:141], v[200:203], v[108:111]
	v_mfma_f32_16x16x32_bf16 v[100:103], v[138:141], v[208:211], v[100:103]
	v_mfma_f32_16x16x32_bf16 v[124:127], v[142:145], v[188:191], v[124:127]
	v_mfma_f32_16x16x32_bf16 v[120:123], v[176:179], v[184:187], v[120:123]
	v_mfma_f32_16x16x32_bf16 v[116:119], v[142:145], v[196:199], v[116:119]
	v_mfma_f32_16x16x32_bf16 v[112:115], v[176:179], v[192:195], v[112:115]
	v_mfma_f32_16x16x32_bf16 v[108:111], v[142:145], v[204:207], v[108:111]
	v_mfma_f32_16x16x32_bf16 v[104:107], v[176:179], v[200:203], v[104:107]
	v_mfma_f32_16x16x32_bf16 v[100:103], v[142:145], v[212:215], v[100:103]
	v_mfma_f32_16x16x32_bf16 v[96:99], v[176:179], v[208:211], v[96:99]
	v_mfma_f32_16x16x32_bf16 v[130:133], v[180:183], v[188:191], v[120:123]
	v_mfma_f32_16x16x32_bf16 v[134:137], v[180:183], v[196:199], v[112:115]
	v_mfma_f32_16x16x32_bf16 v[172:175], v[180:183], v[204:207], v[104:107]
	v_mfma_f32_16x16x32_bf16 v[216:219], v[180:183], v[212:215], v[96:99]
	s_barrier
	s_nop 1
	ds_read_b128 v[96:99], v170
	ds_read_b128 v[104:107], v170 offset:1024
	ds_read_b128 v[112:115], v170 offset:2048
	ds_read_b128 v[120:123], v170 offset:3072
	s_barrier
	s_waitcnt lgkmcnt(0)
	v_mfma_f32_16x16x32_bf16 v[92:95], v[96:99], v[184:187], v[92:95]
	v_mfma_f32_16x16x32_bf16 v[84:87], v[96:99], v[192:195], v[84:87]
	v_mfma_f32_16x16x32_bf16 v[76:79], v[96:99], v[200:203], v[76:79]
	v_mfma_f32_16x16x32_bf16 v[68:71], v[96:99], v[208:211], v[68:71]
	v_mfma_f32_16x16x32_bf16 v[92:95], v[104:107], v[188:191], v[92:95]
	v_mfma_f32_16x16x32_bf16 v[88:91], v[112:115], v[184:187], v[88:91]
	v_mfma_f32_16x16x32_bf16 v[84:87], v[104:107], v[196:199], v[84:87]
	v_mfma_f32_16x16x32_bf16 v[80:83], v[112:115], v[192:195], v[80:83]
	v_mfma_f32_16x16x32_bf16 v[76:79], v[104:107], v[204:207], v[76:79]
	v_mfma_f32_16x16x32_bf16 v[72:75], v[112:115], v[200:203], v[72:75]
	v_mfma_f32_16x16x32_bf16 v[68:71], v[104:107], v[212:215], v[68:71]
	v_mfma_f32_16x16x32_bf16 v[64:67], v[112:115], v[208:211], v[64:67]
	v_mfma_f32_16x16x32_bf16 v[168:171], v[120:123], v[188:191], v[88:91]
	v_mfma_f32_16x16x32_bf16 v[184:187], v[120:123], v[196:199], v[80:83]
	v_mfma_f32_16x16x32_bf16 v[188:191], v[120:123], v[204:207], v[72:75]
	v_mfma_f32_16x16x32_bf16 v[192:195], v[120:123], v[212:215], v[64:67]
	s_barrier
	s_nop 1
	ds_read_b128 v[64:67], v155 offset:16384
	ds_read_b128 v[72:75], v155 offset:17408
	ds_read_b128 v[80:83], v154 offset:16384
	ds_read_b128 v[88:91], v154 offset:17408
	ds_read_b128 v[196:199], v153 offset:16384
	ds_read_b128 v[200:203], v153 offset:17408
	ds_read_b128 v[204:207], v152 offset:16384
	ds_read_b128 v[208:211], v152 offset:17408
	s_waitcnt vmcnt(4)
	s_barrier
	s_waitcnt lgkmcnt(0)
	v_mfma_f32_16x16x32_bf16 v[60:63], v[138:141], v[64:67], v[60:63]
	v_mfma_f32_16x16x32_bf16 v[52:55], v[138:141], v[80:83], v[52:55]
	v_mfma_f32_16x16x32_bf16 v[44:47], v[138:141], v[196:199], v[44:47]
	v_mfma_f32_16x16x32_bf16 v[36:39], v[138:141], v[204:207], v[36:39]
	v_mfma_f32_16x16x32_bf16 v[60:63], v[142:145], v[72:75], v[60:63]
	v_mfma_f32_16x16x32_bf16 v[56:59], v[176:179], v[64:67], v[56:59]
	v_mfma_f32_16x16x32_bf16 v[52:55], v[142:145], v[88:91], v[52:55]
	v_mfma_f32_16x16x32_bf16 v[48:51], v[176:179], v[80:83], v[48:51]
	v_mfma_f32_16x16x32_bf16 v[44:47], v[142:145], v[200:203], v[44:47]
	v_mfma_f32_16x16x32_bf16 v[40:43], v[176:179], v[196:199], v[40:43]
	v_mfma_f32_16x16x32_bf16 v[36:39], v[142:145], v[208:211], v[36:39]
	v_mfma_f32_16x16x32_bf16 v[32:35], v[176:179], v[204:207], v[32:35]
	v_mfma_f32_16x16x32_bf16 v[212:215], v[180:183], v[72:75], v[56:59]
	v_mfma_f32_16x16x32_bf16 v[220:223], v[180:183], v[88:91], v[48:51]
	v_mfma_f32_16x16x32_bf16 v[224:227], v[180:183], v[200:203], v[40:43]
	v_mfma_f32_16x16x32_bf16 v[138:141], v[180:183], v[208:211], v[32:35]
	v_mfma_f32_16x16x32_bf16 v[28:31], v[96:99], v[64:67], v[28:31]
	v_mfma_f32_16x16x32_bf16 v[20:23], v[96:99], v[80:83], v[20:23]
	v_mfma_f32_16x16x32_bf16 v[12:15], v[96:99], v[196:199], v[12:15]
	v_mfma_f32_16x16x32_bf16 v[4:7], v[96:99], v[204:207], v[4:7]
	v_mfma_f32_16x16x32_bf16 v[28:31], v[104:107], v[72:75], v[28:31]
	v_mfma_f32_16x16x32_bf16 v[24:27], v[112:115], v[64:67], v[24:27]
	v_mfma_f32_16x16x32_bf16 v[20:23], v[104:107], v[88:91], v[20:23]
	v_mfma_f32_16x16x32_bf16 v[16:19], v[112:115], v[80:83], v[16:19]
	v_mfma_f32_16x16x32_bf16 v[12:15], v[104:107], v[200:203], v[12:15]
	v_mfma_f32_16x16x32_bf16 v[8:11], v[112:115], v[196:199], v[8:11]
	v_mfma_f32_16x16x32_bf16 v[4:7], v[104:107], v[208:211], v[4:7]
	v_mfma_f32_16x16x32_bf16 v[0:3], v[112:115], v[204:207], v[0:3]
	v_mfma_f32_16x16x32_bf16 v[142:145], v[120:123], v[72:75], v[24:27]
	v_mfma_f32_16x16x32_bf16 v[176:179], v[120:123], v[88:91], v[16:19]
	v_mfma_f32_16x16x32_bf16 v[180:183], v[120:123], v[200:203], v[8:11]
	v_mfma_f32_16x16x32_bf16 v[196:199], v[120:123], v[208:211], v[0:3]
	s_barrier
	s_nop 1
	ds_read_b128 v[0:3], v160
	ds_read_b128 v[8:11], v160 offset:1024
	ds_read_b128 v[16:19], v160 offset:2048
	ds_read_b128 v[24:27], v160 offset:3072
	ds_read_b128 v[32:35], v155 offset:32768
	ds_read_b128 v[40:43], v155 offset:33792
	ds_read_b128 v[48:51], v154 offset:32768
	ds_read_b128 v[56:59], v154 offset:33792
	ds_read_b128 v[64:67], v153 offset:32768
	ds_read_b128 v[158:161], v153 offset:33792
	ds_read_b128 v[200:203], v152 offset:32768
	ds_read_b128 v[204:207], v152 offset:33792
	s_waitcnt vmcnt(2)
	s_barrier
	s_waitcnt lgkmcnt(0)
	v_mfma_f32_16x16x32_bf16 v[72:75], v[0:3], v[32:35], v[124:127]
	v_mfma_f32_16x16x32_bf16 v[120:123], v[8:11], v[40:43], v[72:75]
	v_mfma_f32_16x16x32_bf16 v[72:75], v[16:19], v[32:35], v[130:133]
	v_mfma_f32_16x16x32_bf16 v[124:127], v[24:27], v[40:43], v[72:75]
	v_mfma_f32_16x16x32_bf16 v[72:75], v[0:3], v[48:51], v[116:119]
	v_mfma_f32_16x16x32_bf16 v[112:115], v[8:11], v[56:59], v[72:75]
	v_mfma_f32_16x16x32_bf16 v[72:75], v[16:19], v[48:51], v[134:137]
	v_mfma_f32_16x16x32_bf16 v[116:119], v[24:27], v[56:59], v[72:75]
	v_mfma_f32_16x16x32_bf16 v[72:75], v[0:3], v[64:67], v[108:111]
	v_mfma_f32_16x16x32_bf16 v[104:107], v[8:11], v[158:161], v[72:75]
	v_mfma_f32_16x16x32_bf16 v[72:75], v[16:19], v[64:67], v[172:175]
	v_mfma_f32_16x16x32_bf16 v[108:111], v[24:27], v[158:161], v[72:75]
	v_mfma_f32_16x16x32_bf16 v[72:75], v[0:3], v[200:203], v[100:103]
	v_mfma_f32_16x16x32_bf16 v[96:99], v[8:11], v[204:207], v[72:75]
	v_mfma_f32_16x16x32_bf16 v[72:75], v[16:19], v[200:203], v[216:219]
	v_mfma_f32_16x16x32_bf16 v[100:103], v[24:27], v[204:207], v[72:75]
	s_barrier
	ds_read_b128 v[130:133], v156
	ds_read_b128 v[134:137], v156 offset:1024
	ds_read_b128 v[172:175], v156 offset:2048
	ds_read_b128 v[208:211], v156 offset:3072
	s_waitcnt vmcnt(0)
	s_barrier
	s_waitcnt lgkmcnt(0)
	v_mfma_f32_16x16x32_bf16 v[72:75], v[130:133], v[32:35], v[92:95]
	v_mfma_f32_16x16x32_bf16 v[32:35], v[172:175], v[32:35], v[168:171]
	v_mfma_f32_16x16x32_bf16 v[92:95], v[208:211], v[40:43], v[32:35]
	v_mfma_f32_16x16x32_bf16 v[32:35], v[130:133], v[48:51], v[84:87]
	v_mfma_f32_16x16x32_bf16 v[80:83], v[134:137], v[56:59], v[32:35]
	v_mfma_f32_16x16x32_bf16 v[32:35], v[172:175], v[48:51], v[184:187]
	v_mfma_f32_16x16x32_bf16 v[84:87], v[208:211], v[56:59], v[32:35]
	v_mfma_f32_16x16x32_bf16 v[32:35], v[130:133], v[64:67], v[76:79]
	v_mfma_f32_16x16x32_bf16 v[88:91], v[134:137], v[40:43], v[72:75]
	v_mfma_f32_16x16x32_bf16 v[72:75], v[134:137], v[158:161], v[32:35]
	v_mfma_f32_16x16x32_bf16 v[32:35], v[172:175], v[64:67], v[188:191]
	v_mfma_f32_16x16x32_bf16 v[76:79], v[208:211], v[158:161], v[32:35]
	v_mfma_f32_16x16x32_bf16 v[32:35], v[130:133], v[200:203], v[68:71]
	v_mfma_f32_16x16x32_bf16 v[64:67], v[134:137], v[204:207], v[32:35]
	v_mfma_f32_16x16x32_bf16 v[32:35], v[172:175], v[200:203], v[192:195]
	v_mfma_f32_16x16x32_bf16 v[68:71], v[208:211], v[204:207], v[32:35]
	s_barrier
	ds_read_b128 v[156:159], v155 offset:49152
	ds_read_b128 v[160:163], v155 offset:50176
	ds_read_b128 v[168:171], v154 offset:49152
	ds_read_b128 v[184:187], v154 offset:50176
	ds_read_b128 v[188:191], v153 offset:49152
	ds_read_b128 v[192:195], v153 offset:50176
	ds_read_b128 v[200:203], v152 offset:49152
	ds_read_b128 v[152:155], v152 offset:50176
	s_barrier
	s_waitcnt lgkmcnt(0)
	v_mfma_f32_16x16x32_bf16 v[32:35], v[0:3], v[156:159], v[60:63]
	v_mfma_f32_16x16x32_bf16 v[56:59], v[8:11], v[160:163], v[32:35]
	v_mfma_f32_16x16x32_bf16 v[32:35], v[16:19], v[156:159], v[212:215]
	v_mfma_f32_16x16x32_bf16 v[60:63], v[24:27], v[160:163], v[32:35]
	v_mfma_f32_16x16x32_bf16 v[32:35], v[0:3], v[168:171], v[52:55]
	v_mfma_f32_16x16x32_bf16 v[48:51], v[8:11], v[184:187], v[32:35]
	v_mfma_f32_16x16x32_bf16 v[32:35], v[16:19], v[168:171], v[220:223]
	v_mfma_f32_16x16x32_bf16 v[52:55], v[24:27], v[184:187], v[32:35]
	v_mfma_f32_16x16x32_bf16 v[32:35], v[0:3], v[188:191], v[44:47]
	v_mfma_f32_16x16x32_bf16 v[40:43], v[8:11], v[192:195], v[32:35]
	v_mfma_f32_16x16x32_bf16 v[32:35], v[16:19], v[188:191], v[224:227]
	v_mfma_f32_16x16x32_bf16 v[0:3], v[0:3], v[200:203], v[36:39]
	v_mfma_f32_16x16x32_bf16 v[44:47], v[24:27], v[192:195], v[32:35]
	v_mfma_f32_16x16x32_bf16 v[32:35], v[8:11], v[152:155], v[0:3]
	v_mfma_f32_16x16x32_bf16 v[0:3], v[16:19], v[200:203], v[138:141]
	v_mfma_f32_16x16x32_bf16 v[36:39], v[24:27], v[152:155], v[0:3]
	v_mfma_f32_16x16x32_bf16 v[0:3], v[130:133], v[156:159], v[28:31]
	v_mfma_f32_16x16x32_bf16 v[24:27], v[134:137], v[160:163], v[0:3]
	v_mfma_f32_16x16x32_bf16 v[0:3], v[172:175], v[156:159], v[142:145]
	v_mfma_f32_16x16x32_bf16 v[28:31], v[208:211], v[160:163], v[0:3]
	v_mfma_f32_16x16x32_bf16 v[0:3], v[130:133], v[168:171], v[20:23]
	v_mfma_f32_16x16x32_bf16 v[16:19], v[134:137], v[184:187], v[0:3]
	v_mfma_f32_16x16x32_bf16 v[0:3], v[172:175], v[168:171], v[176:179]
	v_mfma_f32_16x16x32_bf16 v[20:23], v[208:211], v[184:187], v[0:3]
	v_mfma_f32_16x16x32_bf16 v[0:3], v[130:133], v[188:191], v[12:15]
	v_mfma_f32_16x16x32_bf16 v[8:11], v[134:137], v[192:195], v[0:3]
	v_mfma_f32_16x16x32_bf16 v[0:3], v[172:175], v[188:191], v[180:183]
	v_mfma_f32_16x16x32_bf16 v[12:15], v[208:211], v[192:195], v[0:3]
	v_mfma_f32_16x16x32_bf16 v[0:3], v[130:133], v[200:203], v[4:7]
	v_mfma_f32_16x16x32_bf16 v[4:7], v[172:175], v[200:203], v[196:199]
	v_mfma_f32_16x16x32_bf16 v[0:3], v[134:137], v[152:155], v[0:3]
	v_mfma_f32_16x16x32_bf16 v[4:7], v[208:211], v[152:155], v[4:7]
	v_cmp_gt_u32_e32 vcc, s56, v128
	s_barrier
	s_and_saveexec_b64 s[34:35], vcc
	s_cbranch_execz .LBB0_2967
	s_barrier
	s_branch .LBB0_2967
